# prologue loops de-serialised (FW1/FWKV conditional loads, x->bf16 double-buffered); EpiUp second-half rowss loads hoisted
# speedup vs baseline: 1.0227x; 1.0100x over previous
; #define LAS __attribute__((address_space(3)))
; template <class F> DI void tr_items(const F& f, int Kdst, int Nrows, bf16_t* WT, LAS float* scr, int gw, int NGW, int lane, int& cum) {
;     const int nblk = Nrows / 32, nitems = (Kdst / 64) * nblk;
;     int first = (gw - cum) % NGW; if (first < 0) first += NGW; cum = (cum + nitems) % NGW;
;     for (int item = first; item < nitems; item += NGW) {
;         const int kb = item / nblk, nb = item % nblk, k0 = 64 * kb, n0 = 32 * nb;
;         float tv[32];
; #pragma unroll
;         for (int i = 0; i < 32; ++i) tv[i] = f(k0 + 2 * i + (lane >> 5), n0 + (lane & 31));
.LBB0_18:
	v_mov_b32_e32 v200, 0
	v_mov_b32_e32 v201, 0
	v_mov_b32_e32 v202, 0
	v_mov_b32_e32 v203, 0
	v_mov_b32_e32 v204, 0
	v_mov_b32_e32 v205, 0
	v_mov_b32_e32 v206, 0
	v_mov_b32_e32 v207, 0
	v_mov_b32_e32 v208, 0
	v_mov_b32_e32 v209, 0
	v_mov_b32_e32 v210, 0
	v_mov_b32_e32 v211, 0
	v_mov_b32_e32 v212, 0
	v_mov_b32_e32 v213, 0
	v_mov_b32_e32 v214, 0
	v_mov_b32_e32 v215, 0
	v_mov_b32_e32 v216, 0
	v_mov_b32_e32 v217, 0
	v_mov_b32_e32 v218, 0
	v_mov_b32_e32 v219, 0
	v_mov_b32_e32 v220, 0
	v_mov_b32_e32 v221, 0
	v_mov_b32_e32 v222, 0
	v_mov_b32_e32 v223, 0
	v_mov_b32_e32 v224, 0
	v_mov_b32_e32 v225, 0
	v_mov_b32_e32 v226, 0
	v_mov_b32_e32 v227, 0
	v_mov_b32_e32 v228, 0
	v_mov_b32_e32 v229, 0
	v_mov_b32_e32 v230, 0
	v_mul_hi_i32 v4, v10, s18
	v_lshrrev_b32_e32 v5, 31, v4
	v_ashrrev_i32_e32 v4, 3, v4
	v_add_u32_e32 v5, v4, v5
	v_mul_lo_u32 v25, v5, s19
	v_lshlrev_b32_e32 v4, 6, v5
	v_add3_u32 v8, v11, v23, v25
	v_or_b32_e32 v6, v4, v12
	v_ashrrev_i32_e32 v9, 31, v8
	v_cmp_gt_i32_e32 vcc, s20, v8
	s_waitcnt lgkmcnt(0)
	v_lshl_add_u64 v[8:9], v[8:9], 2, s[6:7]
	v_ashrrev_i32_e32 v7, 31, v6
	v_mov_b32_e32 v5, 0
	s_and_saveexec_b64 s[10:11], vcc
	s_cbranch_execz .LBB0_20
	v_mad_i64_i32 v[26:27], s[26:27], v6, s21, v[8:9]
	global_load_dword v5, v[26:27], off nt
	v_lshl_add_u64 v[26:27], v[6:7], 2, s[4:5]
	global_load_dword v200, v[26:27], off
.LBB0_20:
	s_or_b64 exec, exec, s[10:11]
	v_mov_b32_e32 v26, 0
	v_mov_b32_e32 v27, 0
	s_and_saveexec_b64 s[10:11], vcc
	s_cbranch_execz .LBB0_22
	v_or_b32_e32 v27, 2, v6
	v_mad_i64_i32 v[28:29], s[26:27], v27, s21, v[8:9]
	global_load_dword v27, v[28:29], off nt
	v_lshl_add_u64 v[28:29], v[6:7], 2, s[4:5]
	global_load_dword v201, v[28:29], off offset:8
.LBB0_22:
	s_or_b64 exec, exec, s[10:11]
	s_and_saveexec_b64 s[10:11], vcc
	s_cbranch_execz .LBB0_24
	v_or_b32_e32 v26, 4, v6
	v_mad_i64_i32 v[28:29], s[26:27], v26, s21, v[8:9]
	global_load_dword v26, v[28:29], off nt
	v_lshl_add_u64 v[28:29], v[6:7], 2, s[4:5]
	global_load_dword v202, v[28:29], off offset:16
.LBB0_24:
	s_or_b64 exec, exec, s[10:11]
	v_mov_b32_e32 v28, 0
	v_mov_b32_e32 v29, 0
	s_and_saveexec_b64 s[10:11], vcc
	s_cbranch_execz .LBB0_26
	v_or_b32_e32 v29, 6, v6
	v_mad_i64_i32 v[30:31], s[26:27], v29, s21, v[8:9]
	global_load_dword v29, v[30:31], off nt
	v_lshl_add_u64 v[30:31], v[6:7], 2, s[4:5]
	global_load_dword v203, v[30:31], off offset:24
.LBB0_26:
	s_or_b64 exec, exec, s[10:11]
	s_and_saveexec_b64 s[10:11], vcc
	s_cbranch_execz .LBB0_28
	v_or_b32_e32 v28, 8, v6
	v_mad_i64_i32 v[30:31], s[26:27], v28, s21, v[8:9]
	global_load_dword v28, v[30:31], off nt
	v_lshl_add_u64 v[30:31], v[6:7], 2, s[4:5]
	global_load_dword v204, v[30:31], off offset:32
.LBB0_28:
	s_or_b64 exec, exec, s[10:11]
	v_mov_b32_e32 v30, 0
	v_mov_b32_e32 v31, 0
	s_and_saveexec_b64 s[10:11], vcc
	s_cbranch_execz .LBB0_30
	v_or_b32_e32 v31, 10, v6
	v_mad_i64_i32 v[32:33], s[26:27], v31, s21, v[8:9]
	global_load_dword v31, v[32:33], off nt
	v_lshl_add_u64 v[32:33], v[6:7], 2, s[4:5]
	global_load_dword v205, v[32:33], off offset:40
.LBB0_30:
	s_or_b64 exec, exec, s[10:11]
	s_and_saveexec_b64 s[10:11], vcc
	s_cbranch_execz .LBB0_32
	v_or_b32_e32 v30, 12, v6
	v_mad_i64_i32 v[32:33], s[26:27], v30, s21, v[8:9]
	global_load_dword v30, v[32:33], off nt
	v_lshl_add_u64 v[32:33], v[6:7], 2, s[4:5]
	global_load_dword v206, v[32:33], off offset:48
.LBB0_32:
	s_or_b64 exec, exec, s[10:11]
	v_mov_b32_e32 v32, 0
	v_mov_b32_e32 v33, 0
	s_and_saveexec_b64 s[10:11], vcc
	s_cbranch_execz .LBB0_34
	v_or_b32_e32 v33, 14, v6
	v_mad_i64_i32 v[34:35], s[26:27], v33, s21, v[8:9]
	global_load_dword v33, v[34:35], off nt
	v_lshl_add_u64 v[34:35], v[6:7], 2, s[4:5]
	global_load_dword v207, v[34:35], off offset:56
.LBB0_34:
	s_or_b64 exec, exec, s[10:11]
	s_and_saveexec_b64 s[10:11], vcc
	s_cbranch_execz .LBB0_36
	v_or_b32_e32 v32, 16, v6
	v_mad_i64_i32 v[34:35], s[26:27], v32, s21, v[8:9]
	global_load_dword v32, v[34:35], off nt
	v_lshl_add_u64 v[34:35], v[6:7], 2, s[4:5]
	global_load_dword v208, v[34:35], off offset:64
.LBB0_36:
	s_or_b64 exec, exec, s[10:11]
	v_mov_b32_e32 v34, 0
	v_mov_b32_e32 v35, 0
	s_and_saveexec_b64 s[10:11], vcc
	s_cbranch_execz .LBB0_38
	v_or_b32_e32 v35, 18, v6
	v_mad_i64_i32 v[36:37], s[26:27], v35, s21, v[8:9]
	global_load_dword v35, v[36:37], off nt
	v_lshl_add_u64 v[36:37], v[6:7], 2, s[4:5]
	global_load_dword v209, v[36:37], off offset:72
.LBB0_38:
	s_or_b64 exec, exec, s[10:11]
	s_and_saveexec_b64 s[10:11], vcc
	s_cbranch_execz .LBB0_40
	v_or_b32_e32 v34, 20, v6
	v_mad_i64_i32 v[36:37], s[26:27], v34, s21, v[8:9]
	global_load_dword v34, v[36:37], off nt
	v_lshl_add_u64 v[36:37], v[6:7], 2, s[4:5]
	global_load_dword v210, v[36:37], off offset:80
.LBB0_40:
	s_or_b64 exec, exec, s[10:11]
	v_mov_b32_e32 v36, 0
	v_mov_b32_e32 v37, 0
	s_and_saveexec_b64 s[10:11], vcc
	s_cbranch_execz .LBB0_42
	v_or_b32_e32 v37, 22, v6
	v_mad_i64_i32 v[38:39], s[26:27], v37, s21, v[8:9]
	global_load_dword v37, v[38:39], off nt
	v_lshl_add_u64 v[38:39], v[6:7], 2, s[4:5]
	global_load_dword v211, v[38:39], off offset:88
.LBB0_42:
	s_or_b64 exec, exec, s[10:11]
	s_and_saveexec_b64 s[10:11], vcc
	s_cbranch_execz .LBB0_44
	v_or_b32_e32 v36, 24, v6
	v_mad_i64_i32 v[38:39], s[26:27], v36, s21, v[8:9]
	global_load_dword v36, v[38:39], off nt
	v_lshl_add_u64 v[38:39], v[6:7], 2, s[4:5]
	global_load_dword v212, v[38:39], off offset:96
.LBB0_44:
	s_or_b64 exec, exec, s[10:11]
	v_mov_b32_e32 v38, 0
	v_mov_b32_e32 v39, 0
	s_and_saveexec_b64 s[10:11], vcc
	s_cbranch_execz .LBB0_46
	v_or_b32_e32 v39, 26, v6
	v_mad_i64_i32 v[40:41], s[26:27], v39, s21, v[8:9]
	global_load_dword v39, v[40:41], off nt
	v_lshl_add_u64 v[40:41], v[6:7], 2, s[4:5]
	global_load_dword v213, v[40:41], off offset:104
; #define LAS __attribute__((address_space(3)))
; template <class F> DI void tr_items(const F& f, int Kdst, int Nrows, bf16_t* WT, LAS float* scr, int gw, int NGW, int lane, int& cum) {
;     const int nblk = Nrows / 32, nitems = (Kdst / 64) * nblk;
;     int first = (gw - cum) % NGW; if (first < 0) first += NGW; cum = (cum + nitems) % NGW;
;     for (int item = first; item < nitems; item += NGW) {
;         const int kb = item / nblk, nb = item % nblk, k0 = 64 * kb, n0 = 32 * nb;
;         float tv[32];
; #pragma unroll
;         for (int i = 0; i < 32; ++i) tv[i] = f(k0 + 2 * i + (lane >> 5), n0 + (lane & 31));
.LBB0_46:
	s_or_b64 exec, exec, s[10:11]
	s_and_saveexec_b64 s[10:11], vcc
	s_cbranch_execz .LBB0_48
	v_or_b32_e32 v38, 28, v6
	v_mad_i64_i32 v[40:41], s[26:27], v38, s21, v[8:9]
	global_load_dword v38, v[40:41], off nt
	v_lshl_add_u64 v[40:41], v[6:7], 2, s[4:5]
	global_load_dword v214, v[40:41], off offset:112
.LBB0_48:
	s_or_b64 exec, exec, s[10:11]
	v_mov_b32_e32 v40, 0
	v_mov_b32_e32 v41, 0
	s_and_saveexec_b64 s[10:11], vcc
	s_cbranch_execz .LBB0_50
	v_or_b32_e32 v41, 30, v6
	v_mad_i64_i32 v[42:43], s[26:27], v41, s21, v[8:9]
	global_load_dword v41, v[42:43], off nt
	v_lshl_add_u64 v[42:43], v[6:7], 2, s[4:5]
	global_load_dword v215, v[42:43], off offset:120
.LBB0_50:
	s_or_b64 exec, exec, s[10:11]
	s_and_saveexec_b64 s[10:11], vcc
	s_cbranch_execz .LBB0_52
	v_or_b32_e32 v40, 32, v6
	v_mad_i64_i32 v[42:43], s[26:27], v40, s21, v[8:9]
	global_load_dword v40, v[42:43], off nt
	v_lshl_add_u64 v[42:43], v[6:7], 2, s[4:5]
	global_load_dword v216, v[42:43], off offset:128
.LBB0_52:
	s_or_b64 exec, exec, s[10:11]
	v_mov_b32_e32 v42, 0
	v_mov_b32_e32 v43, 0
	s_and_saveexec_b64 s[10:11], vcc
	s_cbranch_execz .LBB0_54
	v_or_b32_e32 v43, 34, v6
	v_mad_i64_i32 v[44:45], s[26:27], v43, s21, v[8:9]
	global_load_dword v43, v[44:45], off nt
	v_lshl_add_u64 v[44:45], v[6:7], 2, s[4:5]
	global_load_dword v217, v[44:45], off offset:136
.LBB0_54:
	s_or_b64 exec, exec, s[10:11]
	s_and_saveexec_b64 s[10:11], vcc
	s_cbranch_execz .LBB0_56
	v_or_b32_e32 v42, 36, v6
	v_mad_i64_i32 v[44:45], s[26:27], v42, s21, v[8:9]
	global_load_dword v42, v[44:45], off nt
	v_lshl_add_u64 v[44:45], v[6:7], 2, s[4:5]
	global_load_dword v218, v[44:45], off offset:144
.LBB0_56:
	s_or_b64 exec, exec, s[10:11]
	v_mov_b32_e32 v44, 0
	v_mov_b32_e32 v45, 0
	s_and_saveexec_b64 s[10:11], vcc
	s_cbranch_execz .LBB0_58
	v_or_b32_e32 v45, 38, v6
	v_mad_i64_i32 v[46:47], s[26:27], v45, s21, v[8:9]
	global_load_dword v45, v[46:47], off nt
	v_lshl_add_u64 v[46:47], v[6:7], 2, s[4:5]
	global_load_dword v219, v[46:47], off offset:152
.LBB0_58:
	s_or_b64 exec, exec, s[10:11]
	s_and_saveexec_b64 s[10:11], vcc
	s_cbranch_execz .LBB0_60
	v_or_b32_e32 v44, 40, v6
	v_mad_i64_i32 v[46:47], s[26:27], v44, s21, v[8:9]
	global_load_dword v44, v[46:47], off nt
	v_lshl_add_u64 v[46:47], v[6:7], 2, s[4:5]
	global_load_dword v220, v[46:47], off offset:160
.LBB0_60:
	s_or_b64 exec, exec, s[10:11]
	v_mov_b32_e32 v46, 0
	v_mov_b32_e32 v47, 0
	s_and_saveexec_b64 s[10:11], vcc
	s_cbranch_execz .LBB0_62
	v_or_b32_e32 v47, 42, v6
	v_mad_i64_i32 v[48:49], s[26:27], v47, s21, v[8:9]
	global_load_dword v47, v[48:49], off nt
	v_lshl_add_u64 v[48:49], v[6:7], 2, s[4:5]
	global_load_dword v221, v[48:49], off offset:168
.LBB0_62:
	s_or_b64 exec, exec, s[10:11]
	s_and_saveexec_b64 s[10:11], vcc
	s_cbranch_execz .LBB0_64
	v_or_b32_e32 v46, 44, v6
	v_mad_i64_i32 v[48:49], s[26:27], v46, s21, v[8:9]
	global_load_dword v46, v[48:49], off nt
	v_lshl_add_u64 v[48:49], v[6:7], 2, s[4:5]
	global_load_dword v222, v[48:49], off offset:176
.LBB0_64:
	s_or_b64 exec, exec, s[10:11]
	v_mov_b32_e32 v48, 0
	v_mov_b32_e32 v49, 0
	s_and_saveexec_b64 s[10:11], vcc
	s_cbranch_execz .LBB0_66
	v_or_b32_e32 v49, 46, v6
	v_mad_i64_i32 v[50:51], s[26:27], v49, s21, v[8:9]
	global_load_dword v49, v[50:51], off nt
	v_lshl_add_u64 v[50:51], v[6:7], 2, s[4:5]
	global_load_dword v223, v[50:51], off offset:184
.LBB0_66:
	s_or_b64 exec, exec, s[10:11]
	s_and_saveexec_b64 s[10:11], vcc
	s_cbranch_execz .LBB0_68
	v_or_b32_e32 v48, 48, v6
	v_mad_i64_i32 v[50:51], s[26:27], v48, s21, v[8:9]
	global_load_dword v48, v[50:51], off nt
	v_lshl_add_u64 v[50:51], v[6:7], 2, s[4:5]
	global_load_dword v224, v[50:51], off offset:192
.LBB0_68:
	s_or_b64 exec, exec, s[10:11]
	v_mov_b32_e32 v50, 0
	v_mov_b32_e32 v51, 0
	s_and_saveexec_b64 s[10:11], vcc
	s_cbranch_execz .LBB0_70
	v_or_b32_e32 v51, 50, v6
	v_mad_i64_i32 v[52:53], s[26:27], v51, s21, v[8:9]
	global_load_dword v51, v[52:53], off nt
	v_lshl_add_u64 v[52:53], v[6:7], 2, s[4:5]
	global_load_dword v225, v[52:53], off offset:200
.LBB0_70:
	s_or_b64 exec, exec, s[10:11]
	s_and_saveexec_b64 s[10:11], vcc
	s_cbranch_execz .LBB0_72
	v_or_b32_e32 v50, 52, v6
	v_mad_i64_i32 v[52:53], s[26:27], v50, s21, v[8:9]
	global_load_dword v50, v[52:53], off nt
	v_lshl_add_u64 v[52:53], v[6:7], 2, s[4:5]
	global_load_dword v226, v[52:53], off offset:208
.LBB0_72:
	s_or_b64 exec, exec, s[10:11]
	v_mov_b32_e32 v52, 0
	v_mov_b32_e32 v53, 0
	s_and_saveexec_b64 s[10:11], vcc
	s_cbranch_execz .LBB0_74
	v_or_b32_e32 v53, 54, v6
	v_mad_i64_i32 v[54:55], s[26:27], v53, s21, v[8:9]
	global_load_dword v53, v[54:55], off nt
	v_lshl_add_u64 v[54:55], v[6:7], 2, s[4:5]
	global_load_dword v227, v[54:55], off offset:216
.LBB0_74:
	s_or_b64 exec, exec, s[10:11]
	s_and_saveexec_b64 s[10:11], vcc
	s_cbranch_execz .LBB0_76
	v_or_b32_e32 v52, 56, v6
	v_mad_i64_i32 v[54:55], s[26:27], v52, s21, v[8:9]
	global_load_dword v52, v[54:55], off nt
	v_lshl_add_u64 v[54:55], v[6:7], 2, s[4:5]
	global_load_dword v228, v[54:55], off offset:224
.LBB0_76:
	s_or_b64 exec, exec, s[10:11]
	v_mov_b32_e32 v54, 0
	v_mov_b32_e32 v55, 0
	s_and_saveexec_b64 s[10:11], vcc
	s_cbranch_execz .LBB0_79
	v_or_b32_e32 v55, 58, v6
	v_mad_i64_i32 v[56:57], s[26:27], v55, s21, v[8:9]
	global_load_dword v55, v[56:57], off nt
	v_lshl_add_u64 v[56:57], v[6:7], 2, s[4:5]
	global_load_dword v229, v[56:57], off offset:232
	s_or_b64 exec, exec, s[10:11]
	s_and_saveexec_b64 s[10:11], vcc
	s_cbranch_execnz .LBB0_80

; #define LAS __attribute__((address_space(3)))
; template <class F> DI void tr_items(const F& f, int Kdst, int Nrows, bf16_t* WT, LAS float* scr, int gw, int NGW, int lane, int& cum) {
;     const int nblk = Nrows / 32, nitems = (Kdst / 64) * nblk;
;     int first = (gw - cum) % NGW; if (first < 0) first += NGW; cum = (cum + nitems) % NGW;
;     for (int item = first; item < nitems; item += NGW) {
;         const int kb = item / nblk, nb = item % nblk, k0 = 64 * kb, n0 = 32 * nb;
;         float tv[32];
; #pragma unroll
;         for (int i = 0; i < 32; ++i) tv[i] = f(k0 + 2 * i + (lane >> 5), n0 + (lane & 31));
.LBB0_80:
	v_or_b32_e32 v54, 60, v6
	v_mad_i64_i32 v[56:57], s[26:27], v54, s21, v[8:9]
	global_load_dword v54, v[56:57], off nt
	v_lshl_add_u64 v[56:57], v[6:7], 2, s[4:5]
	global_load_dword v230, v[56:57], off offset:240
	s_or_b64 exec, exec, s[10:11]
	s_waitcnt vmcnt(0)
	v_mul_f32_e32 v5, v5, v200
	v_mul_f32_e32 v27, v27, v201
	v_mul_f32_e32 v26, v26, v202
	v_mul_f32_e32 v29, v29, v203
	v_mul_f32_e32 v28, v28, v204
	v_mul_f32_e32 v31, v31, v205
	v_mul_f32_e32 v30, v30, v206
	v_mul_f32_e32 v33, v33, v207
	v_mul_f32_e32 v32, v32, v208
	v_mul_f32_e32 v35, v35, v209
	v_mul_f32_e32 v34, v34, v210
	v_mul_f32_e32 v37, v37, v211
	v_mul_f32_e32 v36, v36, v212
	v_mul_f32_e32 v39, v39, v213
	v_mul_f32_e32 v38, v38, v214
	v_mul_f32_e32 v41, v41, v215
	v_mul_f32_e32 v40, v40, v216
	v_mul_f32_e32 v43, v43, v217
	v_mul_f32_e32 v42, v42, v218
	v_mul_f32_e32 v45, v45, v219
	v_mul_f32_e32 v44, v44, v220
	v_mul_f32_e32 v47, v47, v221
	v_mul_f32_e32 v46, v46, v222
	v_mul_f32_e32 v49, v49, v223
	v_mul_f32_e32 v48, v48, v224
	v_mul_f32_e32 v51, v51, v225
	v_mul_f32_e32 v50, v50, v226
	v_mul_f32_e32 v53, v53, v227
	v_mul_f32_e32 v52, v52, v228
	v_mul_f32_e32 v55, v55, v229
	v_mul_f32_e32 v54, v54, v230
	v_mov_b32_e32 v56, 0
	s_and_saveexec_b64 s[10:11], vcc
	s_cbranch_execz .LBB0_17

; #define LAS __attribute__((address_space(3)))
; template <class F> DI void tr_items(const F& f, int Kdst, int Nrows, bf16_t* WT, LAS float* scr, int gw, int NGW, int lane, int& cum) {
;     const int nblk = Nrows / 32, nitems = (Kdst / 64) * nblk;
;     int first = (gw - cum) % NGW; if (first < 0) first += NGW; cum = (cum + nitems) % NGW;
;     for (int item = first; item < nitems; item += NGW) {
;         const int kb = item / nblk, nb = item % nblk, k0 = 64 * kb, n0 = 32 * nb;
;         float tv[32];
; #pragma unroll
;         for (int i = 0; i < 32; ++i) tv[i] = f(k0 + 2 * i + (lane >> 5), n0 + (lane & 31));
; DI void phase_prologue(int wv, const ArgP a, LAS unsigned char* lds, int parts) {
;     ...
;     { FWKV f{a.in(14), a.in(13), 0}; tr_items(f, 256, 512, (bf16_t*)(ws + O_WKT), scr, gw, NGW, lane, cum); }
.LBB0_88:
	v_mov_b32_e32 v200, 0
	v_mov_b32_e32 v201, 0
	v_mov_b32_e32 v202, 0
	v_mov_b32_e32 v203, 0
	v_mov_b32_e32 v204, 0
	v_mov_b32_e32 v205, 0
	v_mov_b32_e32 v206, 0
	v_mov_b32_e32 v207, 0
	v_mov_b32_e32 v208, 0
	v_mov_b32_e32 v209, 0
	v_mov_b32_e32 v210, 0
	v_mov_b32_e32 v211, 0
	v_mov_b32_e32 v212, 0
	v_mov_b32_e32 v213, 0
	v_mov_b32_e32 v214, 0
	v_mov_b32_e32 v215, 0
	v_mov_b32_e32 v216, 0
	v_mov_b32_e32 v217, 0
	v_mov_b32_e32 v218, 0
	v_mov_b32_e32 v219, 0
	v_mov_b32_e32 v220, 0
	v_mov_b32_e32 v221, 0
	v_mov_b32_e32 v222, 0
	v_mov_b32_e32 v223, 0
	v_mov_b32_e32 v224, 0
	v_mov_b32_e32 v225, 0
	v_mov_b32_e32 v226, 0
	v_mov_b32_e32 v227, 0
	v_mov_b32_e32 v228, 0
	v_mov_b32_e32 v229, 0
	v_mov_b32_e32 v230, 0
	v_ashrrev_i32_e32 v2, 31, v22
	v_lshrrev_b32_e32 v2, 28, v2
	v_add_u32_e32 v2, v22, v2
	v_ashrrev_i32_e32 v2, 4, v2
	v_lshlrev_b32_e32 v6, 6, v2
	v_lshlrev_b32_e32 v7, 9, v2
	v_lshlrev_b32_e32 v2, 10, v2
	v_sub_u32_e32 v2, v28, v2
	v_sub_u32_e32 v9, v27, v7
	v_and_b32_e32 v10, 0xffffff80, v2
	v_ashrrev_i32_e32 v11, 31, v10
	v_and_or_b32 v2, v9, 32, v24
	v_or_b32_e32 v8, v6, v23
	s_waitcnt lgkmcnt(0)
	v_lshl_add_u64 v[10:11], v[10:11], 2, s[6:7]
	v_lshlrev_b32_e32 v2, 2, v2
	v_lshl_add_u64 v[10:11], v[10:11], 0, v[2:3]
	v_cmp_gt_i32_e32 vcc, s21, v8
	v_ashrrev_i32_e32 v9, 31, v8
	v_mov_b32_e32 v2, 0
	s_and_saveexec_b64 s[10:11], vcc
	s_cbranch_execz .LBB0_90
	v_lshlrev_b64 v[12:13], 12, v[8:9]
	v_lshl_add_u64 v[12:13], v[10:11], 0, v[12:13]
	v_lshl_add_u64 v[30:31], v[8:9], 2, s[4:5]
	global_load_dword v2, v[12:13], off nt
	global_load_dword v200, v[30:31], off
.LBB0_90:
	s_or_b64 exec, exec, s[10:11]
	v_or_b32_e32 v12, 2, v8
	v_cmp_gt_i32_e32 vcc, s21, v12
	v_mov_b32_e32 v30, 0
	v_mov_b32_e32 v31, 0
	s_and_saveexec_b64 s[10:11], vcc
	s_cbranch_execz .LBB0_92
	v_ashrrev_i32_e32 v13, 31, v12
	v_lshlrev_b64 v[12:13], 12, v[12:13]
	v_lshl_add_u64 v[12:13], v[10:11], 0, v[12:13]
	v_lshl_add_u64 v[32:33], v[8:9], 2, s[4:5]
	global_load_dword v31, v[12:13], off nt
	global_load_dword v201, v[32:33], off offset:8
.LBB0_92:
	s_or_b64 exec, exec, s[10:11]
	v_or_b32_e32 v12, 4, v8
	v_cmp_gt_i32_e32 vcc, s21, v12
	s_and_saveexec_b64 s[10:11], vcc
	s_cbranch_execz .LBB0_94
	v_ashrrev_i32_e32 v13, 31, v12
	v_lshlrev_b64 v[12:13], 12, v[12:13]
	v_lshl_add_u64 v[12:13], v[10:11], 0, v[12:13]
	v_lshl_add_u64 v[32:33], v[8:9], 2, s[4:5]
	global_load_dword v30, v[12:13], off nt
	global_load_dword v202, v[32:33], off offset:16
.LBB0_94:
	s_or_b64 exec, exec, s[10:11]
	v_or_b32_e32 v12, 6, v8
	v_cmp_gt_i32_e32 vcc, s21, v12
	v_mov_b32_e32 v32, 0
	v_mov_b32_e32 v33, 0
	s_and_saveexec_b64 s[10:11], vcc
	s_cbranch_execz .LBB0_96
	v_ashrrev_i32_e32 v13, 31, v12
	v_lshlrev_b64 v[12:13], 12, v[12:13]
	v_lshl_add_u64 v[12:13], v[10:11], 0, v[12:13]
	v_lshl_add_u64 v[34:35], v[8:9], 2, s[4:5]
	global_load_dword v33, v[12:13], off nt
	global_load_dword v203, v[34:35], off offset:24
.LBB0_96:
	s_or_b64 exec, exec, s[10:11]
	v_or_b32_e32 v12, 8, v8
	v_cmp_gt_i32_e32 vcc, s21, v12
	s_and_saveexec_b64 s[10:11], vcc
	s_cbranch_execz .LBB0_98
	v_ashrrev_i32_e32 v13, 31, v12
	v_lshlrev_b64 v[12:13], 12, v[12:13]
	v_lshl_add_u64 v[12:13], v[10:11], 0, v[12:13]
	v_lshl_add_u64 v[34:35], v[8:9], 2, s[4:5]
	global_load_dword v32, v[12:13], off nt
	global_load_dword v204, v[34:35], off offset:32
.LBB0_98:
	s_or_b64 exec, exec, s[10:11]
	v_or_b32_e32 v12, 10, v8
	v_cmp_gt_i32_e32 vcc, s21, v12
	v_mov_b32_e32 v34, 0
	v_mov_b32_e32 v35, 0
	s_and_saveexec_b64 s[10:11], vcc
	s_cbranch_execz .LBB0_100
	v_ashrrev_i32_e32 v13, 31, v12
	v_lshlrev_b64 v[12:13], 12, v[12:13]
	v_lshl_add_u64 v[12:13], v[10:11], 0, v[12:13]
	v_lshl_add_u64 v[36:37], v[8:9], 2, s[4:5]
	global_load_dword v35, v[12:13], off nt
	global_load_dword v205, v[36:37], off offset:40
.LBB0_100:
	s_or_b64 exec, exec, s[10:11]
	v_or_b32_e32 v12, 12, v8
	v_cmp_gt_i32_e32 vcc, s21, v12
	s_and_saveexec_b64 s[10:11], vcc
	s_cbranch_execz .LBB0_102
	v_ashrrev_i32_e32 v13, 31, v12
	v_lshlrev_b64 v[12:13], 12, v[12:13]
	v_lshl_add_u64 v[12:13], v[10:11], 0, v[12:13]
	v_lshl_add_u64 v[36:37], v[8:9], 2, s[4:5]
	global_load_dword v34, v[12:13], off nt
	global_load_dword v206, v[36:37], off offset:48
.LBB0_102:
	s_or_b64 exec, exec, s[10:11]
	v_or_b32_e32 v12, 14, v8
	v_cmp_gt_i32_e32 vcc, s21, v12
	v_mov_b32_e32 v36, 0
	v_mov_b32_e32 v37, 0
	s_and_saveexec_b64 s[10:11], vcc
	s_cbranch_execz .LBB0_104
	v_ashrrev_i32_e32 v13, 31, v12
	v_lshlrev_b64 v[12:13], 12, v[12:13]
	v_lshl_add_u64 v[12:13], v[10:11], 0, v[12:13]
	v_lshl_add_u64 v[38:39], v[8:9], 2, s[4:5]
	global_load_dword v37, v[12:13], off nt
	global_load_dword v207, v[38:39], off offset:56
.LBB0_104:
	s_or_b64 exec, exec, s[10:11]
	v_or_b32_e32 v12, 16, v8
	v_cmp_gt_i32_e32 vcc, s21, v12
	s_and_saveexec_b64 s[10:11], vcc
	s_cbranch_execz .LBB0_106
	v_ashrrev_i32_e32 v13, 31, v12
	v_lshlrev_b64 v[12:13], 12, v[12:13]
	v_lshl_add_u64 v[12:13], v[10:11], 0, v[12:13]
	v_lshl_add_u64 v[38:39], v[8:9], 2, s[4:5]
	global_load_dword v36, v[12:13], off nt
	global_load_dword v208, v[38:39], off offset:64
.LBB0_106:
	s_or_b64 exec, exec, s[10:11]
	v_or_b32_e32 v12, 18, v8
	v_cmp_gt_i32_e32 vcc, s21, v12
	v_mov_b32_e32 v38, 0
	v_mov_b32_e32 v39, 0
	s_and_saveexec_b64 s[10:11], vcc
	s_cbranch_execz .LBB0_108
	v_ashrrev_i32_e32 v13, 31, v12
	v_lshlrev_b64 v[12:13], 12, v[12:13]
	v_lshl_add_u64 v[12:13], v[10:11], 0, v[12:13]
	v_lshl_add_u64 v[40:41], v[8:9], 2, s[4:5]
	global_load_dword v39, v[12:13], off nt
	global_load_dword v209, v[40:41], off offset:72
; #define LAS __attribute__((address_space(3)))
; template <class F> DI void tr_items(const F& f, int Kdst, int Nrows, bf16_t* WT, LAS float* scr, int gw, int NGW, int lane, int& cum) {
;     const int nblk = Nrows / 32, nitems = (Kdst / 64) * nblk;
;     int first = (gw - cum) % NGW; if (first < 0) first += NGW; cum = (cum + nitems) % NGW;
;     for (int item = first; item < nitems; item += NGW) {
;         const int kb = item / nblk, nb = item % nblk, k0 = 64 * kb, n0 = 32 * nb;
;         float tv[32];
; #pragma unroll
;         for (int i = 0; i < 32; ++i) tv[i] = f(k0 + 2 * i + (lane >> 5), n0 + (lane & 31));
; DI void phase_prologue(int wv, const ArgP a, LAS unsigned char* lds, int parts) {
;     ...
;     { FWKV f{a.in(14), a.in(13), 0}; tr_items(f, 256, 512, (bf16_t*)(ws + O_WKT), scr, gw, NGW, lane, cum); }
.LBB0_108:
	s_or_b64 exec, exec, s[10:11]
	v_or_b32_e32 v12, 20, v8
	v_cmp_gt_i32_e32 vcc, s21, v12
	s_and_saveexec_b64 s[10:11], vcc
	s_cbranch_execz .LBB0_110
	v_ashrrev_i32_e32 v13, 31, v12
	v_lshlrev_b64 v[12:13], 12, v[12:13]
	v_lshl_add_u64 v[12:13], v[10:11], 0, v[12:13]
	v_lshl_add_u64 v[40:41], v[8:9], 2, s[4:5]
	global_load_dword v38, v[12:13], off nt
	global_load_dword v210, v[40:41], off offset:80
.LBB0_110:
	s_or_b64 exec, exec, s[10:11]
	v_or_b32_e32 v12, 22, v8
	v_cmp_gt_i32_e32 vcc, s21, v12
	v_mov_b32_e32 v40, 0
	v_mov_b32_e32 v41, 0
	s_and_saveexec_b64 s[10:11], vcc
	s_cbranch_execz .LBB0_112
	v_ashrrev_i32_e32 v13, 31, v12
	v_lshlrev_b64 v[12:13], 12, v[12:13]
	v_lshl_add_u64 v[12:13], v[10:11], 0, v[12:13]
	v_lshl_add_u64 v[42:43], v[8:9], 2, s[4:5]
	global_load_dword v41, v[12:13], off nt
	global_load_dword v211, v[42:43], off offset:88
.LBB0_112:
	s_or_b64 exec, exec, s[10:11]
	v_or_b32_e32 v12, 24, v8
	v_cmp_gt_i32_e32 vcc, s21, v12
	s_and_saveexec_b64 s[10:11], vcc
	s_cbranch_execz .LBB0_114
	v_ashrrev_i32_e32 v13, 31, v12
	v_lshlrev_b64 v[12:13], 12, v[12:13]
	v_lshl_add_u64 v[12:13], v[10:11], 0, v[12:13]
	v_lshl_add_u64 v[42:43], v[8:9], 2, s[4:5]
	global_load_dword v40, v[12:13], off nt
	global_load_dword v212, v[42:43], off offset:96
.LBB0_114:
	s_or_b64 exec, exec, s[10:11]
	v_or_b32_e32 v12, 26, v8
	v_cmp_gt_i32_e32 vcc, s21, v12
	v_mov_b32_e32 v42, 0
	v_mov_b32_e32 v43, 0
	s_and_saveexec_b64 s[10:11], vcc
	s_cbranch_execz .LBB0_116
	v_ashrrev_i32_e32 v13, 31, v12
	v_lshlrev_b64 v[12:13], 12, v[12:13]
	v_lshl_add_u64 v[12:13], v[10:11], 0, v[12:13]
	v_lshl_add_u64 v[44:45], v[8:9], 2, s[4:5]
	global_load_dword v43, v[12:13], off nt
	global_load_dword v213, v[44:45], off offset:104
.LBB0_116:
	s_or_b64 exec, exec, s[10:11]
	v_or_b32_e32 v12, 28, v8
	v_cmp_gt_i32_e32 vcc, s21, v12
	s_and_saveexec_b64 s[10:11], vcc
	s_cbranch_execz .LBB0_118
	v_ashrrev_i32_e32 v13, 31, v12
	v_lshlrev_b64 v[12:13], 12, v[12:13]
	v_lshl_add_u64 v[12:13], v[10:11], 0, v[12:13]
	v_lshl_add_u64 v[44:45], v[8:9], 2, s[4:5]
	global_load_dword v42, v[12:13], off nt
	global_load_dword v214, v[44:45], off offset:112
.LBB0_118:
	s_or_b64 exec, exec, s[10:11]
	v_or_b32_e32 v12, 30, v8
	v_cmp_gt_i32_e32 vcc, s21, v12
	v_mov_b32_e32 v44, 0
	v_mov_b32_e32 v45, 0
	s_and_saveexec_b64 s[10:11], vcc
	s_cbranch_execz .LBB0_120
	v_ashrrev_i32_e32 v13, 31, v12
	v_lshlrev_b64 v[12:13], 12, v[12:13]
	v_lshl_add_u64 v[12:13], v[10:11], 0, v[12:13]
	v_lshl_add_u64 v[46:47], v[8:9], 2, s[4:5]
	global_load_dword v45, v[12:13], off nt
	global_load_dword v215, v[46:47], off offset:120
.LBB0_120:
	s_or_b64 exec, exec, s[10:11]
	v_or_b32_e32 v12, 32, v8
	v_cmp_gt_i32_e32 vcc, s21, v12
	s_and_saveexec_b64 s[10:11], vcc
	s_cbranch_execz .LBB0_122
	v_ashrrev_i32_e32 v13, 31, v12
	v_lshlrev_b64 v[12:13], 12, v[12:13]
	v_lshl_add_u64 v[12:13], v[10:11], 0, v[12:13]
	v_lshl_add_u64 v[46:47], v[8:9], 2, s[4:5]
	global_load_dword v44, v[12:13], off nt
	global_load_dword v216, v[46:47], off offset:128
.LBB0_122:
	s_or_b64 exec, exec, s[10:11]
	v_or_b32_e32 v12, 34, v8
	v_cmp_gt_i32_e32 vcc, s21, v12
	v_mov_b32_e32 v46, 0
	v_mov_b32_e32 v47, 0
	s_and_saveexec_b64 s[10:11], vcc
	s_cbranch_execz .LBB0_124
	v_ashrrev_i32_e32 v13, 31, v12
	v_lshlrev_b64 v[12:13], 12, v[12:13]
	v_lshl_add_u64 v[12:13], v[10:11], 0, v[12:13]
	v_lshl_add_u64 v[48:49], v[8:9], 2, s[4:5]
	global_load_dword v47, v[12:13], off nt
	global_load_dword v217, v[48:49], off offset:136
.LBB0_124:
	s_or_b64 exec, exec, s[10:11]
	v_or_b32_e32 v12, 36, v8
	v_cmp_gt_i32_e32 vcc, s21, v12
	s_and_saveexec_b64 s[10:11], vcc
	s_cbranch_execz .LBB0_126
	v_ashrrev_i32_e32 v13, 31, v12
	v_lshlrev_b64 v[12:13], 12, v[12:13]
	v_lshl_add_u64 v[12:13], v[10:11], 0, v[12:13]
	v_lshl_add_u64 v[48:49], v[8:9], 2, s[4:5]
	global_load_dword v46, v[12:13], off nt
	global_load_dword v218, v[48:49], off offset:144
.LBB0_126:
	s_or_b64 exec, exec, s[10:11]
	v_or_b32_e32 v12, 38, v8
	v_cmp_gt_i32_e32 vcc, s21, v12
	v_mov_b32_e32 v48, 0
	v_mov_b32_e32 v49, 0
	s_and_saveexec_b64 s[10:11], vcc
	s_cbranch_execz .LBB0_128
	v_ashrrev_i32_e32 v13, 31, v12
	v_lshlrev_b64 v[12:13], 12, v[12:13]
	v_lshl_add_u64 v[12:13], v[10:11], 0, v[12:13]
	v_lshl_add_u64 v[50:51], v[8:9], 2, s[4:5]
	global_load_dword v49, v[12:13], off nt
	global_load_dword v219, v[50:51], off offset:152
.LBB0_128:
	s_or_b64 exec, exec, s[10:11]
	v_or_b32_e32 v12, 40, v8
	v_cmp_gt_i32_e32 vcc, s21, v12
	s_and_saveexec_b64 s[10:11], vcc
	s_cbranch_execz .LBB0_130
	v_ashrrev_i32_e32 v13, 31, v12
	v_lshlrev_b64 v[12:13], 12, v[12:13]
	v_lshl_add_u64 v[12:13], v[10:11], 0, v[12:13]
	v_lshl_add_u64 v[50:51], v[8:9], 2, s[4:5]
	global_load_dword v48, v[12:13], off nt
	global_load_dword v220, v[50:51], off offset:160
.LBB0_130:
	s_or_b64 exec, exec, s[10:11]
	v_or_b32_e32 v12, 42, v8
	v_cmp_gt_i32_e32 vcc, s21, v12
	v_mov_b32_e32 v50, 0
	v_mov_b32_e32 v51, 0
	s_and_saveexec_b64 s[10:11], vcc
	s_cbranch_execz .LBB0_132
	v_ashrrev_i32_e32 v13, 31, v12
	v_lshlrev_b64 v[12:13], 12, v[12:13]
	v_lshl_add_u64 v[12:13], v[10:11], 0, v[12:13]
	v_lshl_add_u64 v[52:53], v[8:9], 2, s[4:5]
	global_load_dword v51, v[12:13], off nt
	global_load_dword v221, v[52:53], off offset:168
; #define LAS __attribute__((address_space(3)))
; template <class F> DI void tr_items(const F& f, int Kdst, int Nrows, bf16_t* WT, LAS float* scr, int gw, int NGW, int lane, int& cum) {
;     const int nblk = Nrows / 32, nitems = (Kdst / 64) * nblk;
;     int first = (gw - cum) % NGW; if (first < 0) first += NGW; cum = (cum + nitems) % NGW;
;     for (int item = first; item < nitems; item += NGW) {
;         const int kb = item / nblk, nb = item % nblk, k0 = 64 * kb, n0 = 32 * nb;
;         float tv[32];
; #pragma unroll
;         for (int i = 0; i < 32; ++i) tv[i] = f(k0 + 2 * i + (lane >> 5), n0 + (lane & 31));
; DI void phase_prologue(int wv, const ArgP a, LAS unsigned char* lds, int parts) {
;     ...
;     { FWKV f{a.in(14), a.in(13), 0}; tr_items(f, 256, 512, (bf16_t*)(ws + O_WKT), scr, gw, NGW, lane, cum); }
.LBB0_132:
	s_or_b64 exec, exec, s[10:11]
	v_or_b32_e32 v12, 44, v8
	v_cmp_gt_i32_e32 vcc, s21, v12
	s_and_saveexec_b64 s[10:11], vcc
	s_cbranch_execz .LBB0_134
	v_ashrrev_i32_e32 v13, 31, v12
	v_lshlrev_b64 v[12:13], 12, v[12:13]
	v_lshl_add_u64 v[12:13], v[10:11], 0, v[12:13]
	v_lshl_add_u64 v[52:53], v[8:9], 2, s[4:5]
	global_load_dword v50, v[12:13], off nt
	global_load_dword v222, v[52:53], off offset:176
.LBB0_134:
	s_or_b64 exec, exec, s[10:11]
	v_or_b32_e32 v12, 46, v8
	v_cmp_gt_i32_e32 vcc, s21, v12
	v_mov_b32_e32 v52, 0
	v_mov_b32_e32 v53, 0
	s_and_saveexec_b64 s[10:11], vcc
	s_cbranch_execz .LBB0_136
	v_ashrrev_i32_e32 v13, 31, v12
	v_lshlrev_b64 v[12:13], 12, v[12:13]
	v_lshl_add_u64 v[12:13], v[10:11], 0, v[12:13]
	v_lshl_add_u64 v[54:55], v[8:9], 2, s[4:5]
	global_load_dword v53, v[12:13], off nt
	global_load_dword v223, v[54:55], off offset:184
.LBB0_136:
	s_or_b64 exec, exec, s[10:11]
	v_or_b32_e32 v12, 48, v8
	v_cmp_gt_i32_e32 vcc, s21, v12
	s_and_saveexec_b64 s[10:11], vcc
	s_cbranch_execz .LBB0_138
	v_ashrrev_i32_e32 v13, 31, v12
	v_lshlrev_b64 v[12:13], 12, v[12:13]
	v_lshl_add_u64 v[12:13], v[10:11], 0, v[12:13]
	v_lshl_add_u64 v[54:55], v[8:9], 2, s[4:5]
	global_load_dword v52, v[12:13], off nt
	global_load_dword v224, v[54:55], off offset:192
.LBB0_138:
	s_or_b64 exec, exec, s[10:11]
	v_or_b32_e32 v12, 50, v8
	v_cmp_gt_i32_e32 vcc, s21, v12
	v_mov_b32_e32 v54, 0
	v_mov_b32_e32 v55, 0
	s_and_saveexec_b64 s[10:11], vcc
	s_cbranch_execz .LBB0_140
	v_ashrrev_i32_e32 v13, 31, v12
	v_lshlrev_b64 v[12:13], 12, v[12:13]
	v_lshl_add_u64 v[12:13], v[10:11], 0, v[12:13]
	v_lshl_add_u64 v[56:57], v[8:9], 2, s[4:5]
	global_load_dword v55, v[12:13], off nt
	global_load_dword v225, v[56:57], off offset:200
.LBB0_140:
	s_or_b64 exec, exec, s[10:11]
	v_or_b32_e32 v12, 52, v8
	v_cmp_gt_i32_e32 vcc, s21, v12
	s_and_saveexec_b64 s[10:11], vcc
	s_cbranch_execz .LBB0_142
	v_ashrrev_i32_e32 v13, 31, v12
	v_lshlrev_b64 v[12:13], 12, v[12:13]
	v_lshl_add_u64 v[12:13], v[10:11], 0, v[12:13]
	v_lshl_add_u64 v[56:57], v[8:9], 2, s[4:5]
	global_load_dword v54, v[12:13], off nt
	global_load_dword v226, v[56:57], off offset:208
.LBB0_142:
	s_or_b64 exec, exec, s[10:11]
	v_or_b32_e32 v12, 54, v8
	v_cmp_gt_i32_e32 vcc, s21, v12
	v_mov_b32_e32 v56, 0
	v_mov_b32_e32 v57, 0
	s_and_saveexec_b64 s[10:11], vcc
	s_cbranch_execz .LBB0_144
	v_ashrrev_i32_e32 v13, 31, v12
	v_lshlrev_b64 v[12:13], 12, v[12:13]
	v_lshl_add_u64 v[12:13], v[10:11], 0, v[12:13]
	v_lshl_add_u64 v[58:59], v[8:9], 2, s[4:5]
	global_load_dword v57, v[12:13], off nt
	global_load_dword v227, v[58:59], off offset:216
.LBB0_144:
	s_or_b64 exec, exec, s[10:11]
	v_or_b32_e32 v12, 56, v8
	v_cmp_gt_i32_e32 vcc, s21, v12
	s_and_saveexec_b64 s[10:11], vcc
	s_cbranch_execz .LBB0_146
	v_ashrrev_i32_e32 v13, 31, v12
	v_lshlrev_b64 v[12:13], 12, v[12:13]
	v_lshl_add_u64 v[12:13], v[10:11], 0, v[12:13]
	v_lshl_add_u64 v[58:59], v[8:9], 2, s[4:5]
	global_load_dword v56, v[12:13], off nt
	global_load_dword v228, v[58:59], off offset:224
.LBB0_146:
	s_or_b64 exec, exec, s[10:11]
	v_or_b32_e32 v12, 58, v8
	v_cmp_gt_i32_e32 vcc, s21, v12
	v_mov_b32_e32 v58, 0
	v_mov_b32_e32 v59, 0
	s_and_saveexec_b64 s[10:11], vcc
	s_cbranch_execz .LBB0_148
	v_ashrrev_i32_e32 v13, 31, v12
	v_lshlrev_b64 v[12:13], 12, v[12:13]
	v_lshl_add_u64 v[12:13], v[10:11], 0, v[12:13]
	v_lshl_add_u64 v[60:61], v[8:9], 2, s[4:5]
	global_load_dword v59, v[12:13], off nt
	global_load_dword v229, v[60:61], off offset:232
.LBB0_148:
	s_or_b64 exec, exec, s[10:11]
	v_or_b32_e32 v12, 60, v8
	v_cmp_gt_i32_e32 vcc, s21, v12
	s_and_saveexec_b64 s[10:11], vcc
	s_cbranch_execz .LBB0_150
	v_ashrrev_i32_e32 v13, 31, v12
	v_lshlrev_b64 v[12:13], 12, v[12:13]
	v_lshl_add_u64 v[12:13], v[10:11], 0, v[12:13]
	v_lshl_add_u64 v[60:61], v[8:9], 2, s[4:5]
	global_load_dword v58, v[12:13], off nt
	global_load_dword v230, v[60:61], off offset:240
.LBB0_150:
	s_or_b64 exec, exec, s[10:11]
	s_waitcnt vmcnt(0)
	v_mul_f32_e32 v2, v2, v200
	v_mul_f32_e32 v31, v31, v201
	v_mul_f32_e32 v30, v30, v202
	v_mul_f32_e32 v33, v33, v203
	v_mul_f32_e32 v32, v32, v204
	v_mul_f32_e32 v35, v35, v205
	v_mul_f32_e32 v34, v34, v206
	v_mul_f32_e32 v37, v37, v207
	v_mul_f32_e32 v36, v36, v208
	v_mul_f32_e32 v39, v39, v209
	v_mul_f32_e32 v38, v38, v210
	v_mul_f32_e32 v41, v41, v211
	v_mul_f32_e32 v40, v40, v212
	v_mul_f32_e32 v43, v43, v213
	v_mul_f32_e32 v42, v42, v214
	v_mul_f32_e32 v45, v45, v215
	v_mul_f32_e32 v44, v44, v216
	v_mul_f32_e32 v47, v47, v217
	v_mul_f32_e32 v46, v46, v218
	v_mul_f32_e32 v49, v49, v219
	v_mul_f32_e32 v48, v48, v220
	v_mul_f32_e32 v51, v51, v221
	v_mul_f32_e32 v50, v50, v222
	v_mul_f32_e32 v53, v53, v223
	v_mul_f32_e32 v52, v52, v224
	v_mul_f32_e32 v55, v55, v225
	v_mul_f32_e32 v54, v54, v226
	v_mul_f32_e32 v57, v57, v227
	v_mul_f32_e32 v56, v56, v228
	v_mul_f32_e32 v59, v59, v229
	v_mul_f32_e32 v58, v58, v230
	v_or_b32_e32 v12, 62, v8
	v_cmp_gt_i32_e32 vcc, s21, v12
	v_mov_b32_e32 v13, 0
	s_and_saveexec_b64 s[10:11], vcc
	s_cbranch_execz .LBB0_87
	v_ashrrev_i32_e32 v13, 31, v12
	v_lshlrev_b64 v[12:13], 12, v[12:13]
	v_lshl_add_u64 v[10:11], v[10:11], 0, v[12:13]
	v_lshl_add_u64 v[8:9], v[8:9], 2, s[4:5]
	global_load_dword v12, v[10:11], off nt
	global_load_dword v13, v[8:9], off offset:248
	s_waitcnt vmcnt(0)
	v_mul_f32_e32 v13, v12, v13
	s_branch .LBB0_87

; #define LAS __attribute__((address_space(3)))
; template <class F> DI void tr_items(const F& f, int Kdst, int Nrows, bf16_t* WT, LAS float* scr, int gw, int NGW, int lane, int& cum) {
;     const int nblk = Nrows / 32, nitems = (Kdst / 64) * nblk;
;     int first = (gw - cum) % NGW; if (first < 0) first += NGW; cum = (cum + nitems) % NGW;
;     for (int item = first; item < nitems; item += NGW) {
;         const int kb = item / nblk, nb = item % nblk, k0 = 64 * kb, n0 = 32 * nb;
;         float tv[32];
; #pragma unroll
;         for (int i = 0; i < 32; ++i) tv[i] = f(k0 + 2 * i + (lane >> 5), n0 + (lane & 31));
; DI void phase_prologue(int wv, const ArgP a, LAS unsigned char* lds, int parts) {
;     ...
;     { FWKV f{a.in(14), a.in(13), 64}; tr_items(f, 256, 512, (bf16_t*)(ws + O_WVT), scr, gw, NGW, lane, cum); }
.LBB0_155:
	v_mov_b32_e32 v200, 0
	v_mov_b32_e32 v201, 0
	v_mov_b32_e32 v202, 0
	v_mov_b32_e32 v203, 0
	v_mov_b32_e32 v204, 0
	v_mov_b32_e32 v205, 0
	v_mov_b32_e32 v206, 0
	v_mov_b32_e32 v207, 0
	v_mov_b32_e32 v208, 0
	v_mov_b32_e32 v209, 0
	v_mov_b32_e32 v210, 0
	v_mov_b32_e32 v211, 0
	v_mov_b32_e32 v212, 0
	v_mov_b32_e32 v213, 0
	v_mov_b32_e32 v214, 0
	v_mov_b32_e32 v215, 0
	v_mov_b32_e32 v216, 0
	v_mov_b32_e32 v217, 0
	v_mov_b32_e32 v218, 0
	v_mov_b32_e32 v219, 0
	v_mov_b32_e32 v220, 0
	v_mov_b32_e32 v221, 0
	v_mov_b32_e32 v222, 0
	v_mov_b32_e32 v223, 0
	v_mov_b32_e32 v224, 0
	v_mov_b32_e32 v225, 0
	v_mov_b32_e32 v226, 0
	v_mov_b32_e32 v227, 0
	v_mov_b32_e32 v228, 0
	v_mov_b32_e32 v229, 0
	v_mov_b32_e32 v230, 0
	v_ashrrev_i32_e32 v2, 31, v22
	v_lshrrev_b32_e32 v2, 28, v2
	v_add_u32_e32 v2, v22, v2
	v_ashrrev_i32_e32 v2, 4, v2
	v_lshlrev_b32_e32 v6, 6, v2
	v_lshlrev_b32_e32 v7, 9, v2
	v_lshlrev_b32_e32 v2, 10, v2
	v_sub_u32_e32 v2, v28, v2
	v_sub_u32_e32 v9, v27, v7
	v_and_b32_e32 v10, 0xffffff80, v2
	v_ashrrev_i32_e32 v11, 31, v10
	v_and_or_b32 v2, v9, 32, v24
	v_or_b32_e32 v8, v6, v23
	s_waitcnt lgkmcnt(0)
	v_lshl_add_u64 v[10:11], v[10:11], 2, s[6:7]
	v_lshlrev_b32_e32 v2, 2, v2
	v_lshl_add_u64 v[10:11], v[10:11], 0, v[2:3]
	v_cmp_gt_i32_e32 vcc, s21, v8
	v_ashrrev_i32_e32 v9, 31, v8
	v_mov_b32_e32 v2, 0
	s_and_saveexec_b64 s[10:11], vcc
	s_cbranch_execz .LBB0_157
	v_lshlrev_b64 v[12:13], 12, v[8:9]
	v_lshl_add_u64 v[12:13], v[10:11], 0, v[12:13]
	v_lshl_add_u64 v[30:31], v[8:9], 2, s[4:5]
	global_load_dword v2, v[12:13], off offset:256 nt
	global_load_dword v200, v[30:31], off
.LBB0_157:
	s_or_b64 exec, exec, s[10:11]
	v_or_b32_e32 v12, 2, v8
	v_cmp_gt_i32_e32 vcc, s21, v12
	v_mov_b32_e32 v30, 0
	v_mov_b32_e32 v31, 0
	s_and_saveexec_b64 s[10:11], vcc
	s_cbranch_execz .LBB0_159
	v_ashrrev_i32_e32 v13, 31, v12
	v_lshlrev_b64 v[12:13], 12, v[12:13]
	v_lshl_add_u64 v[12:13], v[10:11], 0, v[12:13]
	v_lshl_add_u64 v[32:33], v[8:9], 2, s[4:5]
	global_load_dword v31, v[12:13], off offset:256 nt
	global_load_dword v201, v[32:33], off offset:8
.LBB0_159:
	s_or_b64 exec, exec, s[10:11]
	v_or_b32_e32 v12, 4, v8
	v_cmp_gt_i32_e32 vcc, s21, v12
	s_and_saveexec_b64 s[10:11], vcc
	s_cbranch_execz .LBB0_161
	v_ashrrev_i32_e32 v13, 31, v12
	v_lshlrev_b64 v[12:13], 12, v[12:13]
	v_lshl_add_u64 v[12:13], v[10:11], 0, v[12:13]
	v_lshl_add_u64 v[32:33], v[8:9], 2, s[4:5]
	global_load_dword v30, v[12:13], off offset:256 nt
	global_load_dword v202, v[32:33], off offset:16
.LBB0_161:
	s_or_b64 exec, exec, s[10:11]
	v_or_b32_e32 v12, 6, v8
	v_cmp_gt_i32_e32 vcc, s21, v12
	v_mov_b32_e32 v32, 0
	v_mov_b32_e32 v33, 0
	s_and_saveexec_b64 s[10:11], vcc
	s_cbranch_execz .LBB0_163
	v_ashrrev_i32_e32 v13, 31, v12
	v_lshlrev_b64 v[12:13], 12, v[12:13]
	v_lshl_add_u64 v[12:13], v[10:11], 0, v[12:13]
	v_lshl_add_u64 v[34:35], v[8:9], 2, s[4:5]
	global_load_dword v33, v[12:13], off offset:256 nt
	global_load_dword v203, v[34:35], off offset:24
.LBB0_163:
	s_or_b64 exec, exec, s[10:11]
	v_or_b32_e32 v12, 8, v8
	v_cmp_gt_i32_e32 vcc, s21, v12
	s_and_saveexec_b64 s[10:11], vcc
	s_cbranch_execz .LBB0_165
	v_ashrrev_i32_e32 v13, 31, v12
	v_lshlrev_b64 v[12:13], 12, v[12:13]
	v_lshl_add_u64 v[12:13], v[10:11], 0, v[12:13]
	v_lshl_add_u64 v[34:35], v[8:9], 2, s[4:5]
	global_load_dword v32, v[12:13], off offset:256 nt
	global_load_dword v204, v[34:35], off offset:32
.LBB0_165:
	s_or_b64 exec, exec, s[10:11]
	v_or_b32_e32 v12, 10, v8
	v_cmp_gt_i32_e32 vcc, s21, v12
	v_mov_b32_e32 v34, 0
	v_mov_b32_e32 v35, 0
	s_and_saveexec_b64 s[10:11], vcc
	s_cbranch_execz .LBB0_167
	v_ashrrev_i32_e32 v13, 31, v12
	v_lshlrev_b64 v[12:13], 12, v[12:13]
	v_lshl_add_u64 v[12:13], v[10:11], 0, v[12:13]
	v_lshl_add_u64 v[36:37], v[8:9], 2, s[4:5]
	global_load_dword v35, v[12:13], off offset:256 nt
	global_load_dword v205, v[36:37], off offset:40
.LBB0_167:
	s_or_b64 exec, exec, s[10:11]
	v_or_b32_e32 v12, 12, v8
	v_cmp_gt_i32_e32 vcc, s21, v12
	s_and_saveexec_b64 s[10:11], vcc
	s_cbranch_execz .LBB0_169
	v_ashrrev_i32_e32 v13, 31, v12
	v_lshlrev_b64 v[12:13], 12, v[12:13]
	v_lshl_add_u64 v[12:13], v[10:11], 0, v[12:13]
	v_lshl_add_u64 v[36:37], v[8:9], 2, s[4:5]
	global_load_dword v34, v[12:13], off offset:256 nt
	global_load_dword v206, v[36:37], off offset:48
.LBB0_169:
	s_or_b64 exec, exec, s[10:11]
	v_or_b32_e32 v12, 14, v8
	v_cmp_gt_i32_e32 vcc, s21, v12
	v_mov_b32_e32 v36, 0
	v_mov_b32_e32 v37, 0
	s_and_saveexec_b64 s[10:11], vcc
	s_cbranch_execz .LBB0_171
	v_ashrrev_i32_e32 v13, 31, v12
	v_lshlrev_b64 v[12:13], 12, v[12:13]
	v_lshl_add_u64 v[12:13], v[10:11], 0, v[12:13]
	v_lshl_add_u64 v[38:39], v[8:9], 2, s[4:5]
	global_load_dword v37, v[12:13], off offset:256 nt
	global_load_dword v207, v[38:39], off offset:56
.LBB0_171:
	s_or_b64 exec, exec, s[10:11]
	v_or_b32_e32 v12, 16, v8
	v_cmp_gt_i32_e32 vcc, s21, v12
	s_and_saveexec_b64 s[10:11], vcc
	s_cbranch_execz .LBB0_173
	v_ashrrev_i32_e32 v13, 31, v12
	v_lshlrev_b64 v[12:13], 12, v[12:13]
	v_lshl_add_u64 v[12:13], v[10:11], 0, v[12:13]
	v_lshl_add_u64 v[38:39], v[8:9], 2, s[4:5]
	global_load_dword v36, v[12:13], off offset:256 nt
	global_load_dword v208, v[38:39], off offset:64
.LBB0_173:
	s_or_b64 exec, exec, s[10:11]
	v_or_b32_e32 v12, 18, v8
	v_cmp_gt_i32_e32 vcc, s21, v12
	v_mov_b32_e32 v38, 0
	v_mov_b32_e32 v39, 0
	s_and_saveexec_b64 s[10:11], vcc
	s_cbranch_execz .LBB0_175
	v_ashrrev_i32_e32 v13, 31, v12
	v_lshlrev_b64 v[12:13], 12, v[12:13]
	v_lshl_add_u64 v[12:13], v[10:11], 0, v[12:13]
	v_lshl_add_u64 v[40:41], v[8:9], 2, s[4:5]
	global_load_dword v39, v[12:13], off offset:256 nt
	global_load_dword v209, v[40:41], off offset:72
; #define LAS __attribute__((address_space(3)))
; template <class F> DI void tr_items(const F& f, int Kdst, int Nrows, bf16_t* WT, LAS float* scr, int gw, int NGW, int lane, int& cum) {
;     const int nblk = Nrows / 32, nitems = (Kdst / 64) * nblk;
;     int first = (gw - cum) % NGW; if (first < 0) first += NGW; cum = (cum + nitems) % NGW;
;     for (int item = first; item < nitems; item += NGW) {
;         const int kb = item / nblk, nb = item % nblk, k0 = 64 * kb, n0 = 32 * nb;
;         float tv[32];
; #pragma unroll
;         for (int i = 0; i < 32; ++i) tv[i] = f(k0 + 2 * i + (lane >> 5), n0 + (lane & 31));
; DI void phase_prologue(int wv, const ArgP a, LAS unsigned char* lds, int parts) {
;     ...
;     { FWKV f{a.in(14), a.in(13), 64}; tr_items(f, 256, 512, (bf16_t*)(ws + O_WVT), scr, gw, NGW, lane, cum); }
.LBB0_175:
	s_or_b64 exec, exec, s[10:11]
	v_or_b32_e32 v12, 20, v8
	v_cmp_gt_i32_e32 vcc, s21, v12
	s_and_saveexec_b64 s[10:11], vcc
	s_cbranch_execz .LBB0_177
	v_ashrrev_i32_e32 v13, 31, v12
	v_lshlrev_b64 v[12:13], 12, v[12:13]
	v_lshl_add_u64 v[12:13], v[10:11], 0, v[12:13]
	v_lshl_add_u64 v[40:41], v[8:9], 2, s[4:5]
	global_load_dword v38, v[12:13], off offset:256 nt
	global_load_dword v210, v[40:41], off offset:80
.LBB0_177:
	s_or_b64 exec, exec, s[10:11]
	v_or_b32_e32 v12, 22, v8
	v_cmp_gt_i32_e32 vcc, s21, v12
	v_mov_b32_e32 v40, 0
	v_mov_b32_e32 v41, 0
	s_and_saveexec_b64 s[10:11], vcc
	s_cbranch_execz .LBB0_179
	v_ashrrev_i32_e32 v13, 31, v12
	v_lshlrev_b64 v[12:13], 12, v[12:13]
	v_lshl_add_u64 v[12:13], v[10:11], 0, v[12:13]
	v_lshl_add_u64 v[42:43], v[8:9], 2, s[4:5]
	global_load_dword v41, v[12:13], off offset:256 nt
	global_load_dword v211, v[42:43], off offset:88
.LBB0_179:
	s_or_b64 exec, exec, s[10:11]
	v_or_b32_e32 v12, 24, v8
	v_cmp_gt_i32_e32 vcc, s21, v12
	s_and_saveexec_b64 s[10:11], vcc
	s_cbranch_execz .LBB0_181
	v_ashrrev_i32_e32 v13, 31, v12
	v_lshlrev_b64 v[12:13], 12, v[12:13]
	v_lshl_add_u64 v[12:13], v[10:11], 0, v[12:13]
	v_lshl_add_u64 v[42:43], v[8:9], 2, s[4:5]
	global_load_dword v40, v[12:13], off offset:256 nt
	global_load_dword v212, v[42:43], off offset:96
.LBB0_181:
	s_or_b64 exec, exec, s[10:11]
	v_or_b32_e32 v12, 26, v8
	v_cmp_gt_i32_e32 vcc, s21, v12
	v_mov_b32_e32 v42, 0
	v_mov_b32_e32 v43, 0
	s_and_saveexec_b64 s[10:11], vcc
	s_cbranch_execz .LBB0_183
	v_ashrrev_i32_e32 v13, 31, v12
	v_lshlrev_b64 v[12:13], 12, v[12:13]
	v_lshl_add_u64 v[12:13], v[10:11], 0, v[12:13]
	v_lshl_add_u64 v[44:45], v[8:9], 2, s[4:5]
	global_load_dword v43, v[12:13], off offset:256 nt
	global_load_dword v213, v[44:45], off offset:104
.LBB0_183:
	s_or_b64 exec, exec, s[10:11]
	v_or_b32_e32 v12, 28, v8
	v_cmp_gt_i32_e32 vcc, s21, v12
	s_and_saveexec_b64 s[10:11], vcc
	s_cbranch_execz .LBB0_185
	v_ashrrev_i32_e32 v13, 31, v12
	v_lshlrev_b64 v[12:13], 12, v[12:13]
	v_lshl_add_u64 v[12:13], v[10:11], 0, v[12:13]
	v_lshl_add_u64 v[44:45], v[8:9], 2, s[4:5]
	global_load_dword v42, v[12:13], off offset:256 nt
	global_load_dword v214, v[44:45], off offset:112
.LBB0_185:
	s_or_b64 exec, exec, s[10:11]
	v_or_b32_e32 v12, 30, v8
	v_cmp_gt_i32_e32 vcc, s21, v12
	v_mov_b32_e32 v44, 0
	v_mov_b32_e32 v45, 0
	s_and_saveexec_b64 s[10:11], vcc
	s_cbranch_execz .LBB0_187
	v_ashrrev_i32_e32 v13, 31, v12
	v_lshlrev_b64 v[12:13], 12, v[12:13]
	v_lshl_add_u64 v[12:13], v[10:11], 0, v[12:13]
	v_lshl_add_u64 v[46:47], v[8:9], 2, s[4:5]
	global_load_dword v45, v[12:13], off offset:256 nt
	global_load_dword v215, v[46:47], off offset:120
.LBB0_187:
	s_or_b64 exec, exec, s[10:11]
	v_or_b32_e32 v12, 32, v8
	v_cmp_gt_i32_e32 vcc, s21, v12
	s_and_saveexec_b64 s[10:11], vcc
	s_cbranch_execz .LBB0_189
	v_ashrrev_i32_e32 v13, 31, v12
	v_lshlrev_b64 v[12:13], 12, v[12:13]
	v_lshl_add_u64 v[12:13], v[10:11], 0, v[12:13]
	v_lshl_add_u64 v[46:47], v[8:9], 2, s[4:5]
	global_load_dword v44, v[12:13], off offset:256 nt
	global_load_dword v216, v[46:47], off offset:128
.LBB0_189:
	s_or_b64 exec, exec, s[10:11]
	v_or_b32_e32 v12, 34, v8
	v_cmp_gt_i32_e32 vcc, s21, v12
	v_mov_b32_e32 v46, 0
	v_mov_b32_e32 v47, 0
	s_and_saveexec_b64 s[10:11], vcc
	s_cbranch_execz .LBB0_191
	v_ashrrev_i32_e32 v13, 31, v12
	v_lshlrev_b64 v[12:13], 12, v[12:13]
	v_lshl_add_u64 v[12:13], v[10:11], 0, v[12:13]
	v_lshl_add_u64 v[48:49], v[8:9], 2, s[4:5]
	global_load_dword v47, v[12:13], off offset:256 nt
	global_load_dword v217, v[48:49], off offset:136
.LBB0_191:
	s_or_b64 exec, exec, s[10:11]
	v_or_b32_e32 v12, 36, v8
	v_cmp_gt_i32_e32 vcc, s21, v12
	s_and_saveexec_b64 s[10:11], vcc
	s_cbranch_execz .LBB0_193
	v_ashrrev_i32_e32 v13, 31, v12
	v_lshlrev_b64 v[12:13], 12, v[12:13]
	v_lshl_add_u64 v[12:13], v[10:11], 0, v[12:13]
	v_lshl_add_u64 v[48:49], v[8:9], 2, s[4:5]
	global_load_dword v46, v[12:13], off offset:256 nt
	global_load_dword v218, v[48:49], off offset:144
.LBB0_193:
	s_or_b64 exec, exec, s[10:11]
	v_or_b32_e32 v12, 38, v8
	v_cmp_gt_i32_e32 vcc, s21, v12
	v_mov_b32_e32 v48, 0
	v_mov_b32_e32 v49, 0
	s_and_saveexec_b64 s[10:11], vcc
	s_cbranch_execz .LBB0_195
	v_ashrrev_i32_e32 v13, 31, v12
	v_lshlrev_b64 v[12:13], 12, v[12:13]
	v_lshl_add_u64 v[12:13], v[10:11], 0, v[12:13]
	v_lshl_add_u64 v[50:51], v[8:9], 2, s[4:5]
	global_load_dword v49, v[12:13], off offset:256 nt
	global_load_dword v219, v[50:51], off offset:152
.LBB0_195:
	s_or_b64 exec, exec, s[10:11]
	v_or_b32_e32 v12, 40, v8
	v_cmp_gt_i32_e32 vcc, s21, v12
	s_and_saveexec_b64 s[10:11], vcc
	s_cbranch_execz .LBB0_197
	v_ashrrev_i32_e32 v13, 31, v12
	v_lshlrev_b64 v[12:13], 12, v[12:13]
	v_lshl_add_u64 v[12:13], v[10:11], 0, v[12:13]
	v_lshl_add_u64 v[50:51], v[8:9], 2, s[4:5]
	global_load_dword v48, v[12:13], off offset:256 nt
	global_load_dword v220, v[50:51], off offset:160
.LBB0_197:
	s_or_b64 exec, exec, s[10:11]
	v_or_b32_e32 v12, 42, v8
	v_cmp_gt_i32_e32 vcc, s21, v12
	v_mov_b32_e32 v50, 0
	v_mov_b32_e32 v51, 0
	s_and_saveexec_b64 s[10:11], vcc
	s_cbranch_execz .LBB0_199
	v_ashrrev_i32_e32 v13, 31, v12
	v_lshlrev_b64 v[12:13], 12, v[12:13]
	v_lshl_add_u64 v[12:13], v[10:11], 0, v[12:13]
	v_lshl_add_u64 v[52:53], v[8:9], 2, s[4:5]
	global_load_dword v51, v[12:13], off offset:256 nt
	global_load_dword v221, v[52:53], off offset:168
; #define LAS __attribute__((address_space(3)))
; template <class F> DI void tr_items(const F& f, int Kdst, int Nrows, bf16_t* WT, LAS float* scr, int gw, int NGW, int lane, int& cum) {
;     const int nblk = Nrows / 32, nitems = (Kdst / 64) * nblk;
;     int first = (gw - cum) % NGW; if (first < 0) first += NGW; cum = (cum + nitems) % NGW;
;     for (int item = first; item < nitems; item += NGW) {
;         const int kb = item / nblk, nb = item % nblk, k0 = 64 * kb, n0 = 32 * nb;
;         float tv[32];
; #pragma unroll
;         for (int i = 0; i < 32; ++i) tv[i] = f(k0 + 2 * i + (lane >> 5), n0 + (lane & 31));
; DI void phase_prologue(int wv, const ArgP a, LAS unsigned char* lds, int parts) {
;     ...
;     { FWKV f{a.in(14), a.in(13), 64}; tr_items(f, 256, 512, (bf16_t*)(ws + O_WVT), scr, gw, NGW, lane, cum); }
.LBB0_199:
	s_or_b64 exec, exec, s[10:11]
	v_or_b32_e32 v12, 44, v8
	v_cmp_gt_i32_e32 vcc, s21, v12
	s_and_saveexec_b64 s[10:11], vcc
	s_cbranch_execz .LBB0_201
	v_ashrrev_i32_e32 v13, 31, v12
	v_lshlrev_b64 v[12:13], 12, v[12:13]
	v_lshl_add_u64 v[12:13], v[10:11], 0, v[12:13]
	v_lshl_add_u64 v[52:53], v[8:9], 2, s[4:5]
	global_load_dword v50, v[12:13], off offset:256 nt
	global_load_dword v222, v[52:53], off offset:176
.LBB0_201:
	s_or_b64 exec, exec, s[10:11]
	v_or_b32_e32 v12, 46, v8
	v_cmp_gt_i32_e32 vcc, s21, v12
	v_mov_b32_e32 v52, 0
	v_mov_b32_e32 v53, 0
	s_and_saveexec_b64 s[10:11], vcc
	s_cbranch_execz .LBB0_203
	v_ashrrev_i32_e32 v13, 31, v12
	v_lshlrev_b64 v[12:13], 12, v[12:13]
	v_lshl_add_u64 v[12:13], v[10:11], 0, v[12:13]
	v_lshl_add_u64 v[54:55], v[8:9], 2, s[4:5]
	global_load_dword v53, v[12:13], off offset:256 nt
	global_load_dword v223, v[54:55], off offset:184
.LBB0_203:
	s_or_b64 exec, exec, s[10:11]
	v_or_b32_e32 v12, 48, v8
	v_cmp_gt_i32_e32 vcc, s21, v12
	s_and_saveexec_b64 s[10:11], vcc
	s_cbranch_execz .LBB0_205
	v_ashrrev_i32_e32 v13, 31, v12
	v_lshlrev_b64 v[12:13], 12, v[12:13]
	v_lshl_add_u64 v[12:13], v[10:11], 0, v[12:13]
	v_lshl_add_u64 v[54:55], v[8:9], 2, s[4:5]
	global_load_dword v52, v[12:13], off offset:256 nt
	global_load_dword v224, v[54:55], off offset:192
.LBB0_205:
	s_or_b64 exec, exec, s[10:11]
	v_or_b32_e32 v12, 50, v8
	v_cmp_gt_i32_e32 vcc, s21, v12
	v_mov_b32_e32 v54, 0
	v_mov_b32_e32 v55, 0
	s_and_saveexec_b64 s[10:11], vcc
	s_cbranch_execz .LBB0_207
	v_ashrrev_i32_e32 v13, 31, v12
	v_lshlrev_b64 v[12:13], 12, v[12:13]
	v_lshl_add_u64 v[12:13], v[10:11], 0, v[12:13]
	v_lshl_add_u64 v[56:57], v[8:9], 2, s[4:5]
	global_load_dword v55, v[12:13], off offset:256 nt
	global_load_dword v225, v[56:57], off offset:200
.LBB0_207:
	s_or_b64 exec, exec, s[10:11]
	v_or_b32_e32 v12, 52, v8
	v_cmp_gt_i32_e32 vcc, s21, v12
	s_and_saveexec_b64 s[10:11], vcc
	s_cbranch_execz .LBB0_209
	v_ashrrev_i32_e32 v13, 31, v12
	v_lshlrev_b64 v[12:13], 12, v[12:13]
	v_lshl_add_u64 v[12:13], v[10:11], 0, v[12:13]
	v_lshl_add_u64 v[56:57], v[8:9], 2, s[4:5]
	global_load_dword v54, v[12:13], off offset:256 nt
	global_load_dword v226, v[56:57], off offset:208
.LBB0_209:
	s_or_b64 exec, exec, s[10:11]
	v_or_b32_e32 v12, 54, v8
	v_cmp_gt_i32_e32 vcc, s21, v12
	v_mov_b32_e32 v56, 0
	v_mov_b32_e32 v57, 0
	s_and_saveexec_b64 s[10:11], vcc
	s_cbranch_execz .LBB0_211
	v_ashrrev_i32_e32 v13, 31, v12
	v_lshlrev_b64 v[12:13], 12, v[12:13]
	v_lshl_add_u64 v[12:13], v[10:11], 0, v[12:13]
	v_lshl_add_u64 v[58:59], v[8:9], 2, s[4:5]
	global_load_dword v57, v[12:13], off offset:256 nt
	global_load_dword v227, v[58:59], off offset:216
.LBB0_211:
	s_or_b64 exec, exec, s[10:11]
	v_or_b32_e32 v12, 56, v8
	v_cmp_gt_i32_e32 vcc, s21, v12
	s_and_saveexec_b64 s[10:11], vcc
	s_cbranch_execz .LBB0_213
	v_ashrrev_i32_e32 v13, 31, v12
	v_lshlrev_b64 v[12:13], 12, v[12:13]
	v_lshl_add_u64 v[12:13], v[10:11], 0, v[12:13]
	v_lshl_add_u64 v[58:59], v[8:9], 2, s[4:5]
	global_load_dword v56, v[12:13], off offset:256 nt
	global_load_dword v228, v[58:59], off offset:224
.LBB0_213:
	s_or_b64 exec, exec, s[10:11]
	v_or_b32_e32 v12, 58, v8
	v_cmp_gt_i32_e32 vcc, s21, v12
	v_mov_b32_e32 v58, 0
	v_mov_b32_e32 v59, 0
	s_and_saveexec_b64 s[10:11], vcc
	s_cbranch_execz .LBB0_215
	v_ashrrev_i32_e32 v13, 31, v12
	v_lshlrev_b64 v[12:13], 12, v[12:13]
	v_lshl_add_u64 v[12:13], v[10:11], 0, v[12:13]
	v_lshl_add_u64 v[60:61], v[8:9], 2, s[4:5]
	global_load_dword v59, v[12:13], off offset:256 nt
	global_load_dword v229, v[60:61], off offset:232
.LBB0_215:
	s_or_b64 exec, exec, s[10:11]
	v_or_b32_e32 v12, 60, v8
	v_cmp_gt_i32_e32 vcc, s21, v12
	s_and_saveexec_b64 s[10:11], vcc
	s_cbranch_execz .LBB0_217
	v_ashrrev_i32_e32 v13, 31, v12
	v_lshlrev_b64 v[12:13], 12, v[12:13]
	v_lshl_add_u64 v[12:13], v[10:11], 0, v[12:13]
	v_lshl_add_u64 v[60:61], v[8:9], 2, s[4:5]
	global_load_dword v58, v[12:13], off offset:256 nt
	global_load_dword v230, v[60:61], off offset:240
.LBB0_217:
	s_or_b64 exec, exec, s[10:11]
	s_waitcnt vmcnt(0)
	v_mul_f32_e32 v2, v2, v200
	v_mul_f32_e32 v31, v31, v201
	v_mul_f32_e32 v30, v30, v202
	v_mul_f32_e32 v33, v33, v203
	v_mul_f32_e32 v32, v32, v204
	v_mul_f32_e32 v35, v35, v205
	v_mul_f32_e32 v34, v34, v206
	v_mul_f32_e32 v37, v37, v207
	v_mul_f32_e32 v36, v36, v208
	v_mul_f32_e32 v39, v39, v209
	v_mul_f32_e32 v38, v38, v210
	v_mul_f32_e32 v41, v41, v211
	v_mul_f32_e32 v40, v40, v212
	v_mul_f32_e32 v43, v43, v213
	v_mul_f32_e32 v42, v42, v214
	v_mul_f32_e32 v45, v45, v215
	v_mul_f32_e32 v44, v44, v216
	v_mul_f32_e32 v47, v47, v217
	v_mul_f32_e32 v46, v46, v218
	v_mul_f32_e32 v49, v49, v219
	v_mul_f32_e32 v48, v48, v220
	v_mul_f32_e32 v51, v51, v221
	v_mul_f32_e32 v50, v50, v222
	v_mul_f32_e32 v53, v53, v223
	v_mul_f32_e32 v52, v52, v224
	v_mul_f32_e32 v55, v55, v225
	v_mul_f32_e32 v54, v54, v226
	v_mul_f32_e32 v57, v57, v227
	v_mul_f32_e32 v56, v56, v228
	v_mul_f32_e32 v59, v59, v229
	v_mul_f32_e32 v58, v58, v230
	v_or_b32_e32 v12, 62, v8
	v_cmp_gt_i32_e32 vcc, s21, v12
	v_mov_b32_e32 v13, 0
	s_and_saveexec_b64 s[10:11], vcc
	s_cbranch_execz .LBB0_154
	v_ashrrev_i32_e32 v13, 31, v12
	v_lshlrev_b64 v[12:13], 12, v[12:13]
	v_lshl_add_u64 v[10:11], v[10:11], 0, v[12:13]
	v_lshl_add_u64 v[8:9], v[8:9], 2, s[4:5]
	global_load_dword v12, v[10:11], off offset:256 nt
	global_load_dword v13, v[8:9], off offset:248
	s_waitcnt vmcnt(0)
	v_mul_f32_e32 v13, v12, v13
	s_branch .LBB0_154

; DI unsigned pk2(float lo, float hi) { f32x2 v = {lo, hi}; bf16x2_t b = __builtin_convertvector(v, bf16x2_t); return __builtin_bit_cast(unsigned, b); }
; DI u64 ss_to_fix(float ss) { return (u64)(ss * 1048576.f); }
; DI void phase_prologue(int wv, const ArgP a, LAS unsigned char* lds, int parts) {
;     ...
;     const float* x = a.in(0); bf16_t* XB = (bf16_t*)(ws + O_XB) + 2 * 1024; u64* rowss = (u64*)(ws + O_ROWSS);
; #pragma unroll 4
;     for (int t = gw; t < S; t += NGW) {
;         float ss = 0.f;
; #pragma unroll
;         for (int j = 0; j < 4; ++j) { const f32x4 v = __builtin_nontemporal_load((const f32x4*)(x + (size_t)t * 1024 + j * 256 + lane * 4));
;             ss += v[0] * v[0] + v[1] * v[1] + v[2] * v[2] + v[3] * v[3];
;             u32x2 w; w.x = pk2(v[0], v[1]); w.y = pk2(v[2], v[3]); *(u32x2*)(XB + (size_t)t * 1024 + j * 256 + lane * 4) = w; }
;         ss = wave_sum(ss);
;         if (lane == 0) rowss[t] = ss_to_fix(ss);
;         if (lane >= 1 && lane < 5) rowss[(size_t)lane * S + t] = 0ull;
.LBB0_309:
	global_load_dwordx4 v[22:25], v[10:11], off offset:-2048 nt
	global_load_dwordx4 v[26:29], v[10:11], off offset:-1024 nt
	global_load_dwordx4 v[30:33], v[10:11], off nt
	global_load_dwordx4 v[34:37], v[10:11], off offset:1024 nt
.Lxc_bodyA:
	v_add_u32_e32 v68, s14, v0
	v_cmp_lt_i32_e32 vcc, s22, v68
	v_lshl_add_u64 v[40:41], v[10:11], 0, s[16:17]
	s_nop 0
	v_cndmask_b32_e32 v40, v40, v10, vcc
	v_cndmask_b32_e32 v41, v41, v11, vcc
	global_load_dwordx4 v[48:51], v[40:41], off offset:-2048 nt
	global_load_dwordx4 v[52:55], v[40:41], off offset:-1024 nt
	global_load_dwordx4 v[56:59], v[40:41], off nt
	global_load_dwordx4 v[60:63], v[40:41], off offset:1024 nt
	v_lshl_add_u64 v[40:41], s[12:13], 0, v[8:9]
	v_add_co_u32_e32 v38, vcc, s15, v40
	s_nop 1
	v_addc_co_u32_e32 v39, vcc, 0, v41, vcc
	s_waitcnt vmcnt(4)
	v_cvt_pk_bf16_f32 v72, v22, v23
	v_cvt_pk_bf16_f32 v73, v24, v25
	global_store_dwordx2 v[38:39], v[72:73], off
	v_mul_f32_e32 v1, v23, v23
	v_fmac_f32_e32 v1, v22, v22
	v_fmac_f32_e32 v1, v24, v24
	v_fmac_f32_e32 v1, v25, v25
	v_cvt_pk_bf16_f32 v74, v26, v27
	v_cvt_pk_bf16_f32 v75, v28, v29
	global_store_dwordx2 v[38:39], v[74:75], off offset:512
	v_mul_f32_e32 v16, v27, v27
	v_fmac_f32_e32 v16, v26, v26
	v_fmac_f32_e32 v16, v28, v28
	v_fmac_f32_e32 v16, v29, v29
	v_add_f32_e32 v1, v1, v16
	v_cvt_pk_bf16_f32 v76, v30, v31
	v_cvt_pk_bf16_f32 v77, v32, v33
	global_store_dwordx2 v[38:39], v[76:77], off offset:1024
	v_mul_f32_e32 v16, v31, v31
	v_fmac_f32_e32 v16, v30, v30
	v_fmac_f32_e32 v16, v32, v32
	v_fmac_f32_e32 v16, v33, v33
	v_add_f32_e32 v1, v1, v16
	v_cvt_pk_bf16_f32 v78, v34, v35
	v_cvt_pk_bf16_f32 v79, v36, v37
	global_store_dwordx2 v[38:39], v[78:79], off offset:1536
	v_mul_f32_e32 v16, v35, v35
	v_fmac_f32_e32 v16, v34, v34
	v_fmac_f32_e32 v16, v36, v36
	v_fmac_f32_e32 v16, v37, v37
	v_add_f32_e32 v1, v1, v16
	ds_bpermute_b32 v16, v12, v1
	s_waitcnt lgkmcnt(0)
	v_add_f32_e32 v1, v1, v16
	ds_bpermute_b32 v16, v13, v1
	s_waitcnt lgkmcnt(0)
	v_add_f32_e32 v1, v1, v16
	ds_bpermute_b32 v16, v17, v1
	s_waitcnt lgkmcnt(0)
	v_add_f32_e32 v1, v1, v16
	ds_bpermute_b32 v16, v18, v1
	s_waitcnt lgkmcnt(0)
	v_add_f32_e32 v1, v1, v16
	ds_bpermute_b32 v16, v19, v1
	s_waitcnt lgkmcnt(0)
	v_add_f32_e32 v1, v1, v16
	ds_bpermute_b32 v16, v20, v1
	s_and_saveexec_b64 s[20:21], s[4:5]
	s_cbranch_execz .Lxc_aA
	s_waitcnt lgkmcnt(0)
	v_add_f32_e32 v1, v1, v16
	v_mul_f32_e32 v1, 0x49800000, v1
	v_trunc_f32_e32 v1, v1
	v_mul_f32_e32 v16, 0x2f800000, v1
	v_floor_f32_e32 v16, v16
	v_fmac_f32_e32 v1, 0xcf800000, v16
	v_cvt_u32_f32_e32 v64, v1
	v_cvt_u32_f32_e32 v65, v16
	v_lshl_add_u64 v[66:67], s[12:13], 0, v[2:3]
	global_store_dwordx2 v[66:67], v[64:65], off
.Lxc_aA:
	s_or_b64 exec, exec, s[20:21]
	s_and_saveexec_b64 s[20:21], s[6:7]
	s_cbranch_execz .Lxc_bA
	v_lshl_add_u64 v[64:65], s[12:13], 0, v[6:7]
	global_store_dwordx2 v[64:65], v[4:5], off

; DI unsigned pk2(float lo, float hi) { f32x2 v = {lo, hi}; bf16x2_t b = __builtin_convertvector(v, bf16x2_t); return __builtin_bit_cast(unsigned, b); }
; DI u64 ss_to_fix(float ss) { return (u64)(ss * 1048576.f); }
; DI void phase_prologue(int wv, const ArgP a, LAS unsigned char* lds, int parts) {
;     ...
;     for (int t = gw; t < S; t += NGW) {
;         float ss = 0.f;
; #pragma unroll
;         for (int j = 0; j < 4; ++j) { const f32x4 v = __builtin_nontemporal_load((const f32x4*)(x + (size_t)t * 1024 + j * 256 + lane * 4));
;             ss += v[0] * v[0] + v[1] * v[1] + v[2] * v[2] + v[3] * v[3];
;             u32x2 w; w.x = pk2(v[0], v[1]); w.y = pk2(v[2], v[3]); *(u32x2*)(XB + (size_t)t * 1024 + j * 256 + lane * 4) = w; }
;         ss = wave_sum(ss);
;         if (lane == 0) rowss[t] = ss_to_fix(ss);
;         if (lane >= 1 && lane < 5) rowss[(size_t)lane * S + t] = 0ull;
.Lxc_bodyB:
	v_add_u32_e32 v68, s14, v0
	v_cmp_lt_i32_e32 vcc, s22, v68
	v_lshl_add_u64 v[40:41], v[10:11], 0, s[16:17]
	s_nop 0
	v_cndmask_b32_e32 v40, v40, v10, vcc
	v_cndmask_b32_e32 v41, v41, v11, vcc
	global_load_dwordx4 v[22:25], v[40:41], off offset:-2048 nt
	global_load_dwordx4 v[26:29], v[40:41], off offset:-1024 nt
	global_load_dwordx4 v[30:33], v[40:41], off nt
	global_load_dwordx4 v[34:37], v[40:41], off offset:1024 nt
	v_lshl_add_u64 v[40:41], s[12:13], 0, v[8:9]
	v_add_co_u32_e32 v38, vcc, s15, v40
	s_nop 1
	v_addc_co_u32_e32 v39, vcc, 0, v41, vcc
	s_waitcnt vmcnt(4)
	v_cvt_pk_bf16_f32 v72, v48, v49
	v_cvt_pk_bf16_f32 v73, v50, v51
	global_store_dwordx2 v[38:39], v[72:73], off
	v_mul_f32_e32 v1, v49, v49
	v_fmac_f32_e32 v1, v48, v48
	v_fmac_f32_e32 v1, v50, v50
	v_fmac_f32_e32 v1, v51, v51
	v_cvt_pk_bf16_f32 v74, v52, v53
	v_cvt_pk_bf16_f32 v75, v54, v55
	global_store_dwordx2 v[38:39], v[74:75], off offset:512
	v_mul_f32_e32 v16, v53, v53
	v_fmac_f32_e32 v16, v52, v52
	v_fmac_f32_e32 v16, v54, v54
	v_fmac_f32_e32 v16, v55, v55
	v_add_f32_e32 v1, v1, v16
	v_cvt_pk_bf16_f32 v76, v56, v57
	v_cvt_pk_bf16_f32 v77, v58, v59
	global_store_dwordx2 v[38:39], v[76:77], off offset:1024
	v_mul_f32_e32 v16, v57, v57
	v_fmac_f32_e32 v16, v56, v56
	v_fmac_f32_e32 v16, v58, v58
	v_fmac_f32_e32 v16, v59, v59
	v_add_f32_e32 v1, v1, v16
	v_cvt_pk_bf16_f32 v78, v60, v61
	v_cvt_pk_bf16_f32 v79, v62, v63
	global_store_dwordx2 v[38:39], v[78:79], off offset:1536
	v_mul_f32_e32 v16, v61, v61
	v_fmac_f32_e32 v16, v60, v60
	v_fmac_f32_e32 v16, v62, v62
	v_fmac_f32_e32 v16, v63, v63
	v_add_f32_e32 v1, v1, v16
	ds_bpermute_b32 v16, v12, v1
	s_waitcnt lgkmcnt(0)
	v_add_f32_e32 v1, v1, v16
	ds_bpermute_b32 v16, v13, v1
	s_waitcnt lgkmcnt(0)
	v_add_f32_e32 v1, v1, v16
	ds_bpermute_b32 v16, v17, v1
	s_waitcnt lgkmcnt(0)
	v_add_f32_e32 v1, v1, v16
	ds_bpermute_b32 v16, v18, v1
	s_waitcnt lgkmcnt(0)
	v_add_f32_e32 v1, v1, v16
	ds_bpermute_b32 v16, v19, v1
	s_waitcnt lgkmcnt(0)
	v_add_f32_e32 v1, v1, v16
	ds_bpermute_b32 v16, v20, v1
	s_and_saveexec_b64 s[20:21], s[4:5]
	s_cbranch_execz .Lxc_aB
	s_waitcnt lgkmcnt(0)
	v_add_f32_e32 v1, v1, v16
	v_mul_f32_e32 v1, 0x49800000, v1
	v_trunc_f32_e32 v1, v1
	v_mul_f32_e32 v16, 0x2f800000, v1
	v_floor_f32_e32 v16, v16
	v_fmac_f32_e32 v1, 0xcf800000, v16
	v_cvt_u32_f32_e32 v64, v1
	v_cvt_u32_f32_e32 v65, v16
	v_lshl_add_u64 v[66:67], s[12:13], 0, v[2:3]
	global_store_dwordx2 v[66:67], v[64:65], off

; DI unsigned pk2(float lo, float hi) { f32x2 v = {lo, hi}; bf16x2_t b = __builtin_convertvector(v, bf16x2_t); return __builtin_bit_cast(unsigned, b); }
; DI u64 ss_to_fix(float ss) { return (u64)(ss * 1048576.f); }
; DI void phase_prologue(int wv, const ArgP a, LAS unsigned char* lds, int parts) {
;     ...
;     for (int t = gw; t < S; t += NGW) {
;         float ss = 0.f;
; #pragma unroll
;         for (int j = 0; j < 4; ++j) { const f32x4 v = __builtin_nontemporal_load((const f32x4*)(x + (size_t)t * 1024 + j * 256 + lane * 4));
;             ss += v[0] * v[0] + v[1] * v[1] + v[2] * v[2] + v[3] * v[3];
;             u32x2 w; w.x = pk2(v[0], v[1]); w.y = pk2(v[2], v[3]); *(u32x2*)(XB + (size_t)t * 1024 + j * 256 + lane * 4) = w; }
;         ss = wave_sum(ss);
;         if (lane == 0) rowss[t] = ss_to_fix(ss);
;         if (lane >= 1 && lane < 5) rowss[(size_t)lane * S + t] = 0ull;
;     }
;     }
;     if (parts & 4) {
;     const int* pos = (const int*)a.in(1); float* cst = (float*)(ws + O_CSTAB);
;     for (int e = blockIdx.x * 512 + tid; e < S * 16; e += gridDim.x * 512) { const int t = e >> 4, i = e & 15;
;         const float invf = __builtin_amdgcn_exp2f(-(float)i * (13.287712379549449f / 16.f)); const float ang = (float)pos[t] * invf;
.Lxc_bB:
	s_or_b64 exec, exec, s[20:21]
	v_add_u32_e32 v0, s14, v0
	v_cmp_lt_i32_e32 vcc, s22, v0
	v_lshl_add_u64 v[2:3], v[2:3], 0, s[8:9]
	v_lshl_add_u64 v[6:7], v[6:7], 0, s[8:9]
	v_lshl_add_u64 v[8:9], v[8:9], 0, s[10:11]
	s_or_b64 s[18:19], vcc, s[18:19]
	v_lshl_add_u64 v[10:11], v[10:11], 0, s[16:17]
	s_andn2_b64 exec, exec, s[18:19]
	s_cbranch_execz .Lxc_exit
	s_branch .Lxc_bodyA
.Lxc_exit:
	s_waitcnt vmcnt(0)
.LBB0_313:
	s_or_b64 exec, exec, s[0:1]
	s_lshl_b32 s33, s80, 9
	v_add_u32_e32 v2, s33, v15
	s_mov_b32 s0, 0x40000
	v_cmp_gt_i32_e32 vcc, s0, v2
	s_and_saveexec_b64 s[0:1], vcc
	s_cbranch_execz .LBB0_316
	v_and_b32_e32 v0, 15, v14
	v_cvt_f32_ubyte0_e32 v0, v0
	s_load_dwordx2 s[2:3], s[2:3], 0x8
	v_mul_f32_e32 v0, 0xbf549a78, v0
	v_exp_f32_e32 v3, v0
	s_add_u32 s4, s12, 0x1940000
	s_addc_u32 s5, s13, 0
	s_lshl_b32 s8, s24, 9
	v_lshlrev_b32_e32 v0, 1, v2
	s_lshl_b32 s9, s24, 10
	s_mov_b64 s[6:7], 0
	s_mov_b32 s10, 0x3ffff

; #define LAS __attribute__((address_space(3)))
;     DI void operator()(const AccT& acc, const Unit& u, int wr, int wc, int fr, int fq) const {
;     ...
;         { const int lane = fq * 16 + fr, kind = lane >> 3, c4 = 4 * (lane & 7), k3 = kind & 3;
;           const float* src = (k3 == 0 ? cb : cw + (k3 - 1) * 5632) + (kind >= 4 ? 2816 : 0) + u.pn * 128 + wc * 32 + c4;
;           *(LAS f32x4*)(P + kind * 32 + c4) = *(const f32x4*)src; }
; #pragma unroll
;         for (int ai = 0; ai < 2; ++ai) {
;             const int tok0 = u.pm * 248 + 62 * (2 * ai + wr) - 2 + fr;
;             float rs[4];
; #pragma unroll
;             for (int m = 0; m < 4; ++m) { const int t = tok0 + 16 * m; const int tc = t < 0 ? 0 : (t >= S ? S - 1 : t); const float r = rs_from_ss(rowss[tc]); rs[m] = t < 0 ? 0.f : r; }
;             const int row0 = fr < 2 ? (S + 236 + fr) : tok0;
; #pragma unroll
;             for (int n = 0; n < 2; ++n) {
;                 const int lc = 8 * fq + 4 * n;
;                 unsigned wpk[4][2];
; #pragma unroll
;                 for (int jp = 0; jp < 2; ++jp) {
;                     const f32x2 bg = *(const LAS f32x2*)(P + lc + 2 * jp), g0 = *(const LAS f32x2*)(P + 32 + lc + 2 * jp), g1 = *(const LAS f32x2*)(P + 64 + lc + 2 * jp), g2 = *(const LAS f32x2*)(P + 96 + lc + 2 * jp);
;                     const f32x2 bv = *(const LAS f32x2*)(P + 128 + lc + 2 * jp), v0 = *(const LAS f32x2*)(P + 160 + lc + 2 * jp), v1 = *(const LAS f32x2*)(P + 192 + lc + 2 * jp), v2 = *(const LAS f32x2*)(P + 224 + lc + 2 * jp);
;                     f32x2 G[4], V[4];
; #pragma unroll
;                     for (int m = 0; m < 4; ++m) { G[m] = (f32x2){acc[ai][0][m][n][2 * jp], acc[ai][0][m][n][2 * jp + 1]} * rs[m]; V[m] = (f32x2){acc[ai][1][m][n][2 * jp], acc[ai][1][m][n][2 * jp + 1]} * rs[m]; }
; #pragma unroll
;                     for (int m = 0; m < 4; ++m) {
;                         const f32x2 zz = {0.f, 0.f}; const f32x2 Gp = m ? G[m - 1] : zz, Vp = m ? V[m - 1] : zz;
;                         const f32x2 gp1 = {dpp_prev1(G[m].x, Gp.x), dpp_prev1(G[m].y, Gp.y)}, gp2 = {dpp_prev2(G[m].x, Gp.x), dpp_prev2(G[m].y, Gp.y)};
;                         const f32x2 vp1 = {dpp_prev1(V[m].x, Vp.x), dpp_prev1(V[m].y, Vp.y)}, vp2 = {dpp_prev2(V[m].x, Vp.x), dpp_prev2(V[m].y, Vp.y)};
;                         const f32x2 gc = bg + g0 * gp2 + g1 * gp1 + g2 * G[m];
.LBB0_1122:
	s_lshl_b32 s10, s58, 7
	s_ashr_i32 s11, s10, 31
	v_lshl_add_u64 v[128:129], s[10:11], 2, v[168:169]
	s_mul_i32 s11, s57, 0xf8
	v_add_u32_e32 v204, s11, v170
	v_med3_i32 v132, v204, 0, s51
	v_lshlrev_b32_e32 v132, 3, v132
	global_load_dwordx2 v[180:181], v132, s[16:17]
	v_add_u32_e32 v205, 16, v204
	v_med3_i32 v132, v205, 0, s51
	v_add_u32_e32 v206, 32, v204
	v_add_u32_e32 v207, 48, v204
	v_lshlrev_b32_e32 v132, 3, v132
	v_med3_i32 v133, v206, 0, s51
	v_med3_i32 v134, v207, 0, s51
	global_load_dwordx4 v[128:131], v[128:129], off
	v_lshlrev_b32_e32 v133, 3, v133
	v_lshlrev_b32_e32 v134, 3, v134
	global_load_dwordx2 v[182:183], v132, s[16:17]
	global_load_dwordx2 v[210:211], v133, s[16:17]
	global_load_dwordx2 v[212:213], v134, s[16:17]
	v_or_b32_e32 v188, s10, v187
	v_ashrrev_i32_e32 v189, 31, v188
	v_cndmask_b32_e64 v208, v204, v190, s[6:7]
	s_waitcnt vmcnt(0)
	v_add_u32_e32 v250, 0x7c, v204
	v_med3_i32 v250, v250, 0, s51
	v_lshlrev_b32_e32 v250, 3, v250
	global_load_dwordx2 v[242:243], v250, s[16:17]
	v_add_u32_e32 v250, 0x8c, v204
	v_med3_i32 v250, v250, 0, s51
	v_lshlrev_b32_e32 v250, 3, v250
	global_load_dwordx2 v[244:245], v250, s[16:17]
	v_add_u32_e32 v250, 0x9c, v204
	v_med3_i32 v250, v250, 0, s51
	v_lshlrev_b32_e32 v250, 3, v250
	global_load_dwordx2 v[246:247], v250, s[16:17]
	v_add_u32_e32 v250, 0xac, v204
	v_med3_i32 v250, v250, 0, s51
	v_lshlrev_b32_e32 v250, 3, v250
	global_load_dwordx2 v[248:249], v250, s[16:17]
	v_ffbh_u32_e32 v184, v181
	v_min_u32_e32 v184, 32, v184
	v_lshlrev_b64 v[180:181], v184, v[180:181]
	v_min_u32_e32 v180, 1, v180
	v_or_b32_e32 v180, v181, v180
	v_cvt_f32_u32_e32 v180, v180
	v_sub_u32_e32 v184, 32, v184
	ds_write_b128 v191, v[128:131]
	v_ffbh_u32_e32 v186, v183
	v_ffbh_u32_e32 v209, v211
	v_min_u32_e32 v186, 32, v186
	v_ffbh_u32_e32 v214, v213
	v_min_u32_e32 v209, 32, v209
	v_lshlrev_b64 v[182:183], v186, v[182:183]
	v_min_u32_e32 v214, 32, v214
	v_lshlrev_b64 v[210:211], v209, v[210:211]
	v_min_u32_e32 v181, 1, v182
	v_lshlrev_b64 v[212:213], v214, v[212:213]
	v_min_u32_e32 v182, 1, v210
	v_or_b32_e32 v181, v183, v181
	v_min_u32_e32 v210, 1, v212
	v_or_b32_e32 v182, v211, v182
	v_cvt_f32_u32_e32 v181, v181
	v_or_b32_e32 v183, v213, v210
	v_cvt_f32_u32_e32 v182, v182
	v_cvt_f32_u32_e32 v183, v183
	v_sub_u32_e32 v186, 32, v186
	v_ldexp_f32 v180, v180, v184
	v_sub_u32_e32 v209, 32, v209
	v_fmamk_f32 v180, v180, 0x30800000, v203
	v_ldexp_f32 v181, v181, v186
	v_sub_u32_e32 v214, 32, v214
	v_ldexp_f32 v182, v182, v209
	v_mul_f32_e32 v184, 0x4b800000, v180
	v_fmamk_f32 v181, v181, 0x30800000, v203
	v_cmp_gt_f32_e32 vcc, s52, v180
	v_ldexp_f32 v183, v183, v214
	v_fmamk_f32 v182, v182, 0x30800000, v203
	v_cndmask_b32_e32 v180, v180, v184, vcc
	v_mul_f32_e32 v184, 0x4b800000, v181
	v_cmp_gt_f32_e64 s[10:11], s52, v181
	v_fmamk_f32 v183, v183, 0x30800000, v203
	v_mul_f32_e32 v186, 0x4b800000, v182
	v_rsq_f32_e32 v180, v180
	v_cndmask_b32_e64 v181, v181, v184, s[10:11]
	v_cmp_gt_f32_e64 s[12:13], s52, v182
	v_mul_f32_e32 v209, 0x4b800000, v183
	v_cmp_gt_f32_e64 s[14:15], s52, v183
	v_cndmask_b32_e64 v182, v182, v186, s[12:13]
	v_rsq_f32_e32 v181, v181
	v_cndmask_b32_e64 v183, v183, v209, s[14:15]
	v_rsq_f32_e32 v182, v182
	v_rsq_f32_e32 v183, v183
	v_mul_f32_e32 v184, 0x45800000, v180
	v_cndmask_b32_e32 v180, v180, v184, vcc
	v_mul_f32_e32 v184, 0x45800000, v181
	v_cmp_lt_i32_e32 vcc, -1, v204
	v_mul_f32_e32 v209, 0x45800000, v182
	v_mul_f32_e32 v210, 0x45800000, v183
	v_cndmask_b32_e32 v186, 0, v180, vcc
	v_cndmask_b32_e64 v180, v181, v184, s[10:11]
	v_cmp_lt_i32_e32 vcc, s53, v204
	v_cndmask_b32_e64 v181, v182, v209, s[12:13]
	v_cndmask_b32_e64 v183, v183, v210, s[14:15]
	v_cndmask_b32_e32 v184, 0, v180, vcc
	v_cmp_lt_i32_e32 vcc, s54, v204
	v_pk_mul_f32 v[124:125], v[124:125], v[186:187] op_sel_hi:[1,0]
	ds_read_b128 v[136:139], v200
	ds_read_b128 v[148:151], v200 offset:128
	ds_read_b128 v[152:155], v200 offset:256
	ds_read_b128 v[156:159], v200 offset:384
	ds_read_b128 v[128:131], v200 offset:512
	ds_read_b128 v[132:135], v200 offset:640
	ds_read_b128 v[140:143], v200 offset:768
	ds_read_b128 v[144:147], v200 offset:896
	v_cndmask_b32_e32 v182, 0, v181, vcc
	v_cmp_lt_i32_e32 vcc, s55, v204
	v_pk_mul_f32 v[108:109], v[108:109], v[182:183] op_sel_hi:[1,0]
	v_pk_mul_f32 v[210:211], v[104:105], v[182:183] op_sel_hi:[1,0]
	v_cndmask_b32_e32 v180, 0, v183, vcc
	v_mov_b32_e32 v183, 0
	v_pk_mul_f32 v[212:213], v[100:101], v[180:181] op_sel_hi:[1,0]
	v_pk_mul_f32 v[214:215], v[96:97], v[180:181] op_sel_hi:[1,0]
	v_mov_b32_e32 v181, 0
	v_mov_b32_dpp v183, v183 row_ror:2 row_mask:0xf bank_mask:0xf
	v_mov_b32_e32 v100, v183
	v_mov_b32_dpp v181, v181 row_ror:1 row_mask:0xf bank_mask:0xf
	v_mov_b32_e32 v101, v183
	v_mov_b32_e32 v96, v181
	v_mov_b32_e32 v97, v181
	v_mov_b32_dpp v100, v124 row_shr:2 row_mask:0xf bank_mask:0xf
	v_mov_b32_dpp v101, v125 row_shr:2 row_mask:0xf bank_mask:0xf
	v_mov_b32_dpp v96, v124 row_shr:1 row_mask:0xf bank_mask:0xf
	v_mov_b32_dpp v97, v125 row_shr:1 row_mask:0xf bank_mask:0xf
	s_waitcnt lgkmcnt(6)
	v_pk_fma_f32 v[100:101], v[148:149], v[100:101], v[136:137]
	v_pk_mul_f32 v[120:121], v[120:121], v[186:187] op_sel_hi:[1,0]
	s_waitcnt lgkmcnt(5)
	v_pk_fma_f32 v[96:97], v[152:153], v[96:97], v[100:101]
	v_mov_b32_e32 v216, v183
	s_waitcnt lgkmcnt(4)
	v_pk_fma_f32 v[96:97], v[156:157], v[124:125], v[96:97]
	v_mov_b32_e32 v217, v183
	v_pk_mul_f32 v[100:101], v[96:97], s[0:1] op_sel_hi:[1,0]
	v_mov_b32_e32 v104, v181
	v_exp_f32_e32 v100, v100
	v_exp_f32_e32 v101, v101
	v_mov_b32_e32 v105, v181
	v_mov_b32_dpp v216, v120 row_shr:2 row_mask:0xf bank_mask:0xf
	v_mov_b32_dpp v217, v121 row_shr:2 row_mask:0xf bank_mask:0xf
	v_pk_add_f32 v[100:101], v[100:101], 1.0 op_sel_hi:[1,0]
	v_mov_b32_dpp v104, v120 row_shr:1 row_mask:0xf bank_mask:0xf
	v_rcp_f32_e32 v100, v100
	v_rcp_f32_e32 v101, v101
	v_mov_b32_dpp v105, v121 row_shr:1 row_mask:0xf bank_mask:0xf
	s_waitcnt lgkmcnt(2)
; #define LAS __attribute__((address_space(3)))
; DI unsigned pk2(float lo, float hi) { f32x2 v = {lo, hi}; bf16x2_t b = __builtin_convertvector(v, bf16x2_t); return __builtin_bit_cast(unsigned, b); }
;     DI void operator()(const AccT& acc, const Unit& u, int wr, int wc, int fr, int fq) const {
;     ...
;                     const f32x2 bg = *(const LAS f32x2*)(P + lc + 2 * jp), g0 = *(const LAS f32x2*)(P + 32 + lc + 2 * jp), g1 = *(const LAS f32x2*)(P + 64 + lc + 2 * jp), g2 = *(const LAS f32x2*)(P + 96 + lc + 2 * jp);
;                     const f32x2 bv = *(const LAS f32x2*)(P + 128 + lc + 2 * jp), v0 = *(const LAS f32x2*)(P + 160 + lc + 2 * jp), v1 = *(const LAS f32x2*)(P + 192 + lc + 2 * jp), v2 = *(const LAS f32x2*)(P + 224 + lc + 2 * jp);
;                     f32x2 G[4], V[4];
; #pragma unroll
;                     for (int m = 0; m < 4; ++m) { G[m] = (f32x2){acc[ai][0][m][n][2 * jp], acc[ai][0][m][n][2 * jp + 1]} * rs[m]; V[m] = (f32x2){acc[ai][1][m][n][2 * jp], acc[ai][1][m][n][2 * jp + 1]} * rs[m]; }
; #pragma unroll
;                     for (int m = 0; m < 4; ++m) {
;                         const f32x2 zz = {0.f, 0.f}; const f32x2 Gp = m ? G[m - 1] : zz, Vp = m ? V[m - 1] : zz;
;                         const f32x2 gp1 = {dpp_prev1(G[m].x, Gp.x), dpp_prev1(G[m].y, Gp.y)}, gp2 = {dpp_prev2(G[m].x, Gp.x), dpp_prev2(G[m].y, Gp.y)};
;                         const f32x2 vp1 = {dpp_prev1(V[m].x, Vp.x), dpp_prev1(V[m].y, Vp.y)}, vp2 = {dpp_prev2(V[m].x, Vp.x), dpp_prev2(V[m].y, Vp.y)};
;                         const f32x2 gc = bg + g0 * gp2 + g1 * gp1 + g2 * G[m];
;                         const f32x2 vc = bv + v0 * vp2 + v1 * vp1 + v2 * V[m];
;                         const f32x2 xe = gc * (-LOG2E);
;                         f32x2 dn = {__builtin_amdgcn_exp2f(xe.x), __builtin_amdgcn_exp2f(xe.y)}; dn = dn + 1.0f;
;                         const f32x2 rc = {__builtin_amdgcn_rcpf(dn.x), __builtin_amdgcn_rcpf(dn.y)};
;                         const f32x2 rr = gc * rc * vc;
;                         wpk[m][jp] = pk2(rr.x, rr.y); }
	v_pk_fma_f32 v[216:217], v[132:133], v[216:217], v[128:129]
	v_pk_mul_f32 v[116:117], v[116:117], v[184:185] op_sel_hi:[1,0]
	s_waitcnt lgkmcnt(1)
	v_pk_fma_f32 v[104:105], v[140:141], v[104:105], v[216:217]
	v_pk_mul_f32 v[96:97], v[96:97], v[100:101]
	s_waitcnt lgkmcnt(0)
	v_pk_fma_f32 v[104:105], v[144:145], v[120:121], v[104:105]
	v_pk_mul_f32 v[96:97], v[104:105], v[96:97]
	v_mov_b32_dpp v104, v124 row_ror:2 row_mask:0xf bank_mask:0xf
	v_mov_b32_dpp v105, v125 row_ror:2 row_mask:0xf bank_mask:0xf
	v_mov_b32_dpp v100, v124 row_ror:1 row_mask:0xf bank_mask:0xf
	v_mov_b32_dpp v101, v125 row_ror:1 row_mask:0xf bank_mask:0xf
	v_mov_b32_dpp v104, v116 row_shr:2 row_mask:0xf bank_mask:0xf
	v_mov_b32_dpp v105, v117 row_shr:2 row_mask:0xf bank_mask:0xf
	v_mov_b32_dpp v100, v116 row_shr:1 row_mask:0xf bank_mask:0xf
	v_mov_b32_dpp v101, v117 row_shr:1 row_mask:0xf bank_mask:0xf
	v_pk_fma_f32 v[104:105], v[148:149], v[104:105], v[136:137]
	v_pk_fma_f32 v[100:101], v[152:153], v[100:101], v[104:105]
	v_pk_fma_f32 v[100:101], v[156:157], v[116:117], v[100:101]
	v_pk_mul_f32 v[112:113], v[112:113], v[184:185] op_sel_hi:[1,0]
	v_pk_mul_f32 v[104:105], v[100:101], s[0:1] op_sel_hi:[1,0]
	v_exp_f32_e32 v104, v104
	v_exp_f32_e32 v105, v105
	v_mov_b32_dpp v216, v120 row_ror:2 row_mask:0xf bank_mask:0xf
	v_mov_b32_dpp v217, v121 row_ror:2 row_mask:0xf bank_mask:0xf
	v_pk_add_f32 v[104:105], v[104:105], 1.0 op_sel_hi:[1,0]
	v_mov_b32_dpp v124, v120 row_ror:1 row_mask:0xf bank_mask:0xf
	v_rcp_f32_e32 v104, v104
	v_rcp_f32_e32 v105, v105
	v_mov_b32_dpp v125, v121 row_ror:1 row_mask:0xf bank_mask:0xf
	v_mov_b32_dpp v216, v112 row_shr:2 row_mask:0xf bank_mask:0xf
	v_mov_b32_dpp v217, v113 row_shr:2 row_mask:0xf bank_mask:0xf
	v_mov_b32_dpp v124, v112 row_shr:1 row_mask:0xf bank_mask:0xf
	v_mov_b32_dpp v125, v113 row_shr:1 row_mask:0xf bank_mask:0xf
	v_pk_fma_f32 v[120:121], v[132:133], v[216:217], v[128:129]
	v_pk_mul_f32 v[100:101], v[100:101], v[104:105]
	v_pk_fma_f32 v[120:121], v[140:141], v[124:125], v[120:121]
	v_pk_fma_f32 v[120:121], v[144:145], v[112:113], v[120:121]
	v_pk_mul_f32 v[100:101], v[120:121], v[100:101]
	v_mov_b32_dpp v104, v116 row_ror:1 row_mask:0xf bank_mask:0xf
	v_mov_b32_dpp v120, v116 row_ror:2 row_mask:0xf bank_mask:0xf
	v_mov_b32_dpp v121, v117 row_ror:2 row_mask:0xf bank_mask:0xf
	v_mov_b32_dpp v105, v117 row_ror:1 row_mask:0xf bank_mask:0xf
	v_mov_b32_dpp v120, v108 row_shr:2 row_mask:0xf bank_mask:0xf
	v_mov_b32_dpp v121, v109 row_shr:2 row_mask:0xf bank_mask:0xf
	v_mov_b32_dpp v104, v108 row_shr:1 row_mask:0xf bank_mask:0xf
	v_mov_b32_dpp v105, v109 row_shr:1 row_mask:0xf bank_mask:0xf
	v_pk_fma_f32 v[120:121], v[148:149], v[120:121], v[136:137]
	v_pk_fma_f32 v[104:105], v[152:153], v[104:105], v[120:121]
	v_pk_fma_f32 v[104:105], v[156:157], v[108:109], v[104:105]
	v_pk_mul_f32 v[120:121], v[104:105], s[0:1] op_sel_hi:[1,0]
	v_exp_f32_e32 v120, v120
	v_exp_f32_e32 v121, v121
	v_mov_b32_dpp v116, v112 row_ror:1 row_mask:0xf bank_mask:0xf
	v_mov_b32_dpp v117, v113 row_ror:1 row_mask:0xf bank_mask:0xf
	v_mov_b32_dpp v124, v112 row_ror:2 row_mask:0xf bank_mask:0xf
	v_mov_b32_dpp v125, v113 row_ror:2 row_mask:0xf bank_mask:0xf
	v_pk_add_f32 v[112:113], v[120:121], 1.0 op_sel_hi:[1,0]
	v_mov_b32_dpp v124, v210 row_shr:2 row_mask:0xf bank_mask:0xf
	v_rcp_f32_e32 v112, v112
	v_rcp_f32_e32 v113, v113
	v_mov_b32_dpp v125, v211 row_shr:2 row_mask:0xf bank_mask:0xf
	v_mov_b32_dpp v116, v210 row_shr:1 row_mask:0xf bank_mask:0xf
	v_mov_b32_dpp v117, v211 row_shr:1 row_mask:0xf bank_mask:0xf
	v_pk_fma_f32 v[120:121], v[132:133], v[124:125], v[128:129]
	v_pk_mul_f32 v[104:105], v[104:105], v[112:113]
	v_pk_fma_f32 v[116:117], v[140:141], v[116:117], v[120:121]
	v_pk_fma_f32 v[116:117], v[144:145], v[210:211], v[116:117]
	v_pk_mul_f32 v[104:105], v[116:117], v[104:105]
	v_mov_b32_dpp v112, v108 row_ror:1 row_mask:0xf bank_mask:0xf
	v_mov_b32_dpp v116, v108 row_ror:2 row_mask:0xf bank_mask:0xf
	v_mov_b32_dpp v117, v109 row_ror:2 row_mask:0xf bank_mask:0xf
	v_mov_b32_dpp v113, v109 row_ror:1 row_mask:0xf bank_mask:0xf
	v_mov_b32_dpp v116, v212 row_shr:2 row_mask:0xf bank_mask:0xf
	v_mov_b32_dpp v117, v213 row_shr:2 row_mask:0xf bank_mask:0xf
	v_mov_b32_dpp v112, v212 row_shr:1 row_mask:0xf bank_mask:0xf
	v_mov_b32_dpp v113, v213 row_shr:1 row_mask:0xf bank_mask:0xf
	v_pk_fma_f32 v[116:117], v[148:149], v[116:117], v[136:137]
	v_pk_fma_f32 v[112:113], v[152:153], v[112:113], v[116:117]
	v_pk_fma_f32 v[112:113], v[156:157], v[212:213], v[112:113]
	v_pk_mul_f32 v[116:117], v[112:113], s[0:1] op_sel_hi:[1,0]
	v_exp_f32_e32 v116, v116
	v_exp_f32_e32 v117, v117
	v_mov_b32_dpp v120, v210 row_ror:2 row_mask:0xf bank_mask:0xf
	v_mov_b32_dpp v121, v211 row_ror:2 row_mask:0xf bank_mask:0xf
	v_mov_b32_dpp v108, v210 row_ror:1 row_mask:0xf bank_mask:0xf
	v_pk_add_f32 v[116:117], v[116:117], 1.0 op_sel_hi:[1,0]
	v_mov_b32_dpp v109, v211 row_ror:1 row_mask:0xf bank_mask:0xf
	v_rcp_f32_e32 v116, v116
	v_rcp_f32_e32 v117, v117
	v_mov_b32_dpp v120, v214 row_shr:2 row_mask:0xf bank_mask:0xf
	v_mov_b32_dpp v121, v215 row_shr:2 row_mask:0xf bank_mask:0xf
	v_mov_b32_dpp v108, v214 row_shr:1 row_mask:0xf bank_mask:0xf
	v_mov_b32_dpp v109, v215 row_shr:1 row_mask:0xf bank_mask:0xf
	v_pk_fma_f32 v[120:121], v[132:133], v[120:121], v[128:129]
	v_pk_mul_f32 v[112:113], v[112:113], v[116:117]
	v_pk_fma_f32 v[108:109], v[140:141], v[108:109], v[120:121]
	v_pk_mul_f32 v[116:117], v[122:123], v[186:187] op_sel_hi:[1,0]
	v_pk_fma_f32 v[108:109], v[144:145], v[214:215], v[108:109]
	v_mov_b32_e32 v122, v183
	v_pk_mul_f32 v[108:109], v[108:109], v[112:113]
; #define LAS __attribute__((address_space(3)))
; DI unsigned pk2(float lo, float hi) { f32x2 v = {lo, hi}; bf16x2_t b = __builtin_convertvector(v, bf16x2_t); return __builtin_bit_cast(unsigned, b); }
;     DI void operator()(const AccT& acc, const Unit& u, int wr, int wc, int fr, int fq) const {
;     ...
;                     const f32x2 bg = *(const LAS f32x2*)(P + lc + 2 * jp), g0 = *(const LAS f32x2*)(P + 32 + lc + 2 * jp), g1 = *(const LAS f32x2*)(P + 64 + lc + 2 * jp), g2 = *(const LAS f32x2*)(P + 96 + lc + 2 * jp);
;                     const f32x2 bv = *(const LAS f32x2*)(P + 128 + lc + 2 * jp), v0 = *(const LAS f32x2*)(P + 160 + lc + 2 * jp), v1 = *(const LAS f32x2*)(P + 192 + lc + 2 * jp), v2 = *(const LAS f32x2*)(P + 224 + lc + 2 * jp);
;                     f32x2 G[4], V[4];
; #pragma unroll
;                     for (int m = 0; m < 4; ++m) { G[m] = (f32x2){acc[ai][0][m][n][2 * jp], acc[ai][0][m][n][2 * jp + 1]} * rs[m]; V[m] = (f32x2){acc[ai][1][m][n][2 * jp], acc[ai][1][m][n][2 * jp + 1]} * rs[m]; }
; #pragma unroll
;                     for (int m = 0; m < 4; ++m) {
;                         const f32x2 zz = {0.f, 0.f}; const f32x2 Gp = m ? G[m - 1] : zz, Vp = m ? V[m - 1] : zz;
;                         const f32x2 gp1 = {dpp_prev1(G[m].x, Gp.x), dpp_prev1(G[m].y, Gp.y)}, gp2 = {dpp_prev2(G[m].x, Gp.x), dpp_prev2(G[m].y, Gp.y)};
;                         const f32x2 vp1 = {dpp_prev1(V[m].x, Vp.x), dpp_prev1(V[m].y, Vp.y)}, vp2 = {dpp_prev2(V[m].x, Vp.x), dpp_prev2(V[m].y, Vp.y)};
;                         const f32x2 gc = bg + g0 * gp2 + g1 * gp1 + g2 * G[m];
;                         const f32x2 vc = bv + v0 * vp2 + v1 * vp1 + v2 * V[m];
;                         const f32x2 xe = gc * (-LOG2E);
;                         f32x2 dn = {__builtin_amdgcn_exp2f(xe.x), __builtin_amdgcn_exp2f(xe.y)}; dn = dn + 1.0f;
;                         const f32x2 rc = {__builtin_amdgcn_rcpf(dn.x), __builtin_amdgcn_rcpf(dn.y)};
;                         const f32x2 rr = gc * rc * vc;
;                         wpk[m][jp] = pk2(rr.x, rr.y); }
	v_pk_mul_f32 v[112:113], v[126:127], v[186:187] op_sel_hi:[1,0]
	v_mov_b32_e32 v123, v183
	v_mov_b32_e32 v120, v181
	v_mov_b32_e32 v121, v181
	v_mov_b32_dpp v122, v112 row_shr:2 row_mask:0xf bank_mask:0xf
	v_mov_b32_dpp v123, v113 row_shr:2 row_mask:0xf bank_mask:0xf
	v_mov_b32_dpp v120, v112 row_shr:1 row_mask:0xf bank_mask:0xf
	v_mov_b32_dpp v121, v113 row_shr:1 row_mask:0xf bank_mask:0xf
	v_pk_fma_f32 v[122:123], v[150:151], v[122:123], v[138:139]
	v_mov_b32_e32 v126, v183
	v_pk_fma_f32 v[120:121], v[154:155], v[120:121], v[122:123]
	v_mov_b32_e32 v127, v183
	v_pk_fma_f32 v[120:121], v[112:113], v[158:159], v[120:121]
	v_mov_b32_e32 v124, v181
	v_pk_mul_f32 v[122:123], v[120:121], s[0:1] op_sel_hi:[1,0]
	v_mov_b32_e32 v125, v181
	v_exp_f32_e32 v122, v122
	v_exp_f32_e32 v123, v123
	v_mov_b32_dpp v126, v116 row_shr:2 row_mask:0xf bank_mask:0xf
	v_mov_b32_dpp v127, v117 row_shr:2 row_mask:0xf bank_mask:0xf
	v_mov_b32_dpp v124, v116 row_shr:1 row_mask:0xf bank_mask:0xf
	v_pk_add_f32 v[122:123], v[122:123], 1.0 op_sel_hi:[1,0]
	v_mov_b32_dpp v125, v117 row_shr:1 row_mask:0xf bank_mask:0xf
	v_rcp_f32_e32 v122, v122
	v_rcp_f32_e32 v123, v123
	v_pk_fma_f32 v[126:127], v[134:135], v[126:127], v[130:131]
	v_cvt_pk_bf16_f32 v96, v96, v97
	v_pk_fma_f32 v[124:125], v[142:143], v[124:125], v[126:127]
	v_pk_mul_f32 v[120:121], v[120:121], v[122:123]
	v_pk_fma_f32 v[124:125], v[116:117], v[146:147], v[124:125]
	v_pk_mul_f32 v[120:121], v[124:125], v[120:121]
	v_pk_mul_f32 v[118:119], v[118:119], v[184:185] op_sel_hi:[1,0]
	v_cvt_pk_bf16_f32 v97, v120, v121
	v_mov_b32_dpp v122, v112 row_ror:2 row_mask:0xf bank_mask:0xf
	v_mov_b32_dpp v123, v113 row_ror:2 row_mask:0xf bank_mask:0xf
	v_mov_b32_dpp v120, v112 row_ror:1 row_mask:0xf bank_mask:0xf
	v_mov_b32_dpp v121, v113 row_ror:1 row_mask:0xf bank_mask:0xf
	v_mov_b32_dpp v122, v118 row_shr:2 row_mask:0xf bank_mask:0xf
	v_mov_b32_dpp v123, v119 row_shr:2 row_mask:0xf bank_mask:0xf
	v_mov_b32_dpp v120, v118 row_shr:1 row_mask:0xf bank_mask:0xf
	v_mov_b32_dpp v121, v119 row_shr:1 row_mask:0xf bank_mask:0xf
	v_pk_fma_f32 v[122:123], v[150:151], v[122:123], v[138:139]
	v_pk_fma_f32 v[120:121], v[154:155], v[120:121], v[122:123]
	v_pk_fma_f32 v[120:121], v[118:119], v[158:159], v[120:121]
	v_pk_mul_f32 v[122:123], v[120:121], s[0:1] op_sel_hi:[1,0]
	v_exp_f32_e32 v122, v122
	v_exp_f32_e32 v123, v123
	v_mov_b32_dpp v112, v116 row_ror:1 row_mask:0xf bank_mask:0xf
	v_mov_b32_dpp v113, v117 row_ror:1 row_mask:0xf bank_mask:0xf
	v_mov_b32_dpp v124, v116 row_ror:2 row_mask:0xf bank_mask:0xf
	v_mov_b32_dpp v125, v117 row_ror:2 row_mask:0xf bank_mask:0xf
	v_pk_add_f32 v[116:117], v[122:123], 1.0 op_sel_hi:[1,0]
	v_pk_mul_f32 v[114:115], v[114:115], v[184:185] op_sel_hi:[1,0]
	v_rcp_f32_e32 v116, v116
	v_rcp_f32_e32 v117, v117
	v_mov_b32_dpp v124, v114 row_shr:2 row_mask:0xf bank_mask:0xf
	v_mov_b32_dpp v125, v115 row_shr:2 row_mask:0xf bank_mask:0xf
	v_mov_b32_dpp v112, v114 row_shr:1 row_mask:0xf bank_mask:0xf
	v_mov_b32_dpp v113, v115 row_shr:1 row_mask:0xf bank_mask:0xf
	v_pk_fma_f32 v[122:123], v[134:135], v[124:125], v[130:131]
	v_pk_mul_f32 v[116:117], v[120:121], v[116:117]
	v_pk_fma_f32 v[112:113], v[142:143], v[112:113], v[122:123]
	v_cvt_pk_bf16_f32 v100, v100, v101
	v_pk_fma_f32 v[112:113], v[114:115], v[146:147], v[112:113]
	v_pk_mul_f32 v[110:111], v[110:111], v[182:183] op_sel_hi:[1,0]
	v_pk_mul_f32 v[112:113], v[112:113], v[116:117]
	v_cvt_pk_bf16_f32 v101, v112, v113
	v_mov_b32_dpp v116, v118 row_ror:2 row_mask:0xf bank_mask:0xf
	v_mov_b32_dpp v117, v119 row_ror:2 row_mask:0xf bank_mask:0xf
	v_mov_b32_dpp v112, v118 row_ror:1 row_mask:0xf bank_mask:0xf
	v_mov_b32_dpp v113, v119 row_ror:1 row_mask:0xf bank_mask:0xf
	v_mov_b32_dpp v116, v110 row_shr:2 row_mask:0xf bank_mask:0xf
	v_mov_b32_dpp v117, v111 row_shr:2 row_mask:0xf bank_mask:0xf
	v_mov_b32_dpp v112, v110 row_shr:1 row_mask:0xf bank_mask:0xf
	v_mov_b32_dpp v113, v111 row_shr:1 row_mask:0xf bank_mask:0xf
	v_pk_fma_f32 v[116:117], v[150:151], v[116:117], v[138:139]
	v_pk_fma_f32 v[112:113], v[154:155], v[112:113], v[116:117]
	v_pk_fma_f32 v[112:113], v[110:111], v[158:159], v[112:113]
	v_pk_mul_f32 v[116:117], v[112:113], s[0:1] op_sel_hi:[1,0]
	v_exp_f32_e32 v116, v116
	v_exp_f32_e32 v117, v117
	v_mov_b32_dpp v118, v114 row_ror:1 row_mask:0xf bank_mask:0xf
	v_mov_b32_dpp v119, v115 row_ror:1 row_mask:0xf bank_mask:0xf
	v_mov_b32_dpp v120, v114 row_ror:2 row_mask:0xf bank_mask:0xf
	v_mov_b32_dpp v121, v115 row_ror:2 row_mask:0xf bank_mask:0xf
	v_pk_add_f32 v[114:115], v[116:117], 1.0 op_sel_hi:[1,0]
	v_pk_mul_f32 v[106:107], v[106:107], v[182:183] op_sel_hi:[1,0]
	v_rcp_f32_e32 v114, v114
	v_rcp_f32_e32 v115, v115
	v_mov_b32_dpp v120, v106 row_shr:2 row_mask:0xf bank_mask:0xf
	v_mov_b32_dpp v121, v107 row_shr:2 row_mask:0xf bank_mask:0xf
	v_mov_b32_dpp v118, v106 row_shr:1 row_mask:0xf bank_mask:0xf
	v_mov_b32_dpp v119, v107 row_shr:1 row_mask:0xf bank_mask:0xf
	v_pk_fma_f32 v[116:117], v[134:135], v[120:121], v[130:131]
	v_pk_mul_f32 v[112:113], v[112:113], v[114:115]
	v_pk_fma_f32 v[116:117], v[142:143], v[118:119], v[116:117]
	v_pk_fma_f32 v[116:117], v[106:107], v[146:147], v[116:117]
	v_pk_mul_f32 v[112:113], v[116:117], v[112:113]
	v_cvt_pk_bf16_f32 v104, v104, v105
	v_pk_mul_f32 v[102:103], v[102:103], v[180:181] op_sel_hi:[1,0]
	v_cvt_pk_bf16_f32 v105, v112, v113
	v_mov_b32_dpp v114, v110 row_ror:2 row_mask:0xf bank_mask:0xf
	v_mov_b32_dpp v115, v111 row_ror:2 row_mask:0xf bank_mask:0xf
	v_mov_b32_dpp v112, v110 row_ror:1 row_mask:0xf bank_mask:0xf
	v_mov_b32_dpp v113, v111 row_ror:1 row_mask:0xf bank_mask:0xf
; #define LAS __attribute__((address_space(3)))
; DI unsigned pk2(float lo, float hi) { f32x2 v = {lo, hi}; bf16x2_t b = __builtin_convertvector(v, bf16x2_t); return __builtin_bit_cast(unsigned, b); }
;     DI void operator()(const AccT& acc, const Unit& u, int wr, int wc, int fr, int fq) const {
;     ...
;                     const f32x2 bg = *(const LAS f32x2*)(P + lc + 2 * jp), g0 = *(const LAS f32x2*)(P + 32 + lc + 2 * jp), g1 = *(const LAS f32x2*)(P + 64 + lc + 2 * jp), g2 = *(const LAS f32x2*)(P + 96 + lc + 2 * jp);
;                     const f32x2 bv = *(const LAS f32x2*)(P + 128 + lc + 2 * jp), v0 = *(const LAS f32x2*)(P + 160 + lc + 2 * jp), v1 = *(const LAS f32x2*)(P + 192 + lc + 2 * jp), v2 = *(const LAS f32x2*)(P + 224 + lc + 2 * jp);
;                     f32x2 G[4], V[4];
; #pragma unroll
;                     for (int m = 0; m < 4; ++m) { G[m] = (f32x2){acc[ai][0][m][n][2 * jp], acc[ai][0][m][n][2 * jp + 1]} * rs[m]; V[m] = (f32x2){acc[ai][1][m][n][2 * jp], acc[ai][1][m][n][2 * jp + 1]} * rs[m]; }
; #pragma unroll
;                     for (int m = 0; m < 4; ++m) {
;                         const f32x2 zz = {0.f, 0.f}; const f32x2 Gp = m ? G[m - 1] : zz, Vp = m ? V[m - 1] : zz;
;                         const f32x2 gp1 = {dpp_prev1(G[m].x, Gp.x), dpp_prev1(G[m].y, Gp.y)}, gp2 = {dpp_prev2(G[m].x, Gp.x), dpp_prev2(G[m].y, Gp.y)};
;                         const f32x2 vp1 = {dpp_prev1(V[m].x, Vp.x), dpp_prev1(V[m].y, Vp.y)}, vp2 = {dpp_prev2(V[m].x, Vp.x), dpp_prev2(V[m].y, Vp.y)};
;                         const f32x2 gc = bg + g0 * gp2 + g1 * gp1 + g2 * G[m];
;                         const f32x2 vc = bv + v0 * vp2 + v1 * vp1 + v2 * V[m];
;                         const f32x2 xe = gc * (-LOG2E);
;                         f32x2 dn = {__builtin_amdgcn_exp2f(xe.x), __builtin_amdgcn_exp2f(xe.y)}; dn = dn + 1.0f;
;                         const f32x2 rc = {__builtin_amdgcn_rcpf(dn.x), __builtin_amdgcn_rcpf(dn.y)};
;                         const f32x2 rr = gc * rc * vc;
;                         wpk[m][jp] = pk2(rr.x, rr.y); }
;                 }
; #pragma unroll
;                 for (int m = 0; m < 4; ++m) { const int row = m ? tok0 + 16 * m : row0;
;                     *(u32x2*)(ACT + (size_t)row * 2816 + cl + 4 * n) = (u32x2){wpk[m][0], wpk[m][1]}; }
	v_mov_b32_dpp v114, v102 row_shr:2 row_mask:0xf bank_mask:0xf
	v_mov_b32_dpp v115, v103 row_shr:2 row_mask:0xf bank_mask:0xf
	v_mov_b32_dpp v112, v102 row_shr:1 row_mask:0xf bank_mask:0xf
	v_mov_b32_dpp v113, v103 row_shr:1 row_mask:0xf bank_mask:0xf
	v_pk_fma_f32 v[114:115], v[150:151], v[114:115], v[138:139]
	v_pk_fma_f32 v[112:113], v[154:155], v[112:113], v[114:115]
	v_pk_fma_f32 v[102:103], v[102:103], v[158:159], v[112:113]
	v_pk_mul_f32 v[112:113], v[102:103], s[0:1] op_sel_hi:[1,0]
	v_exp_f32_e32 v112, v112
	v_exp_f32_e32 v113, v113
	v_mov_b32_dpp v110, v106 row_ror:1 row_mask:0xf bank_mask:0xf
	v_mov_b32_dpp v111, v107 row_ror:1 row_mask:0xf bank_mask:0xf
	v_mov_b32_dpp v116, v106 row_ror:2 row_mask:0xf bank_mask:0xf
	v_mov_b32_dpp v117, v107 row_ror:2 row_mask:0xf bank_mask:0xf
	v_pk_add_f32 v[106:107], v[112:113], 1.0 op_sel_hi:[1,0]
	v_pk_mul_f32 v[98:99], v[98:99], v[180:181] op_sel_hi:[1,0]
	v_rcp_f32_e32 v106, v106
	v_rcp_f32_e32 v107, v107
	v_mov_b32_dpp v116, v98 row_shr:2 row_mask:0xf bank_mask:0xf
	v_mov_b32_dpp v117, v99 row_shr:2 row_mask:0xf bank_mask:0xf
	v_mov_b32_dpp v110, v98 row_shr:1 row_mask:0xf bank_mask:0xf
	v_mov_b32_dpp v111, v99 row_shr:1 row_mask:0xf bank_mask:0xf
	v_pk_fma_f32 v[112:113], v[134:135], v[116:117], v[130:131]
	v_pk_mul_f32 v[102:103], v[102:103], v[106:107]
	v_pk_fma_f32 v[110:111], v[142:143], v[110:111], v[112:113]
	v_mov_b64_e32 v[128:129], s[4:5]
	v_pk_fma_f32 v[98:99], v[98:99], v[146:147], v[110:111]
	v_cvt_pk_bf16_f32 v108, v108, v109
	v_pk_mul_f32 v[98:99], v[98:99], v[102:103]
	v_lshlrev_b64 v[130:131], 1, v[188:189]
	v_cvt_pk_bf16_f32 v109, v98, v99
	v_mad_i64_i32 v[98:99], s[10:11], v208, s48, v[128:129]
	v_lshl_add_u64 v[132:133], v[98:99], 0, v[130:131]
	global_store_dwordx2 v[132:133], v[96:97], off
	v_mad_i64_i32 v[96:97], s[10:11], v205, s48, v[128:129]
	v_lshl_add_u64 v[134:135], v[96:97], 0, v[130:131]
	v_mad_i64_i32 v[96:97], s[10:11], v206, s48, v[128:129]
	v_lshl_add_u64 v[136:137], v[96:97], 0, v[130:131]
	v_mad_i64_i32 v[96:97], s[10:11], v207, s48, v[128:129]
	v_lshl_add_u64 v[138:139], v[96:97], 0, v[130:131]
	global_store_dwordx2 v[134:135], v[100:101], off
	global_store_dwordx2 v[136:137], v[104:105], off
	global_store_dwordx2 v[138:139], v[108:109], off
	v_pk_mul_f32 v[92:93], v[92:93], v[186:187] op_sel_hi:[1,0]
	v_pk_mul_f32 v[142:143], v[68:69], v[180:181] op_sel_hi:[1,0]
	v_mov_b32_e32 v68, v183
	v_mov_b32_e32 v69, v183
	v_pk_mul_f32 v[144:145], v[64:65], v[180:181] op_sel_hi:[1,0]
	v_mov_b32_e32 v64, v181
	v_mov_b32_e32 v65, v181
	v_mov_b32_dpp v68, v92 row_shr:2 row_mask:0xf bank_mask:0xf
	v_mov_b32_dpp v69, v93 row_shr:2 row_mask:0xf bank_mask:0xf
	ds_read_b128 v[104:107], v200 offset:16
	ds_read_b128 v[116:119], v200 offset:144
	ds_read_b128 v[120:123], v200 offset:272
	ds_read_b128 v[124:127], v200 offset:400
	ds_read_b128 v[96:99], v200 offset:528
	ds_read_b128 v[100:103], v200 offset:656
	ds_read_b128 v[108:111], v200 offset:784
	ds_read_b128 v[112:115], v200 offset:912
	v_mov_b32_dpp v64, v92 row_shr:1 row_mask:0xf bank_mask:0xf
	v_mov_b32_dpp v65, v93 row_shr:1 row_mask:0xf bank_mask:0xf
	s_waitcnt lgkmcnt(6)
	v_pk_fma_f32 v[68:69], v[116:117], v[68:69], v[104:105]
	v_pk_mul_f32 v[88:89], v[88:89], v[186:187] op_sel_hi:[1,0]
	s_waitcnt lgkmcnt(5)
	v_pk_fma_f32 v[64:65], v[120:121], v[64:65], v[68:69]
	v_mov_b32_e32 v146, v183
	s_waitcnt lgkmcnt(4)
	v_pk_fma_f32 v[64:65], v[92:93], v[124:125], v[64:65]
	v_mov_b32_e32 v147, v183
	v_pk_mul_f32 v[68:69], v[64:65], s[0:1] op_sel_hi:[1,0]
	v_pk_mul_f32 v[140:141], v[72:73], v[182:183] op_sel_hi:[1,0]
	v_exp_f32_e32 v68, v68
	v_exp_f32_e32 v69, v69
	v_mov_b32_e32 v72, v181
	v_mov_b32_e32 v73, v181
	v_mov_b32_dpp v146, v88 row_shr:2 row_mask:0xf bank_mask:0xf
	v_pk_add_f32 v[68:69], v[68:69], 1.0 op_sel_hi:[1,0]
	v_mov_b32_dpp v147, v89 row_shr:2 row_mask:0xf bank_mask:0xf
	v_rcp_f32_e32 v68, v68
	v_rcp_f32_e32 v69, v69
	v_mov_b32_dpp v72, v88 row_shr:1 row_mask:0xf bank_mask:0xf
	v_mov_b32_dpp v73, v89 row_shr:1 row_mask:0xf bank_mask:0xf
	s_waitcnt lgkmcnt(2)
	v_pk_fma_f32 v[146:147], v[100:101], v[146:147], v[96:97]
	v_pk_mul_f32 v[64:65], v[64:65], v[68:69]
	s_waitcnt lgkmcnt(1)
	v_pk_fma_f32 v[72:73], v[108:109], v[72:73], v[146:147]
	v_pk_mul_f32 v[84:85], v[84:85], v[184:185] op_sel_hi:[1,0]
	s_waitcnt lgkmcnt(0)
; #define LAS __attribute__((address_space(3)))
; DI unsigned pk2(float lo, float hi) { f32x2 v = {lo, hi}; bf16x2_t b = __builtin_convertvector(v, bf16x2_t); return __builtin_bit_cast(unsigned, b); }
;     DI void operator()(const AccT& acc, const Unit& u, int wr, int wc, int fr, int fq) const {
;     ...
;             for (int n = 0; n < 2; ++n) {
;                 const int lc = 8 * fq + 4 * n;
;                 unsigned wpk[4][2];
; #pragma unroll
;                 for (int jp = 0; jp < 2; ++jp) {
;                     const f32x2 bg = *(const LAS f32x2*)(P + lc + 2 * jp), g0 = *(const LAS f32x2*)(P + 32 + lc + 2 * jp), g1 = *(const LAS f32x2*)(P + 64 + lc + 2 * jp), g2 = *(const LAS f32x2*)(P + 96 + lc + 2 * jp);
;                     const f32x2 bv = *(const LAS f32x2*)(P + 128 + lc + 2 * jp), v0 = *(const LAS f32x2*)(P + 160 + lc + 2 * jp), v1 = *(const LAS f32x2*)(P + 192 + lc + 2 * jp), v2 = *(const LAS f32x2*)(P + 224 + lc + 2 * jp);
;                     f32x2 G[4], V[4];
; #pragma unroll
;                     for (int m = 0; m < 4; ++m) { G[m] = (f32x2){acc[ai][0][m][n][2 * jp], acc[ai][0][m][n][2 * jp + 1]} * rs[m]; V[m] = (f32x2){acc[ai][1][m][n][2 * jp], acc[ai][1][m][n][2 * jp + 1]} * rs[m]; }
; #pragma unroll
;                     for (int m = 0; m < 4; ++m) {
;                         const f32x2 zz = {0.f, 0.f}; const f32x2 Gp = m ? G[m - 1] : zz, Vp = m ? V[m - 1] : zz;
;                         const f32x2 gp1 = {dpp_prev1(G[m].x, Gp.x), dpp_prev1(G[m].y, Gp.y)}, gp2 = {dpp_prev2(G[m].x, Gp.x), dpp_prev2(G[m].y, Gp.y)};
;                         const f32x2 vp1 = {dpp_prev1(V[m].x, Vp.x), dpp_prev1(V[m].y, Vp.y)}, vp2 = {dpp_prev2(V[m].x, Vp.x), dpp_prev2(V[m].y, Vp.y)};
;                         const f32x2 gc = bg + g0 * gp2 + g1 * gp1 + g2 * G[m];
;                         const f32x2 vc = bv + v0 * vp2 + v1 * vp1 + v2 * V[m];
;                         const f32x2 xe = gc * (-LOG2E);
;                         f32x2 dn = {__builtin_amdgcn_exp2f(xe.x), __builtin_amdgcn_exp2f(xe.y)}; dn = dn + 1.0f;
;                         const f32x2 rc = {__builtin_amdgcn_rcpf(dn.x), __builtin_amdgcn_rcpf(dn.y)};
;                         const f32x2 rr = gc * rc * vc;
;                         wpk[m][jp] = pk2(rr.x, rr.y); }
	v_pk_fma_f32 v[72:73], v[88:89], v[112:113], v[72:73]
	v_pk_mul_f32 v[64:65], v[72:73], v[64:65]
	v_mov_b32_dpp v72, v92 row_ror:2 row_mask:0xf bank_mask:0xf
	v_mov_b32_dpp v73, v93 row_ror:2 row_mask:0xf bank_mask:0xf
	v_mov_b32_dpp v68, v92 row_ror:1 row_mask:0xf bank_mask:0xf
	v_mov_b32_dpp v69, v93 row_ror:1 row_mask:0xf bank_mask:0xf
	v_mov_b32_dpp v72, v84 row_shr:2 row_mask:0xf bank_mask:0xf
	v_mov_b32_dpp v73, v85 row_shr:2 row_mask:0xf bank_mask:0xf
	v_mov_b32_dpp v68, v84 row_shr:1 row_mask:0xf bank_mask:0xf
	v_mov_b32_dpp v69, v85 row_shr:1 row_mask:0xf bank_mask:0xf
	v_pk_fma_f32 v[72:73], v[116:117], v[72:73], v[104:105]
	v_pk_fma_f32 v[68:69], v[120:121], v[68:69], v[72:73]
	v_pk_fma_f32 v[68:69], v[84:85], v[124:125], v[68:69]
	v_pk_mul_f32 v[80:81], v[80:81], v[184:185] op_sel_hi:[1,0]
	v_pk_mul_f32 v[72:73], v[68:69], s[0:1] op_sel_hi:[1,0]
	v_exp_f32_e32 v72, v72
	v_exp_f32_e32 v73, v73
	v_mov_b32_dpp v146, v88 row_ror:2 row_mask:0xf bank_mask:0xf
	v_mov_b32_dpp v147, v89 row_ror:2 row_mask:0xf bank_mask:0xf
	v_pk_add_f32 v[72:73], v[72:73], 1.0 op_sel_hi:[1,0]
	v_mov_b32_dpp v92, v88 row_ror:1 row_mask:0xf bank_mask:0xf
	v_rcp_f32_e32 v72, v72
	v_rcp_f32_e32 v73, v73
	v_mov_b32_dpp v93, v89 row_ror:1 row_mask:0xf bank_mask:0xf
	v_mov_b32_dpp v146, v80 row_shr:2 row_mask:0xf bank_mask:0xf
	v_mov_b32_dpp v147, v81 row_shr:2 row_mask:0xf bank_mask:0xf
	v_mov_b32_dpp v92, v80 row_shr:1 row_mask:0xf bank_mask:0xf
	v_mov_b32_dpp v93, v81 row_shr:1 row_mask:0xf bank_mask:0xf
	v_pk_fma_f32 v[88:89], v[100:101], v[146:147], v[96:97]
	v_pk_mul_f32 v[68:69], v[68:69], v[72:73]
	v_pk_fma_f32 v[88:89], v[108:109], v[92:93], v[88:89]
	v_pk_mul_f32 v[76:77], v[76:77], v[182:183] op_sel_hi:[1,0]
	v_pk_fma_f32 v[88:89], v[80:81], v[112:113], v[88:89]
	v_pk_mul_f32 v[68:69], v[88:89], v[68:69]
	v_mov_b32_dpp v88, v84 row_ror:2 row_mask:0xf bank_mask:0xf
	v_mov_b32_dpp v89, v85 row_ror:2 row_mask:0xf bank_mask:0xf
	v_mov_b32_dpp v72, v84 row_ror:1 row_mask:0xf bank_mask:0xf
	v_mov_b32_dpp v73, v85 row_ror:1 row_mask:0xf bank_mask:0xf
	v_mov_b32_dpp v88, v76 row_shr:2 row_mask:0xf bank_mask:0xf
	v_mov_b32_dpp v89, v77 row_shr:2 row_mask:0xf bank_mask:0xf
	v_mov_b32_dpp v72, v76 row_shr:1 row_mask:0xf bank_mask:0xf
	v_mov_b32_dpp v73, v77 row_shr:1 row_mask:0xf bank_mask:0xf
	v_pk_fma_f32 v[88:89], v[116:117], v[88:89], v[104:105]
	v_pk_fma_f32 v[72:73], v[120:121], v[72:73], v[88:89]
	v_pk_fma_f32 v[72:73], v[76:77], v[124:125], v[72:73]
	v_pk_mul_f32 v[88:89], v[72:73], s[0:1] op_sel_hi:[1,0]
	v_exp_f32_e32 v88, v88
	v_exp_f32_e32 v89, v89
	v_mov_b32_dpp v84, v80 row_ror:1 row_mask:0xf bank_mask:0xf
	v_mov_b32_dpp v85, v81 row_ror:1 row_mask:0xf bank_mask:0xf
	v_mov_b32_dpp v92, v80 row_ror:2 row_mask:0xf bank_mask:0xf
	v_mov_b32_dpp v93, v81 row_ror:2 row_mask:0xf bank_mask:0xf
	v_pk_add_f32 v[80:81], v[88:89], 1.0 op_sel_hi:[1,0]
	v_mov_b32_dpp v92, v140 row_shr:2 row_mask:0xf bank_mask:0xf
	v_rcp_f32_e32 v80, v80
	v_rcp_f32_e32 v81, v81
	v_mov_b32_dpp v93, v141 row_shr:2 row_mask:0xf bank_mask:0xf
	v_mov_b32_dpp v84, v140 row_shr:1 row_mask:0xf bank_mask:0xf
	v_mov_b32_dpp v85, v141 row_shr:1 row_mask:0xf bank_mask:0xf
	v_pk_fma_f32 v[88:89], v[100:101], v[92:93], v[96:97]
	v_pk_mul_f32 v[72:73], v[72:73], v[80:81]
	v_pk_fma_f32 v[84:85], v[108:109], v[84:85], v[88:89]
	v_pk_fma_f32 v[84:85], v[140:141], v[112:113], v[84:85]
	v_pk_mul_f32 v[72:73], v[84:85], v[72:73]
	v_mov_b32_dpp v80, v76 row_ror:1 row_mask:0xf bank_mask:0xf
	v_mov_b32_dpp v84, v76 row_ror:2 row_mask:0xf bank_mask:0xf
	v_mov_b32_dpp v85, v77 row_ror:2 row_mask:0xf bank_mask:0xf
	v_mov_b32_dpp v81, v77 row_ror:1 row_mask:0xf bank_mask:0xf
	v_mov_b32_dpp v84, v142 row_shr:2 row_mask:0xf bank_mask:0xf
	v_mov_b32_dpp v85, v143 row_shr:2 row_mask:0xf bank_mask:0xf
	v_mov_b32_dpp v80, v142 row_shr:1 row_mask:0xf bank_mask:0xf
	v_mov_b32_dpp v81, v143 row_shr:1 row_mask:0xf bank_mask:0xf
	v_pk_fma_f32 v[84:85], v[116:117], v[84:85], v[104:105]
	v_pk_fma_f32 v[80:81], v[120:121], v[80:81], v[84:85]
	v_pk_fma_f32 v[80:81], v[142:143], v[124:125], v[80:81]
	v_pk_mul_f32 v[84:85], v[80:81], s[0:1] op_sel_hi:[1,0]
	v_exp_f32_e32 v84, v84
	v_exp_f32_e32 v85, v85
	v_mov_b32_dpp v88, v140 row_ror:2 row_mask:0xf bank_mask:0xf
	v_mov_b32_dpp v89, v141 row_ror:2 row_mask:0xf bank_mask:0xf
	v_mov_b32_dpp v76, v140 row_ror:1 row_mask:0xf bank_mask:0xf
	v_pk_add_f32 v[84:85], v[84:85], 1.0 op_sel_hi:[1,0]
	v_mov_b32_dpp v77, v141 row_ror:1 row_mask:0xf bank_mask:0xf
	v_rcp_f32_e32 v84, v84
	v_rcp_f32_e32 v85, v85
	v_mov_b32_dpp v88, v144 row_shr:2 row_mask:0xf bank_mask:0xf
	v_mov_b32_dpp v89, v145 row_shr:2 row_mask:0xf bank_mask:0xf
	v_mov_b32_dpp v76, v144 row_shr:1 row_mask:0xf bank_mask:0xf
	v_mov_b32_dpp v77, v145 row_shr:1 row_mask:0xf bank_mask:0xf
	v_pk_fma_f32 v[88:89], v[100:101], v[88:89], v[96:97]
	v_pk_mul_f32 v[80:81], v[80:81], v[84:85]
	v_pk_fma_f32 v[76:77], v[108:109], v[76:77], v[88:89]
	v_pk_mul_f32 v[84:85], v[90:91], v[186:187] op_sel_hi:[1,0]
	v_pk_fma_f32 v[76:77], v[144:145], v[112:113], v[76:77]
	v_mov_b32_e32 v90, v183
	v_pk_mul_f32 v[76:77], v[76:77], v[80:81]
	v_pk_mul_f32 v[80:81], v[94:95], v[186:187] op_sel_hi:[1,0]
	v_mov_b32_e32 v91, v183
	v_mov_b32_e32 v88, v181
	v_mov_b32_e32 v89, v181
	v_mov_b32_dpp v90, v80 row_shr:2 row_mask:0xf bank_mask:0xf
	v_mov_b32_dpp v91, v81 row_shr:2 row_mask:0xf bank_mask:0xf
	v_mov_b32_dpp v88, v80 row_shr:1 row_mask:0xf bank_mask:0xf
	v_mov_b32_dpp v89, v81 row_shr:1 row_mask:0xf bank_mask:0xf
	v_pk_fma_f32 v[90:91], v[118:119], v[90:91], v[106:107]
	v_mov_b32_e32 v94, v183
	v_pk_fma_f32 v[88:89], v[122:123], v[88:89], v[90:91]
; #define LAS __attribute__((address_space(3)))
; DI unsigned pk2(float lo, float hi) { f32x2 v = {lo, hi}; bf16x2_t b = __builtin_convertvector(v, bf16x2_t); return __builtin_bit_cast(unsigned, b); }
;     DI void operator()(const AccT& acc, const Unit& u, int wr, int wc, int fr, int fq) const {
;     ...
;                     const f32x2 bg = *(const LAS f32x2*)(P + lc + 2 * jp), g0 = *(const LAS f32x2*)(P + 32 + lc + 2 * jp), g1 = *(const LAS f32x2*)(P + 64 + lc + 2 * jp), g2 = *(const LAS f32x2*)(P + 96 + lc + 2 * jp);
;                     const f32x2 bv = *(const LAS f32x2*)(P + 128 + lc + 2 * jp), v0 = *(const LAS f32x2*)(P + 160 + lc + 2 * jp), v1 = *(const LAS f32x2*)(P + 192 + lc + 2 * jp), v2 = *(const LAS f32x2*)(P + 224 + lc + 2 * jp);
;                     f32x2 G[4], V[4];
; #pragma unroll
;                     for (int m = 0; m < 4; ++m) { G[m] = (f32x2){acc[ai][0][m][n][2 * jp], acc[ai][0][m][n][2 * jp + 1]} * rs[m]; V[m] = (f32x2){acc[ai][1][m][n][2 * jp], acc[ai][1][m][n][2 * jp + 1]} * rs[m]; }
; #pragma unroll
;                     for (int m = 0; m < 4; ++m) {
;                         const f32x2 zz = {0.f, 0.f}; const f32x2 Gp = m ? G[m - 1] : zz, Vp = m ? V[m - 1] : zz;
;                         const f32x2 gp1 = {dpp_prev1(G[m].x, Gp.x), dpp_prev1(G[m].y, Gp.y)}, gp2 = {dpp_prev2(G[m].x, Gp.x), dpp_prev2(G[m].y, Gp.y)};
;                         const f32x2 vp1 = {dpp_prev1(V[m].x, Vp.x), dpp_prev1(V[m].y, Vp.y)}, vp2 = {dpp_prev2(V[m].x, Vp.x), dpp_prev2(V[m].y, Vp.y)};
;                         const f32x2 gc = bg + g0 * gp2 + g1 * gp1 + g2 * G[m];
;                         const f32x2 vc = bv + v0 * vp2 + v1 * vp1 + v2 * V[m];
;                         const f32x2 xe = gc * (-LOG2E);
;                         f32x2 dn = {__builtin_amdgcn_exp2f(xe.x), __builtin_amdgcn_exp2f(xe.y)}; dn = dn + 1.0f;
;                         const f32x2 rc = {__builtin_amdgcn_rcpf(dn.x), __builtin_amdgcn_rcpf(dn.y)};
;                         const f32x2 rr = gc * rc * vc;
;                         wpk[m][jp] = pk2(rr.x, rr.y); }
	v_mov_b32_e32 v95, v183
	v_pk_fma_f32 v[88:89], v[80:81], v[126:127], v[88:89]
	v_mov_b32_e32 v92, v181
	v_pk_mul_f32 v[90:91], v[88:89], s[0:1] op_sel_hi:[1,0]
	v_mov_b32_e32 v93, v181
	v_exp_f32_e32 v90, v90
	v_exp_f32_e32 v91, v91
	v_mov_b32_dpp v94, v84 row_shr:2 row_mask:0xf bank_mask:0xf
	v_mov_b32_dpp v95, v85 row_shr:2 row_mask:0xf bank_mask:0xf
	v_mov_b32_dpp v92, v84 row_shr:1 row_mask:0xf bank_mask:0xf
	v_pk_add_f32 v[90:91], v[90:91], 1.0 op_sel_hi:[1,0]
	v_mov_b32_dpp v93, v85 row_shr:1 row_mask:0xf bank_mask:0xf
	v_rcp_f32_e32 v90, v90
	v_rcp_f32_e32 v91, v91
	v_pk_fma_f32 v[94:95], v[102:103], v[94:95], v[98:99]
	v_cvt_pk_bf16_f32 v64, v64, v65
	v_pk_fma_f32 v[92:93], v[110:111], v[92:93], v[94:95]
	v_pk_mul_f32 v[88:89], v[88:89], v[90:91]
	v_pk_fma_f32 v[92:93], v[84:85], v[114:115], v[92:93]
	v_pk_mul_f32 v[88:89], v[92:93], v[88:89]
	v_pk_mul_f32 v[86:87], v[86:87], v[184:185] op_sel_hi:[1,0]
	v_cvt_pk_bf16_f32 v65, v88, v89
	v_mov_b32_dpp v90, v80 row_ror:2 row_mask:0xf bank_mask:0xf
	v_mov_b32_dpp v91, v81 row_ror:2 row_mask:0xf bank_mask:0xf
	v_mov_b32_dpp v88, v80 row_ror:1 row_mask:0xf bank_mask:0xf
	v_mov_b32_dpp v89, v81 row_ror:1 row_mask:0xf bank_mask:0xf
	v_mov_b32_dpp v90, v86 row_shr:2 row_mask:0xf bank_mask:0xf
	v_mov_b32_dpp v91, v87 row_shr:2 row_mask:0xf bank_mask:0xf
	v_mov_b32_dpp v88, v86 row_shr:1 row_mask:0xf bank_mask:0xf
	v_mov_b32_dpp v89, v87 row_shr:1 row_mask:0xf bank_mask:0xf
	v_pk_fma_f32 v[90:91], v[118:119], v[90:91], v[106:107]
	v_pk_fma_f32 v[88:89], v[122:123], v[88:89], v[90:91]
	v_pk_fma_f32 v[88:89], v[86:87], v[126:127], v[88:89]
	v_pk_mul_f32 v[90:91], v[88:89], s[0:1] op_sel_hi:[1,0]
	v_exp_f32_e32 v90, v90
	v_exp_f32_e32 v91, v91
	v_mov_b32_dpp v80, v84 row_ror:1 row_mask:0xf bank_mask:0xf
	v_mov_b32_dpp v81, v85 row_ror:1 row_mask:0xf bank_mask:0xf
	v_mov_b32_dpp v92, v84 row_ror:2 row_mask:0xf bank_mask:0xf
	v_mov_b32_dpp v93, v85 row_ror:2 row_mask:0xf bank_mask:0xf
	v_pk_add_f32 v[84:85], v[90:91], 1.0 op_sel_hi:[1,0]
	v_pk_mul_f32 v[82:83], v[82:83], v[184:185] op_sel_hi:[1,0]
	v_rcp_f32_e32 v84, v84
	v_rcp_f32_e32 v85, v85
	v_mov_b32_dpp v92, v82 row_shr:2 row_mask:0xf bank_mask:0xf
	v_mov_b32_dpp v93, v83 row_shr:2 row_mask:0xf bank_mask:0xf
	v_mov_b32_dpp v80, v82 row_shr:1 row_mask:0xf bank_mask:0xf
	v_mov_b32_dpp v81, v83 row_shr:1 row_mask:0xf bank_mask:0xf
	v_pk_fma_f32 v[90:91], v[102:103], v[92:93], v[98:99]
	v_pk_mul_f32 v[84:85], v[88:89], v[84:85]
	v_pk_fma_f32 v[80:81], v[110:111], v[80:81], v[90:91]
	v_cvt_pk_bf16_f32 v68, v68, v69
	v_pk_fma_f32 v[80:81], v[82:83], v[114:115], v[80:81]
	v_pk_mul_f32 v[78:79], v[78:79], v[182:183] op_sel_hi:[1,0]
	v_pk_mul_f32 v[80:81], v[80:81], v[84:85]
	v_cvt_pk_bf16_f32 v69, v80, v81
	v_mov_b32_dpp v84, v86 row_ror:2 row_mask:0xf bank_mask:0xf
	v_mov_b32_dpp v85, v87 row_ror:2 row_mask:0xf bank_mask:0xf
	v_mov_b32_dpp v80, v86 row_ror:1 row_mask:0xf bank_mask:0xf
	v_mov_b32_dpp v81, v87 row_ror:1 row_mask:0xf bank_mask:0xf
	v_mov_b32_dpp v84, v78 row_shr:2 row_mask:0xf bank_mask:0xf
	v_mov_b32_dpp v85, v79 row_shr:2 row_mask:0xf bank_mask:0xf
	v_mov_b32_dpp v80, v78 row_shr:1 row_mask:0xf bank_mask:0xf
	v_mov_b32_dpp v81, v79 row_shr:1 row_mask:0xf bank_mask:0xf
	v_pk_fma_f32 v[84:85], v[118:119], v[84:85], v[106:107]
	v_pk_fma_f32 v[80:81], v[122:123], v[80:81], v[84:85]
	v_pk_fma_f32 v[80:81], v[78:79], v[126:127], v[80:81]
	v_pk_mul_f32 v[84:85], v[80:81], s[0:1] op_sel_hi:[1,0]
	v_exp_f32_e32 v84, v84
	v_exp_f32_e32 v85, v85
	v_mov_b32_dpp v86, v82 row_ror:1 row_mask:0xf bank_mask:0xf
	v_mov_b32_dpp v87, v83 row_ror:1 row_mask:0xf bank_mask:0xf
	v_mov_b32_dpp v88, v82 row_ror:2 row_mask:0xf bank_mask:0xf
	v_mov_b32_dpp v89, v83 row_ror:2 row_mask:0xf bank_mask:0xf
	v_pk_add_f32 v[82:83], v[84:85], 1.0 op_sel_hi:[1,0]
	v_pk_mul_f32 v[74:75], v[74:75], v[182:183] op_sel_hi:[1,0]
	v_rcp_f32_e32 v82, v82
	v_rcp_f32_e32 v83, v83
	v_mov_b32_dpp v88, v74 row_shr:2 row_mask:0xf bank_mask:0xf
	v_mov_b32_dpp v89, v75 row_shr:2 row_mask:0xf bank_mask:0xf
	v_mov_b32_dpp v86, v74 row_shr:1 row_mask:0xf bank_mask:0xf
	v_mov_b32_dpp v87, v75 row_shr:1 row_mask:0xf bank_mask:0xf
	v_pk_fma_f32 v[84:85], v[102:103], v[88:89], v[98:99]
	v_pk_mul_f32 v[80:81], v[80:81], v[82:83]
	v_pk_fma_f32 v[84:85], v[110:111], v[86:87], v[84:85]
	v_pk_fma_f32 v[84:85], v[74:75], v[114:115], v[84:85]
	v_pk_mul_f32 v[80:81], v[84:85], v[80:81]
	v_cvt_pk_bf16_f32 v72, v72, v73
	v_pk_mul_f32 v[70:71], v[70:71], v[180:181] op_sel_hi:[1,0]
	v_cvt_pk_bf16_f32 v73, v80, v81
	v_mov_b32_dpp v82, v78 row_ror:2 row_mask:0xf bank_mask:0xf
	v_mov_b32_dpp v83, v79 row_ror:2 row_mask:0xf bank_mask:0xf
	v_mov_b32_dpp v80, v78 row_ror:1 row_mask:0xf bank_mask:0xf
	v_mov_b32_dpp v81, v79 row_ror:1 row_mask:0xf bank_mask:0xf
	v_mov_b32_dpp v82, v70 row_shr:2 row_mask:0xf bank_mask:0xf
	v_mov_b32_dpp v83, v71 row_shr:2 row_mask:0xf bank_mask:0xf
	v_mov_b32_dpp v80, v70 row_shr:1 row_mask:0xf bank_mask:0xf
	v_mov_b32_dpp v81, v71 row_shr:1 row_mask:0xf bank_mask:0xf
	v_pk_fma_f32 v[82:83], v[118:119], v[82:83], v[106:107]
	v_pk_fma_f32 v[80:81], v[122:123], v[80:81], v[82:83]
	v_pk_fma_f32 v[70:71], v[70:71], v[126:127], v[80:81]
	v_pk_mul_f32 v[80:81], v[70:71], s[0:1] op_sel_hi:[1,0]
	v_exp_f32_e32 v80, v80
	v_exp_f32_e32 v81, v81
	v_mov_b32_dpp v78, v74 row_ror:1 row_mask:0xf bank_mask:0xf
	v_mov_b32_dpp v79, v75 row_ror:1 row_mask:0xf bank_mask:0xf
	v_mov_b32_dpp v84, v74 row_ror:2 row_mask:0xf bank_mask:0xf
	v_mov_b32_dpp v85, v75 row_ror:2 row_mask:0xf bank_mask:0xf
	v_pk_add_f32 v[74:75], v[80:81], 1.0 op_sel_hi:[1,0]
	v_pk_mul_f32 v[66:67], v[66:67], v[180:181] op_sel_hi:[1,0]
;     DI void operator()(const AccT& acc, const Unit& u, int wr, int wc, int fr, int fq) const {
;     ...
;             for (int m = 0; m < 4; ++m) { const int t = tok0 + 16 * m; const int tc = t < 0 ? 0 : (t >= S ? S - 1 : t); const float r = rs_from_ss(rowss[tc]); rs[m] = t < 0 ? 0.f : r; }
;             const int row0 = fr < 2 ? (S + 236 + fr) : tok0;
; #pragma unroll
;             for (int n = 0; n < 2; ++n) {
;                 const int lc = 8 * fq + 4 * n;
;                 unsigned wpk[4][2];
; #pragma unroll
;                 for (int jp = 0; jp < 2; ++jp) {
;                     const f32x2 bg = *(const LAS f32x2*)(P + lc + 2 * jp), g0 = *(const LAS f32x2*)(P + 32 + lc + 2 * jp), g1 = *(const LAS f32x2*)(P + 64 + lc + 2 * jp), g2 = *(const LAS f32x2*)(P + 96 + lc + 2 * jp);
;                     const f32x2 bv = *(const LAS f32x2*)(P + 128 + lc + 2 * jp), v0 = *(const LAS f32x2*)(P + 160 + lc + 2 * jp), v1 = *(const LAS f32x2*)(P + 192 + lc + 2 * jp), v2 = *(const LAS f32x2*)(P + 224 + lc + 2 * jp);
;                     f32x2 G[4], V[4];
; #pragma unroll
;                     for (int m = 0; m < 4; ++m) { G[m] = (f32x2){acc[ai][0][m][n][2 * jp], acc[ai][0][m][n][2 * jp + 1]} * rs[m]; V[m] = (f32x2){acc[ai][1][m][n][2 * jp], acc[ai][1][m][n][2 * jp + 1]} * rs[m]; }
; #pragma unroll
;                     for (int m = 0; m < 4; ++m) {
;                         const f32x2 zz = {0.f, 0.f}; const f32x2 Gp = m ? G[m - 1] : zz, Vp = m ? V[m - 1] : zz;
;                         const f32x2 gp1 = {dpp_prev1(G[m].x, Gp.x), dpp_prev1(G[m].y, Gp.y)}, gp2 = {dpp_prev2(G[m].x, Gp.x), dpp_prev2(G[m].y, Gp.y)};
;                         const f32x2 vp1 = {dpp_prev1(V[m].x, Vp.x), dpp_prev1(V[m].y, Vp.y)}, vp2 = {dpp_prev2(V[m].x, Vp.x), dpp_prev2(V[m].y, Vp.y)};
;                         const f32x2 gc = bg + g0 * gp2 + g1 * gp1 + g2 * G[m];
;                         const f32x2 vc = bv + v0 * vp2 + v1 * vp1 + v2 * V[m];
;                         const f32x2 xe = gc * (-LOG2E);
;                         f32x2 dn = {__builtin_amdgcn_exp2f(xe.x), __builtin_amdgcn_exp2f(xe.y)}; dn = dn + 1.0f;
;                         const f32x2 rc = {__builtin_amdgcn_rcpf(dn.x), __builtin_amdgcn_rcpf(dn.y)};
;                         const f32x2 rr = gc * rc * vc;
;                         wpk[m][jp] = pk2(rr.x, rr.y); }
;                 }
; #pragma unroll
	v_rcp_f32_e32 v74, v74
	v_rcp_f32_e32 v75, v75
	v_mov_b32_dpp v84, v66 row_shr:2 row_mask:0xf bank_mask:0xf
	v_mov_b32_dpp v85, v67 row_shr:2 row_mask:0xf bank_mask:0xf
	v_mov_b32_dpp v78, v66 row_shr:1 row_mask:0xf bank_mask:0xf
	v_mov_b32_dpp v79, v67 row_shr:1 row_mask:0xf bank_mask:0xf
	v_pk_fma_f32 v[80:81], v[102:103], v[84:85], v[98:99]
	v_pk_mul_f32 v[70:71], v[70:71], v[74:75]
	v_pk_fma_f32 v[78:79], v[110:111], v[78:79], v[80:81]
	v_cvt_pk_bf16_f32 v76, v76, v77
	v_pk_fma_f32 v[66:67], v[66:67], v[114:115], v[78:79]
	s_nop 0
	v_pk_mul_f32 v[66:67], v[66:67], v[70:71]
	s_nop 0
	v_cvt_pk_bf16_f32 v77, v66, v67
	global_store_dwordx2 v[132:133], v[64:65], off offset:8
	global_store_dwordx2 v[134:135], v[68:69], off offset:8
	global_store_dwordx2 v[136:137], v[72:73], off offset:8
	global_store_dwordx2 v[138:139], v[76:77], off offset:8
	v_add_u32_e32 v96, 0x7c, v204
	v_med3_i32 v64, v96, 0, s51
	v_add_u32_e32 v97, 0x8c, v204
	v_add_u32_e32 v99, 0x9c, v204
	v_add_u32_e32 v101, 0xac, v204
	v_lshlrev_b32_e32 v64, 3, v64
	v_med3_i32 v65, v97, 0, s51
	v_med3_i32 v66, v99, 0, s51
	v_med3_i32 v67, v101, 0, s51
	v_lshlrev_b32_e32 v65, 3, v65
	v_lshlrev_b32_e32 v66, 3, v66
	v_lshlrev_b32_e32 v67, 3, v67
	v_cndmask_b32_e64 v103, v96, v190, s[6:7]
	v_mov_b32_e32 v112, v181
	v_mov_b32_e32 v113, v181
	ds_read_b128 v[72:75], v200
	ds_read_b128 v[84:87], v200 offset:128
	ds_read_b128 v[88:91], v200 offset:256
	ds_read_b128 v[92:95], v200 offset:384
	ds_read_b128 v[64:67], v200 offset:512
	ds_read_b128 v[68:71], v200 offset:640
	ds_read_b128 v[76:79], v200 offset:768
	ds_read_b128 v[80:83], v200 offset:896
	s_waitcnt vmcnt(8)
	v_mov_b32_e32 v104, v242
	v_mov_b32_e32 v105, v243
	v_mov_b32_e32 v106, v244
	v_mov_b32_e32 v107, v245
	v_mov_b32_e32 v108, v246
	v_mov_b32_e32 v109, v247
	v_mov_b32_e32 v110, v248
	v_mov_b32_e32 v111, v249
	v_ffbh_u32_e32 v98, v105
	v_ffbh_u32_e32 v100, v107
	v_ffbh_u32_e32 v102, v109
	v_min_u32_e32 v98, 32, v98
	v_min_u32_e32 v100, 32, v100
	v_min_u32_e32 v102, 32, v102
	v_lshlrev_b64 v[104:105], v98, v[104:105]
	v_ffbh_u32_e32 v114, v111
	v_lshlrev_b64 v[106:107], v100, v[106:107]
	v_lshlrev_b64 v[108:109], v102, v[108:109]
	v_min_u32_e32 v104, 1, v104
	v_min_u32_e32 v114, 32, v114
	v_min_u32_e32 v106, 1, v106
	v_min_u32_e32 v108, 1, v108
	v_or_b32_e32 v104, v105, v104
	v_lshlrev_b64 v[110:111], v114, v[110:111]
	v_or_b32_e32 v105, v107, v106
	v_or_b32_e32 v106, v109, v108
	v_cvt_f32_u32_e32 v104, v104
	v_min_u32_e32 v110, 1, v110
	v_cvt_f32_u32_e32 v105, v105
	v_cvt_f32_u32_e32 v106, v106
	v_or_b32_e32 v107, v111, v110
	v_sub_u32_e32 v98, 32, v98
	v_cvt_f32_u32_e32 v107, v107
	v_sub_u32_e32 v100, 32, v100
	v_sub_u32_e32 v102, 32, v102
	v_ldexp_f32 v98, v104, v98
	v_ldexp_f32 v100, v105, v100
	v_ldexp_f32 v102, v106, v102
	v_fmamk_f32 v98, v98, 0x30800000, v203
	v_sub_u32_e32 v114, 32, v114
	v_fmamk_f32 v100, v100, 0x30800000, v203
	v_fmamk_f32 v102, v102, 0x30800000, v203
	v_mul_f32_e32 v105, 0x4b800000, v98
	v_cmp_gt_f32_e32 vcc, s52, v98
	v_ldexp_f32 v104, v107, v114
	v_mul_f32_e32 v106, 0x4b800000, v100
	v_mul_f32_e32 v107, 0x4b800000, v102
	v_cndmask_b32_e32 v98, v98, v105, vcc
	v_cmp_gt_f32_e64 s[10:11], s52, v100
	v_cmp_gt_f32_e64 s[12:13], s52, v102
	v_fmamk_f32 v104, v104, 0x30800000, v203
	v_cndmask_b32_e64 v100, v100, v106, s[10:11]
	v_cndmask_b32_e64 v102, v102, v107, s[12:13]
	v_rsq_f32_e32 v98, v98
	v_mul_f32_e32 v108, 0x4b800000, v104
	v_cmp_gt_f32_e64 s[14:15], s52, v104
	v_rsq_f32_e32 v100, v100
	v_rsq_f32_e32 v102, v102
	v_cndmask_b32_e64 v104, v104, v108, s[14:15]
	v_rsq_f32_e32 v104, v104
	v_mul_f32_e32 v105, 0x45800000, v98
	v_mul_f32_e32 v106, 0x45800000, v100
	v_mul_f32_e32 v107, 0x45800000, v102
	v_cndmask_b32_e32 v98, v98, v105, vcc
	v_cmp_lt_i32_e32 vcc, -1, v96
	v_cndmask_b32_e64 v100, v100, v106, s[10:11]
	v_cndmask_b32_e64 v105, v102, v107, s[12:13]
	v_cndmask_b32_e32 v102, 0, v98, vcc
	v_cmp_lt_i32_e32 vcc, s53, v96
	v_mul_f32_e32 v108, 0x45800000, v104
	v_cndmask_b32_e64 v104, v104, v108, s[14:15]
	v_cndmask_b32_e32 v100, 0, v100, vcc
	v_cmp_lt_i32_e32 vcc, s54, v96
	v_pk_mul_f32 v[60:61], v[60:61], v[102:103] op_sel_hi:[1,0]
	v_pk_mul_f32 v[56:57], v[56:57], v[102:103] op_sel_hi:[1,0]
	v_cndmask_b32_e32 v98, 0, v105, vcc
	v_cmp_lt_i32_e32 vcc, s55, v96
	v_mov_b32_dpp v112, v60 row_shr:1 row_mask:0xf bank_mask:0xf
	v_mov_b32_dpp v113, v61 row_shr:1 row_mask:0xf bank_mask:0xf
	v_cndmask_b32_e32 v96, 0, v104, vcc
	v_pk_mul_f32 v[108:109], v[32:33], v[96:97] op_sel_hi:[1,0]
	v_mov_b32_e32 v32, v183
	v_mov_b32_e32 v33, v183
	v_pk_mul_f32 v[104:105], v[40:41], v[98:99] op_sel_hi:[1,0]
	v_mov_b32_dpp v32, v60 row_shr:2 row_mask:0xf bank_mask:0xf
	v_mov_b32_dpp v33, v61 row_shr:2 row_mask:0xf bank_mask:0xf
	s_waitcnt lgkmcnt(6)
	v_pk_fma_f32 v[32:33], v[84:85], v[32:33], v[72:73]
	v_mov_b32_e32 v40, v183
	s_waitcnt lgkmcnt(5)
	v_pk_fma_f32 v[32:33], v[88:89], v[112:113], v[32:33]
	v_mov_b32_e32 v41, v183
	s_waitcnt lgkmcnt(4)
	v_pk_fma_f32 v[32:33], v[92:93], v[60:61], v[32:33]
	v_pk_mul_f32 v[106:107], v[36:37], v[96:97] op_sel_hi:[1,0]
	v_pk_mul_f32 v[110:111], v[32:33], s[0:1] op_sel_hi:[1,0]
	v_mov_b32_e32 v36, v181
	v_exp_f32_e32 v110, v110
	v_exp_f32_e32 v111, v111
	v_mov_b32_e32 v37, v181
	v_mov_b32_dpp v40, v56 row_shr:2 row_mask:0xf bank_mask:0xf
	v_mov_b32_dpp v41, v57 row_shr:2 row_mask:0xf bank_mask:0xf
	v_pk_add_f32 v[110:111], v[110:111], 1.0 op_sel_hi:[1,0]
	v_mov_b32_dpp v36, v56 row_shr:1 row_mask:0xf bank_mask:0xf
	v_rcp_f32_e32 v110, v110
	v_rcp_f32_e32 v111, v111
	v_mov_b32_dpp v37, v57 row_shr:1 row_mask:0xf bank_mask:0xf
	s_waitcnt lgkmcnt(2)
; #define LAS __attribute__((address_space(3)))
; DI unsigned pk2(float lo, float hi) { f32x2 v = {lo, hi}; bf16x2_t b = __builtin_convertvector(v, bf16x2_t); return __builtin_bit_cast(unsigned, b); }
;     DI void operator()(const AccT& acc, const Unit& u, int wr, int wc, int fr, int fq) const {
;     ...
;                     const f32x2 bg = *(const LAS f32x2*)(P + lc + 2 * jp), g0 = *(const LAS f32x2*)(P + 32 + lc + 2 * jp), g1 = *(const LAS f32x2*)(P + 64 + lc + 2 * jp), g2 = *(const LAS f32x2*)(P + 96 + lc + 2 * jp);
;                     const f32x2 bv = *(const LAS f32x2*)(P + 128 + lc + 2 * jp), v0 = *(const LAS f32x2*)(P + 160 + lc + 2 * jp), v1 = *(const LAS f32x2*)(P + 192 + lc + 2 * jp), v2 = *(const LAS f32x2*)(P + 224 + lc + 2 * jp);
;                     f32x2 G[4], V[4];
; #pragma unroll
;                     for (int m = 0; m < 4; ++m) { G[m] = (f32x2){acc[ai][0][m][n][2 * jp], acc[ai][0][m][n][2 * jp + 1]} * rs[m]; V[m] = (f32x2){acc[ai][1][m][n][2 * jp], acc[ai][1][m][n][2 * jp + 1]} * rs[m]; }
; #pragma unroll
;                     for (int m = 0; m < 4; ++m) {
;                         const f32x2 zz = {0.f, 0.f}; const f32x2 Gp = m ? G[m - 1] : zz, Vp = m ? V[m - 1] : zz;
;                         const f32x2 gp1 = {dpp_prev1(G[m].x, Gp.x), dpp_prev1(G[m].y, Gp.y)}, gp2 = {dpp_prev2(G[m].x, Gp.x), dpp_prev2(G[m].y, Gp.y)};
;                         const f32x2 vp1 = {dpp_prev1(V[m].x, Vp.x), dpp_prev1(V[m].y, Vp.y)}, vp2 = {dpp_prev2(V[m].x, Vp.x), dpp_prev2(V[m].y, Vp.y)};
;                         const f32x2 gc = bg + g0 * gp2 + g1 * gp1 + g2 * G[m];
;                         const f32x2 vc = bv + v0 * vp2 + v1 * vp1 + v2 * V[m];
;                         const f32x2 xe = gc * (-LOG2E);
;                         f32x2 dn = {__builtin_amdgcn_exp2f(xe.x), __builtin_amdgcn_exp2f(xe.y)}; dn = dn + 1.0f;
;                         const f32x2 rc = {__builtin_amdgcn_rcpf(dn.x), __builtin_amdgcn_rcpf(dn.y)};
;                         const f32x2 rr = gc * rc * vc;
;                         wpk[m][jp] = pk2(rr.x, rr.y); }
	v_pk_fma_f32 v[40:41], v[68:69], v[40:41], v[64:65]
	v_pk_mul_f32 v[52:53], v[52:53], v[100:101] op_sel_hi:[1,0]
	s_waitcnt lgkmcnt(1)
	v_pk_fma_f32 v[36:37], v[76:77], v[36:37], v[40:41]
	v_pk_mul_f32 v[32:33], v[32:33], v[110:111]
	s_waitcnt lgkmcnt(0)
	v_pk_fma_f32 v[36:37], v[80:81], v[56:57], v[36:37]
	v_pk_mul_f32 v[32:33], v[36:37], v[32:33]
	v_mov_b32_dpp v40, v60 row_ror:2 row_mask:0xf bank_mask:0xf
	v_mov_b32_dpp v41, v61 row_ror:2 row_mask:0xf bank_mask:0xf
	v_mov_b32_dpp v36, v60 row_ror:1 row_mask:0xf bank_mask:0xf
	v_mov_b32_dpp v37, v61 row_ror:1 row_mask:0xf bank_mask:0xf
	v_mov_b32_dpp v40, v52 row_shr:2 row_mask:0xf bank_mask:0xf
	v_mov_b32_dpp v41, v53 row_shr:2 row_mask:0xf bank_mask:0xf
	v_mov_b32_dpp v36, v52 row_shr:1 row_mask:0xf bank_mask:0xf
	v_mov_b32_dpp v37, v53 row_shr:1 row_mask:0xf bank_mask:0xf
	v_pk_fma_f32 v[40:41], v[84:85], v[40:41], v[72:73]
	v_pk_fma_f32 v[36:37], v[88:89], v[36:37], v[40:41]
	v_pk_fma_f32 v[36:37], v[92:93], v[52:53], v[36:37]
	v_pk_mul_f32 v[48:49], v[48:49], v[100:101] op_sel_hi:[1,0]
	v_pk_mul_f32 v[40:41], v[36:37], s[0:1] op_sel_hi:[1,0]
	v_exp_f32_e32 v40, v40
	v_exp_f32_e32 v41, v41
	v_mov_b32_dpp v110, v56 row_ror:2 row_mask:0xf bank_mask:0xf
	v_mov_b32_dpp v111, v57 row_ror:2 row_mask:0xf bank_mask:0xf
	v_pk_add_f32 v[40:41], v[40:41], 1.0 op_sel_hi:[1,0]
	v_mov_b32_dpp v60, v56 row_ror:1 row_mask:0xf bank_mask:0xf
	v_rcp_f32_e32 v40, v40
	v_rcp_f32_e32 v41, v41
	v_mov_b32_dpp v61, v57 row_ror:1 row_mask:0xf bank_mask:0xf
	v_mov_b32_dpp v110, v48 row_shr:2 row_mask:0xf bank_mask:0xf
	v_mov_b32_dpp v111, v49 row_shr:2 row_mask:0xf bank_mask:0xf
	v_mov_b32_dpp v60, v48 row_shr:1 row_mask:0xf bank_mask:0xf
	v_mov_b32_dpp v61, v49 row_shr:1 row_mask:0xf bank_mask:0xf
	v_pk_fma_f32 v[56:57], v[68:69], v[110:111], v[64:65]
	v_pk_mul_f32 v[36:37], v[36:37], v[40:41]
	v_pk_fma_f32 v[56:57], v[76:77], v[60:61], v[56:57]
	v_pk_mul_f32 v[44:45], v[44:45], v[98:99] op_sel_hi:[1,0]
	v_pk_fma_f32 v[56:57], v[80:81], v[48:49], v[56:57]
	v_pk_mul_f32 v[36:37], v[56:57], v[36:37]
	v_mov_b32_dpp v56, v52 row_ror:2 row_mask:0xf bank_mask:0xf
	v_mov_b32_dpp v57, v53 row_ror:2 row_mask:0xf bank_mask:0xf
	v_mov_b32_dpp v40, v52 row_ror:1 row_mask:0xf bank_mask:0xf
	v_mov_b32_dpp v41, v53 row_ror:1 row_mask:0xf bank_mask:0xf
	v_mov_b32_dpp v56, v44 row_shr:2 row_mask:0xf bank_mask:0xf
	v_mov_b32_dpp v57, v45 row_shr:2 row_mask:0xf bank_mask:0xf
	v_mov_b32_dpp v40, v44 row_shr:1 row_mask:0xf bank_mask:0xf
	v_mov_b32_dpp v41, v45 row_shr:1 row_mask:0xf bank_mask:0xf
	v_pk_fma_f32 v[56:57], v[84:85], v[56:57], v[72:73]
	v_pk_fma_f32 v[40:41], v[88:89], v[40:41], v[56:57]
	v_pk_fma_f32 v[40:41], v[92:93], v[44:45], v[40:41]
	v_pk_mul_f32 v[56:57], v[40:41], s[0:1] op_sel_hi:[1,0]
	v_exp_f32_e32 v56, v56
	v_exp_f32_e32 v57, v57
	v_mov_b32_dpp v52, v48 row_ror:1 row_mask:0xf bank_mask:0xf
	v_mov_b32_dpp v53, v49 row_ror:1 row_mask:0xf bank_mask:0xf
	v_mov_b32_dpp v60, v48 row_ror:2 row_mask:0xf bank_mask:0xf
	v_mov_b32_dpp v61, v49 row_ror:2 row_mask:0xf bank_mask:0xf
	v_pk_add_f32 v[48:49], v[56:57], 1.0 op_sel_hi:[1,0]
	v_mov_b32_dpp v60, v104 row_shr:2 row_mask:0xf bank_mask:0xf
	v_rcp_f32_e32 v48, v48
	v_rcp_f32_e32 v49, v49
	v_mov_b32_dpp v61, v105 row_shr:2 row_mask:0xf bank_mask:0xf
	v_mov_b32_dpp v52, v104 row_shr:1 row_mask:0xf bank_mask:0xf
	v_mov_b32_dpp v53, v105 row_shr:1 row_mask:0xf bank_mask:0xf
	v_pk_fma_f32 v[56:57], v[68:69], v[60:61], v[64:65]
	v_pk_mul_f32 v[40:41], v[40:41], v[48:49]
	v_pk_fma_f32 v[52:53], v[76:77], v[52:53], v[56:57]
	v_pk_fma_f32 v[52:53], v[80:81], v[104:105], v[52:53]
	v_pk_mul_f32 v[40:41], v[52:53], v[40:41]
	v_mov_b32_dpp v48, v44 row_ror:1 row_mask:0xf bank_mask:0xf
	v_mov_b32_dpp v52, v44 row_ror:2 row_mask:0xf bank_mask:0xf
	v_mov_b32_dpp v53, v45 row_ror:2 row_mask:0xf bank_mask:0xf
	v_mov_b32_dpp v49, v45 row_ror:1 row_mask:0xf bank_mask:0xf
	v_mov_b32_dpp v52, v106 row_shr:2 row_mask:0xf bank_mask:0xf
	v_mov_b32_dpp v53, v107 row_shr:2 row_mask:0xf bank_mask:0xf
	v_mov_b32_dpp v48, v106 row_shr:1 row_mask:0xf bank_mask:0xf
	v_mov_b32_dpp v49, v107 row_shr:1 row_mask:0xf bank_mask:0xf
	v_pk_fma_f32 v[52:53], v[84:85], v[52:53], v[72:73]
	v_pk_fma_f32 v[48:49], v[88:89], v[48:49], v[52:53]
	v_pk_fma_f32 v[48:49], v[92:93], v[106:107], v[48:49]
	v_pk_mul_f32 v[52:53], v[48:49], s[0:1] op_sel_hi:[1,0]
	v_exp_f32_e32 v52, v52
	v_exp_f32_e32 v53, v53
	v_mov_b32_dpp v56, v104 row_ror:2 row_mask:0xf bank_mask:0xf
	v_mov_b32_dpp v57, v105 row_ror:2 row_mask:0xf bank_mask:0xf
	v_mov_b32_dpp v44, v104 row_ror:1 row_mask:0xf bank_mask:0xf
	v_pk_add_f32 v[52:53], v[52:53], 1.0 op_sel_hi:[1,0]
	v_mov_b32_dpp v45, v105 row_ror:1 row_mask:0xf bank_mask:0xf
	v_rcp_f32_e32 v52, v52
	v_rcp_f32_e32 v53, v53
	v_mov_b32_dpp v56, v108 row_shr:2 row_mask:0xf bank_mask:0xf
	v_mov_b32_dpp v57, v109 row_shr:2 row_mask:0xf bank_mask:0xf
	v_mov_b32_dpp v44, v108 row_shr:1 row_mask:0xf bank_mask:0xf
	v_mov_b32_dpp v45, v109 row_shr:1 row_mask:0xf bank_mask:0xf
	v_pk_fma_f32 v[56:57], v[68:69], v[56:57], v[64:65]
	v_pk_mul_f32 v[48:49], v[48:49], v[52:53]
	v_pk_fma_f32 v[44:45], v[76:77], v[44:45], v[56:57]
	v_pk_mul_f32 v[52:53], v[58:59], v[102:103] op_sel_hi:[1,0]
	v_pk_fma_f32 v[44:45], v[80:81], v[108:109], v[44:45]
	v_mov_b32_e32 v58, v183
	v_pk_mul_f32 v[44:45], v[44:45], v[48:49]
	v_pk_mul_f32 v[48:49], v[62:63], v[102:103] op_sel_hi:[1,0]
	v_mov_b32_e32 v59, v183
	v_mov_b32_e32 v56, v181
	v_mov_b32_e32 v57, v181
	v_mov_b32_dpp v58, v48 row_shr:2 row_mask:0xf bank_mask:0xf
	v_mov_b32_dpp v59, v49 row_shr:2 row_mask:0xf bank_mask:0xf
	v_mov_b32_dpp v56, v48 row_shr:1 row_mask:0xf bank_mask:0xf
; #define LAS __attribute__((address_space(3)))
; DI unsigned pk2(float lo, float hi) { f32x2 v = {lo, hi}; bf16x2_t b = __builtin_convertvector(v, bf16x2_t); return __builtin_bit_cast(unsigned, b); }
;     DI void operator()(const AccT& acc, const Unit& u, int wr, int wc, int fr, int fq) const {
;     ...
;                     const f32x2 bg = *(const LAS f32x2*)(P + lc + 2 * jp), g0 = *(const LAS f32x2*)(P + 32 + lc + 2 * jp), g1 = *(const LAS f32x2*)(P + 64 + lc + 2 * jp), g2 = *(const LAS f32x2*)(P + 96 + lc + 2 * jp);
;                     const f32x2 bv = *(const LAS f32x2*)(P + 128 + lc + 2 * jp), v0 = *(const LAS f32x2*)(P + 160 + lc + 2 * jp), v1 = *(const LAS f32x2*)(P + 192 + lc + 2 * jp), v2 = *(const LAS f32x2*)(P + 224 + lc + 2 * jp);
;                     f32x2 G[4], V[4];
; #pragma unroll
;                     for (int m = 0; m < 4; ++m) { G[m] = (f32x2){acc[ai][0][m][n][2 * jp], acc[ai][0][m][n][2 * jp + 1]} * rs[m]; V[m] = (f32x2){acc[ai][1][m][n][2 * jp], acc[ai][1][m][n][2 * jp + 1]} * rs[m]; }
; #pragma unroll
;                     for (int m = 0; m < 4; ++m) {
;                         const f32x2 zz = {0.f, 0.f}; const f32x2 Gp = m ? G[m - 1] : zz, Vp = m ? V[m - 1] : zz;
;                         const f32x2 gp1 = {dpp_prev1(G[m].x, Gp.x), dpp_prev1(G[m].y, Gp.y)}, gp2 = {dpp_prev2(G[m].x, Gp.x), dpp_prev2(G[m].y, Gp.y)};
;                         const f32x2 vp1 = {dpp_prev1(V[m].x, Vp.x), dpp_prev1(V[m].y, Vp.y)}, vp2 = {dpp_prev2(V[m].x, Vp.x), dpp_prev2(V[m].y, Vp.y)};
;                         const f32x2 gc = bg + g0 * gp2 + g1 * gp1 + g2 * G[m];
;                         const f32x2 vc = bv + v0 * vp2 + v1 * vp1 + v2 * V[m];
;                         const f32x2 xe = gc * (-LOG2E);
;                         f32x2 dn = {__builtin_amdgcn_exp2f(xe.x), __builtin_amdgcn_exp2f(xe.y)}; dn = dn + 1.0f;
;                         const f32x2 rc = {__builtin_amdgcn_rcpf(dn.x), __builtin_amdgcn_rcpf(dn.y)};
;                         const f32x2 rr = gc * rc * vc;
;                         wpk[m][jp] = pk2(rr.x, rr.y); }
	v_mov_b32_dpp v57, v49 row_shr:1 row_mask:0xf bank_mask:0xf
	v_pk_fma_f32 v[58:59], v[86:87], v[58:59], v[74:75]
	v_mov_b32_e32 v62, v183
	v_pk_fma_f32 v[56:57], v[90:91], v[56:57], v[58:59]
	v_mov_b32_e32 v63, v183
	v_pk_fma_f32 v[56:57], v[48:49], v[94:95], v[56:57]
	v_mov_b32_e32 v60, v181
	v_pk_mul_f32 v[58:59], v[56:57], s[0:1] op_sel_hi:[1,0]
	v_mov_b32_e32 v61, v181
	v_exp_f32_e32 v58, v58
	v_exp_f32_e32 v59, v59
	v_mov_b32_dpp v62, v52 row_shr:2 row_mask:0xf bank_mask:0xf
	v_mov_b32_dpp v63, v53 row_shr:2 row_mask:0xf bank_mask:0xf
	v_mov_b32_dpp v60, v52 row_shr:1 row_mask:0xf bank_mask:0xf
	v_pk_add_f32 v[58:59], v[58:59], 1.0 op_sel_hi:[1,0]
	v_mov_b32_dpp v61, v53 row_shr:1 row_mask:0xf bank_mask:0xf
	v_rcp_f32_e32 v58, v58
	v_rcp_f32_e32 v59, v59
	v_pk_fma_f32 v[62:63], v[70:71], v[62:63], v[66:67]
	v_cvt_pk_bf16_f32 v32, v32, v33
	v_pk_fma_f32 v[60:61], v[78:79], v[60:61], v[62:63]
	v_pk_mul_f32 v[56:57], v[56:57], v[58:59]
	v_pk_fma_f32 v[60:61], v[52:53], v[82:83], v[60:61]
	v_pk_mul_f32 v[56:57], v[60:61], v[56:57]
	v_pk_mul_f32 v[54:55], v[54:55], v[100:101] op_sel_hi:[1,0]
	v_cvt_pk_bf16_f32 v33, v56, v57
	v_mov_b32_dpp v58, v48 row_ror:2 row_mask:0xf bank_mask:0xf
	v_mov_b32_dpp v59, v49 row_ror:2 row_mask:0xf bank_mask:0xf
	v_mov_b32_dpp v56, v48 row_ror:1 row_mask:0xf bank_mask:0xf
	v_mov_b32_dpp v57, v49 row_ror:1 row_mask:0xf bank_mask:0xf
	v_mov_b32_dpp v58, v54 row_shr:2 row_mask:0xf bank_mask:0xf
	v_mov_b32_dpp v59, v55 row_shr:2 row_mask:0xf bank_mask:0xf
	v_mov_b32_dpp v56, v54 row_shr:1 row_mask:0xf bank_mask:0xf
	v_mov_b32_dpp v57, v55 row_shr:1 row_mask:0xf bank_mask:0xf
	v_pk_fma_f32 v[58:59], v[86:87], v[58:59], v[74:75]
	v_pk_fma_f32 v[56:57], v[90:91], v[56:57], v[58:59]
	v_pk_fma_f32 v[56:57], v[54:55], v[94:95], v[56:57]
	v_pk_mul_f32 v[58:59], v[56:57], s[0:1] op_sel_hi:[1,0]
	v_exp_f32_e32 v58, v58
	v_exp_f32_e32 v59, v59
	v_mov_b32_dpp v48, v52 row_ror:1 row_mask:0xf bank_mask:0xf
	v_mov_b32_dpp v49, v53 row_ror:1 row_mask:0xf bank_mask:0xf
	v_mov_b32_dpp v60, v52 row_ror:2 row_mask:0xf bank_mask:0xf
	v_mov_b32_dpp v61, v53 row_ror:2 row_mask:0xf bank_mask:0xf
	v_pk_add_f32 v[52:53], v[58:59], 1.0 op_sel_hi:[1,0]
	v_pk_mul_f32 v[50:51], v[50:51], v[100:101] op_sel_hi:[1,0]
	v_rcp_f32_e32 v52, v52
	v_rcp_f32_e32 v53, v53
	v_mov_b32_dpp v60, v50 row_shr:2 row_mask:0xf bank_mask:0xf
	v_mov_b32_dpp v61, v51 row_shr:2 row_mask:0xf bank_mask:0xf
	v_mov_b32_dpp v48, v50 row_shr:1 row_mask:0xf bank_mask:0xf
	v_mov_b32_dpp v49, v51 row_shr:1 row_mask:0xf bank_mask:0xf
	v_pk_fma_f32 v[58:59], v[70:71], v[60:61], v[66:67]
	v_pk_mul_f32 v[52:53], v[56:57], v[52:53]
	v_pk_fma_f32 v[48:49], v[78:79], v[48:49], v[58:59]
	v_cvt_pk_bf16_f32 v36, v36, v37
	v_pk_fma_f32 v[48:49], v[50:51], v[82:83], v[48:49]
	v_pk_mul_f32 v[46:47], v[46:47], v[98:99] op_sel_hi:[1,0]
	v_pk_mul_f32 v[48:49], v[48:49], v[52:53]
	v_cvt_pk_bf16_f32 v37, v48, v49
	v_mov_b32_dpp v52, v54 row_ror:2 row_mask:0xf bank_mask:0xf
	v_mov_b32_dpp v53, v55 row_ror:2 row_mask:0xf bank_mask:0xf
	v_mov_b32_dpp v48, v54 row_ror:1 row_mask:0xf bank_mask:0xf
	v_mov_b32_dpp v49, v55 row_ror:1 row_mask:0xf bank_mask:0xf
	v_mov_b32_dpp v52, v46 row_shr:2 row_mask:0xf bank_mask:0xf
	v_mov_b32_dpp v53, v47 row_shr:2 row_mask:0xf bank_mask:0xf
	v_mov_b32_dpp v48, v46 row_shr:1 row_mask:0xf bank_mask:0xf
	v_mov_b32_dpp v49, v47 row_shr:1 row_mask:0xf bank_mask:0xf
	v_pk_fma_f32 v[52:53], v[86:87], v[52:53], v[74:75]
	v_pk_fma_f32 v[48:49], v[90:91], v[48:49], v[52:53]
	v_pk_fma_f32 v[48:49], v[46:47], v[94:95], v[48:49]
	v_pk_mul_f32 v[52:53], v[48:49], s[0:1] op_sel_hi:[1,0]
	v_exp_f32_e32 v52, v52
	v_exp_f32_e32 v53, v53
	v_mov_b32_dpp v54, v50 row_ror:1 row_mask:0xf bank_mask:0xf
	v_mov_b32_dpp v55, v51 row_ror:1 row_mask:0xf bank_mask:0xf
	v_mov_b32_dpp v56, v50 row_ror:2 row_mask:0xf bank_mask:0xf
	v_mov_b32_dpp v57, v51 row_ror:2 row_mask:0xf bank_mask:0xf
	v_pk_add_f32 v[50:51], v[52:53], 1.0 op_sel_hi:[1,0]
	v_pk_mul_f32 v[42:43], v[42:43], v[98:99] op_sel_hi:[1,0]
	v_rcp_f32_e32 v50, v50
	v_rcp_f32_e32 v51, v51
	v_mov_b32_dpp v56, v42 row_shr:2 row_mask:0xf bank_mask:0xf
	v_mov_b32_dpp v57, v43 row_shr:2 row_mask:0xf bank_mask:0xf
	v_mov_b32_dpp v54, v42 row_shr:1 row_mask:0xf bank_mask:0xf
	v_mov_b32_dpp v55, v43 row_shr:1 row_mask:0xf bank_mask:0xf
	v_pk_fma_f32 v[52:53], v[70:71], v[56:57], v[66:67]
	v_pk_mul_f32 v[48:49], v[48:49], v[50:51]
	v_pk_fma_f32 v[52:53], v[78:79], v[54:55], v[52:53]
	v_pk_fma_f32 v[52:53], v[42:43], v[82:83], v[52:53]
	v_pk_mul_f32 v[48:49], v[52:53], v[48:49]
	v_cvt_pk_bf16_f32 v40, v40, v41
	v_pk_mul_f32 v[38:39], v[38:39], v[96:97] op_sel_hi:[1,0]
	v_cvt_pk_bf16_f32 v41, v48, v49
	v_mov_b32_dpp v50, v46 row_ror:2 row_mask:0xf bank_mask:0xf
	v_mov_b32_dpp v51, v47 row_ror:2 row_mask:0xf bank_mask:0xf
	v_mov_b32_dpp v48, v46 row_ror:1 row_mask:0xf bank_mask:0xf
	v_mov_b32_dpp v49, v47 row_ror:1 row_mask:0xf bank_mask:0xf
	v_mov_b32_dpp v50, v38 row_shr:2 row_mask:0xf bank_mask:0xf
	v_mov_b32_dpp v51, v39 row_shr:2 row_mask:0xf bank_mask:0xf
	v_mov_b32_dpp v48, v38 row_shr:1 row_mask:0xf bank_mask:0xf
	v_mov_b32_dpp v49, v39 row_shr:1 row_mask:0xf bank_mask:0xf
	v_pk_fma_f32 v[50:51], v[86:87], v[50:51], v[74:75]
	v_pk_fma_f32 v[48:49], v[90:91], v[48:49], v[50:51]
	v_pk_fma_f32 v[38:39], v[38:39], v[94:95], v[48:49]
	v_pk_mul_f32 v[48:49], v[38:39], s[0:1] op_sel_hi:[1,0]
	v_exp_f32_e32 v48, v48
	v_exp_f32_e32 v49, v49
	v_mov_b32_dpp v46, v42 row_ror:1 row_mask:0xf bank_mask:0xf
	v_mov_b32_dpp v47, v43 row_ror:1 row_mask:0xf bank_mask:0xf
	v_mov_b32_dpp v52, v42 row_ror:2 row_mask:0xf bank_mask:0xf
; #define LAS __attribute__((address_space(3)))
; DI unsigned pk2(float lo, float hi) { f32x2 v = {lo, hi}; bf16x2_t b = __builtin_convertvector(v, bf16x2_t); return __builtin_bit_cast(unsigned, b); }
;     DI void operator()(const AccT& acc, const Unit& u, int wr, int wc, int fr, int fq) const {
;     ...
;                     const f32x2 bg = *(const LAS f32x2*)(P + lc + 2 * jp), g0 = *(const LAS f32x2*)(P + 32 + lc + 2 * jp), g1 = *(const LAS f32x2*)(P + 64 + lc + 2 * jp), g2 = *(const LAS f32x2*)(P + 96 + lc + 2 * jp);
;                     const f32x2 bv = *(const LAS f32x2*)(P + 128 + lc + 2 * jp), v0 = *(const LAS f32x2*)(P + 160 + lc + 2 * jp), v1 = *(const LAS f32x2*)(P + 192 + lc + 2 * jp), v2 = *(const LAS f32x2*)(P + 224 + lc + 2 * jp);
;                     f32x2 G[4], V[4];
; #pragma unroll
;                     for (int m = 0; m < 4; ++m) { G[m] = (f32x2){acc[ai][0][m][n][2 * jp], acc[ai][0][m][n][2 * jp + 1]} * rs[m]; V[m] = (f32x2){acc[ai][1][m][n][2 * jp], acc[ai][1][m][n][2 * jp + 1]} * rs[m]; }
; #pragma unroll
;                     for (int m = 0; m < 4; ++m) {
;                         const f32x2 zz = {0.f, 0.f}; const f32x2 Gp = m ? G[m - 1] : zz, Vp = m ? V[m - 1] : zz;
;                         const f32x2 gp1 = {dpp_prev1(G[m].x, Gp.x), dpp_prev1(G[m].y, Gp.y)}, gp2 = {dpp_prev2(G[m].x, Gp.x), dpp_prev2(G[m].y, Gp.y)};
;                         const f32x2 vp1 = {dpp_prev1(V[m].x, Vp.x), dpp_prev1(V[m].y, Vp.y)}, vp2 = {dpp_prev2(V[m].x, Vp.x), dpp_prev2(V[m].y, Vp.y)};
;                         const f32x2 gc = bg + g0 * gp2 + g1 * gp1 + g2 * G[m];
;                         const f32x2 vc = bv + v0 * vp2 + v1 * vp1 + v2 * V[m];
;                         const f32x2 xe = gc * (-LOG2E);
;                         f32x2 dn = {__builtin_amdgcn_exp2f(xe.x), __builtin_amdgcn_exp2f(xe.y)}; dn = dn + 1.0f;
;                         const f32x2 rc = {__builtin_amdgcn_rcpf(dn.x), __builtin_amdgcn_rcpf(dn.y)};
;                         const f32x2 rr = gc * rc * vc;
;                         wpk[m][jp] = pk2(rr.x, rr.y); }
;                 }
; #pragma unroll
;                 for (int m = 0; m < 4; ++m) { const int row = m ? tok0 + 16 * m : row0;
;                     *(u32x2*)(ACT + (size_t)row * 2816 + cl + 4 * n) = (u32x2){wpk[m][0], wpk[m][1]}; }
	v_mov_b32_dpp v53, v43 row_ror:2 row_mask:0xf bank_mask:0xf
	v_pk_add_f32 v[42:43], v[48:49], 1.0 op_sel_hi:[1,0]
	v_pk_mul_f32 v[34:35], v[34:35], v[96:97] op_sel_hi:[1,0]
	v_rcp_f32_e32 v42, v42
	v_rcp_f32_e32 v43, v43
	v_mov_b32_dpp v52, v34 row_shr:2 row_mask:0xf bank_mask:0xf
	v_mov_b32_dpp v53, v35 row_shr:2 row_mask:0xf bank_mask:0xf
	v_mov_b32_dpp v46, v34 row_shr:1 row_mask:0xf bank_mask:0xf
	v_mov_b32_dpp v47, v35 row_shr:1 row_mask:0xf bank_mask:0xf
	v_pk_fma_f32 v[48:49], v[70:71], v[52:53], v[66:67]
	v_pk_mul_f32 v[38:39], v[38:39], v[42:43]
	v_pk_fma_f32 v[46:47], v[78:79], v[46:47], v[48:49]
	v_cvt_pk_bf16_f32 v44, v44, v45
	v_pk_fma_f32 v[34:35], v[34:35], v[82:83], v[46:47]
	s_nop 0
	v_pk_mul_f32 v[34:35], v[34:35], v[38:39]
	s_nop 0
	v_cvt_pk_bf16_f32 v45, v34, v35
	v_mad_i64_i32 v[34:35], s[10:11], v103, s48, v[128:129]
	v_lshl_add_u64 v[64:65], v[34:35], 0, v[130:131]
	global_store_dwordx2 v[64:65], v[32:33], off
	v_mad_i64_i32 v[32:33], s[10:11], v97, s48, v[128:129]
	v_lshl_add_u64 v[66:67], v[32:33], 0, v[130:131]
	v_mad_i64_i32 v[32:33], s[10:11], v99, s48, v[128:129]
	v_lshl_add_u64 v[68:69], v[32:33], 0, v[130:131]
	v_mad_i64_i32 v[32:33], s[10:11], v101, s48, v[128:129]
	v_lshl_add_u64 v[70:71], v[32:33], 0, v[130:131]
	global_store_dwordx2 v[66:67], v[36:37], off
	global_store_dwordx2 v[68:69], v[40:41], off
	global_store_dwordx2 v[70:71], v[44:45], off
	v_pk_mul_f32 v[30:31], v[30:31], v[102:103] op_sel_hi:[1,0]
	v_pk_mul_f32 v[22:23], v[22:23], v[100:101] op_sel_hi:[1,0]
	s_nop 0
	v_mov_b32_dpp v114, v30 row_ror:2 row_mask:0xf bank_mask:0xf
	v_mov_b32_dpp v115, v31 row_ror:2 row_mask:0xf bank_mask:0xf
	v_mov_b32_dpp v112, v30 row_ror:1 row_mask:0xf bank_mask:0xf
	v_mov_b32_dpp v113, v31 row_ror:1 row_mask:0xf bank_mask:0xf
	v_mov_b32_dpp v114, v22 row_shr:2 row_mask:0xf bank_mask:0xf
	v_mov_b32_dpp v115, v23 row_shr:2 row_mask:0xf bank_mask:0xf
	ds_read_b128 v[40:43], v200 offset:16
	ds_read_b128 v[52:55], v200 offset:144
	ds_read_b128 v[56:59], v200 offset:272
	ds_read_b128 v[60:63], v200 offset:400
	ds_read_b128 v[32:35], v200 offset:528
	ds_read_b128 v[36:39], v200 offset:656
	ds_read_b128 v[44:47], v200 offset:784
	ds_read_b128 v[48:51], v200 offset:912
	v_mov_b32_dpp v112, v22 row_shr:1 row_mask:0xf bank_mask:0xf
	v_mov_b32_dpp v113, v23 row_shr:1 row_mask:0xf bank_mask:0xf
	s_waitcnt lgkmcnt(6)
	v_pk_fma_f32 v[114:115], v[54:55], v[114:115], v[42:43]
	v_pk_mul_f32 v[28:29], v[28:29], v[102:103] op_sel_hi:[1,0]
	v_pk_mul_f32 v[24:25], v[24:25], v[102:103] op_sel_hi:[1,0]
	v_pk_mul_f32 v[20:21], v[20:21], v[100:101] op_sel_hi:[1,0]
	v_pk_mul_f32 v[16:17], v[16:17], v[100:101] op_sel_hi:[1,0]
	v_pk_mul_f32 v[26:27], v[26:27], v[102:103] op_sel_hi:[1,0]
	v_pk_mul_f32 v[100:101], v[18:19], v[100:101] op_sel_hi:[1,0]
	v_mov_b32_e32 v102, v183
	v_mov_b32_e32 v103, v183
	s_waitcnt lgkmcnt(5)
	v_pk_fma_f32 v[112:113], v[58:59], v[112:113], v[114:115]
	v_pk_mul_f32 v[76:77], v[12:13], v[98:99] op_sel_hi:[1,0]
	v_pk_mul_f32 v[72:73], v[8:9], v[98:99] op_sel_hi:[1,0]
	v_pk_mul_f32 v[14:15], v[14:15], v[98:99] op_sel_hi:[1,0]
	v_pk_mul_f32 v[10:11], v[10:11], v[98:99] op_sel_hi:[1,0]
	v_mov_b32_e32 v98, v181
	v_mov_b32_e32 v99, v181
	v_mov_b32_dpp v102, v30 row_shr:2 row_mask:0xf bank_mask:0xf
	v_mov_b32_dpp v103, v31 row_shr:2 row_mask:0xf bank_mask:0xf
	v_mov_b32_dpp v18, v22 row_ror:1 row_mask:0xf bank_mask:0xf
	v_mov_b32_dpp v19, v23 row_ror:1 row_mask:0xf bank_mask:0xf
	v_mov_b32_dpp v120, v22 row_ror:2 row_mask:0xf bank_mask:0xf
	v_mov_b32_dpp v121, v23 row_ror:2 row_mask:0xf bank_mask:0xf
	s_waitcnt lgkmcnt(4)
	v_pk_fma_f32 v[22:23], v[22:23], v[62:63], v[112:113]
	v_mov_b32_dpp v98, v30 row_shr:1 row_mask:0xf bank_mask:0xf
	v_mov_b32_dpp v99, v31 row_shr:1 row_mask:0xf bank_mask:0xf
	v_pk_mul_f32 v[112:113], v[22:23], s[0:1] op_sel_hi:[1,0]
	v_pk_fma_f32 v[102:103], v[54:55], v[102:103], v[42:43]
	v_exp_f32_e32 v112, v112
	v_exp_f32_e32 v113, v113
	v_pk_fma_f32 v[98:99], v[58:59], v[98:99], v[102:103]
	v_pk_fma_f32 v[30:31], v[30:31], v[62:63], v[98:99]
	v_pk_mul_f32 v[98:99], v[30:31], s[0:1] op_sel_hi:[1,0]
	v_pk_add_f32 v[112:113], v[112:113], 1.0 op_sel_hi:[1,0]
	v_exp_f32_e32 v98, v98
	v_exp_f32_e32 v99, v99
	v_mov_b32_dpp v118, v26 row_ror:2 row_mask:0xf bank_mask:0xf
	v_mov_b32_dpp v119, v27 row_ror:2 row_mask:0xf bank_mask:0xf
	v_rcp_f32_e32 v112, v112
	v_rcp_f32_e32 v113, v113
	v_mov_b32_dpp v116, v26 row_ror:1 row_mask:0xf bank_mask:0xf
	v_mov_b32_dpp v117, v27 row_ror:1 row_mask:0xf bank_mask:0xf
	v_mov_b32_dpp v118, v100 row_shr:2 row_mask:0xf bank_mask:0xf
	v_mov_b32_dpp v119, v101 row_shr:2 row_mask:0xf bank_mask:0xf
	v_mov_b32_dpp v116, v100 row_shr:1 row_mask:0xf bank_mask:0xf
	v_mov_b32_dpp v117, v101 row_shr:1 row_mask:0xf bank_mask:0xf
	s_waitcnt lgkmcnt(2)
	v_pk_fma_f32 v[114:115], v[38:39], v[118:119], v[34:35]
	v_pk_add_f32 v[98:99], v[98:99], 1.0 op_sel_hi:[1,0]
	v_mov_b32_e32 v182, v183
	s_waitcnt lgkmcnt(1)
	v_pk_fma_f32 v[114:115], v[46:47], v[116:117], v[114:115]
	v_rcp_f32_e32 v98, v98
	v_rcp_f32_e32 v99, v99
	v_pk_mul_f32 v[86:87], v[4:5], v[96:97] op_sel_hi:[1,0]
	v_mov_b32_e32 v12, v183
	v_mov_b32_e32 v13, v183
	v_mov_b32_e32 v4, v183
	v_mov_b32_e32 v5, v183
	v_mov_b32_e32 v180, v181
	v_mov_b32_dpp v182, v26 row_shr:2 row_mask:0xf bank_mask:0xf
	v_mov_b32_dpp v183, v27 row_shr:2 row_mask:0xf bank_mask:0xf
	v_mov_b32_dpp v122, v100 row_ror:1 row_mask:0xf bank_mask:0xf
	v_mov_b32_dpp v123, v101 row_ror:1 row_mask:0xf bank_mask:0xf
	v_mov_b32_dpp v124, v100 row_ror:2 row_mask:0xf bank_mask:0xf
	v_mov_b32_dpp v125, v101 row_ror:2 row_mask:0xf bank_mask:0xf
	s_waitcnt lgkmcnt(0)
; #define LAS __attribute__((address_space(3)))
; DI unsigned pk2(float lo, float hi) { f32x2 v = {lo, hi}; bf16x2_t b = __builtin_convertvector(v, bf16x2_t); return __builtin_bit_cast(unsigned, b); }
;     DI void operator()(const AccT& acc, const Unit& u, int wr, int wc, int fr, int fq) const {
;     ...
;                     const f32x2 bg = *(const LAS f32x2*)(P + lc + 2 * jp), g0 = *(const LAS f32x2*)(P + 32 + lc + 2 * jp), g1 = *(const LAS f32x2*)(P + 64 + lc + 2 * jp), g2 = *(const LAS f32x2*)(P + 96 + lc + 2 * jp);
;                     const f32x2 bv = *(const LAS f32x2*)(P + 128 + lc + 2 * jp), v0 = *(const LAS f32x2*)(P + 160 + lc + 2 * jp), v1 = *(const LAS f32x2*)(P + 192 + lc + 2 * jp), v2 = *(const LAS f32x2*)(P + 224 + lc + 2 * jp);
;                     f32x2 G[4], V[4];
; #pragma unroll
;                     for (int m = 0; m < 4; ++m) { G[m] = (f32x2){acc[ai][0][m][n][2 * jp], acc[ai][0][m][n][2 * jp + 1]} * rs[m]; V[m] = (f32x2){acc[ai][1][m][n][2 * jp], acc[ai][1][m][n][2 * jp + 1]} * rs[m]; }
; #pragma unroll
;                     for (int m = 0; m < 4; ++m) {
;                         const f32x2 zz = {0.f, 0.f}; const f32x2 Gp = m ? G[m - 1] : zz, Vp = m ? V[m - 1] : zz;
;                         const f32x2 gp1 = {dpp_prev1(G[m].x, Gp.x), dpp_prev1(G[m].y, Gp.y)}, gp2 = {dpp_prev2(G[m].x, Gp.x), dpp_prev2(G[m].y, Gp.y)};
;                         const f32x2 vp1 = {dpp_prev1(V[m].x, Vp.x), dpp_prev1(V[m].y, Vp.y)}, vp2 = {dpp_prev2(V[m].x, Vp.x), dpp_prev2(V[m].y, Vp.y)};
;                         const f32x2 gc = bg + g0 * gp2 + g1 * gp1 + g2 * G[m];
;                         const f32x2 vc = bv + v0 * vp2 + v1 * vp1 + v2 * V[m];
;                         const f32x2 xe = gc * (-LOG2E);
;                         f32x2 dn = {__builtin_amdgcn_exp2f(xe.x), __builtin_amdgcn_exp2f(xe.y)}; dn = dn + 1.0f;
;                         const f32x2 rc = {__builtin_amdgcn_rcpf(dn.x), __builtin_amdgcn_rcpf(dn.y)};
;                         const f32x2 rr = gc * rc * vc;
;                         wpk[m][jp] = pk2(rr.x, rr.y); }
	v_pk_fma_f32 v[100:101], v[100:101], v[50:51], v[114:115]
	v_pk_mul_f32 v[22:23], v[22:23], v[112:113]
	v_pk_mul_f32 v[84:85], v[0:1], v[96:97] op_sel_hi:[1,0]
	v_mov_b32_e32 v8, v181
	v_mov_b32_e32 v9, v181
	v_mov_b32_e32 v0, v181
	v_mov_b32_e32 v1, v181
	v_mov_b32_dpp v180, v26 row_shr:1 row_mask:0xf bank_mask:0xf
	v_mov_b32_dpp v181, v27 row_shr:1 row_mask:0xf bank_mask:0xf
	v_pk_mul_f32 v[22:23], v[100:101], v[22:23]
	v_pk_fma_f32 v[100:101], v[38:39], v[182:183], v[34:35]
	v_mov_b32_dpp v106, v76 row_ror:2 row_mask:0xf bank_mask:0xf
	v_mov_b32_dpp v107, v77 row_ror:2 row_mask:0xf bank_mask:0xf
	v_pk_fma_f32 v[100:101], v[46:47], v[180:181], v[100:101]
	v_mov_b32_dpp v104, v76 row_ror:1 row_mask:0xf bank_mask:0xf
	v_mov_b32_dpp v105, v77 row_ror:1 row_mask:0xf bank_mask:0xf
	v_mov_b32_dpp v106, v86 row_shr:2 row_mask:0xf bank_mask:0xf
	v_mov_b32_dpp v107, v87 row_shr:2 row_mask:0xf bank_mask:0xf
	v_pk_fma_f32 v[26:27], v[26:27], v[50:51], v[100:101]
	v_pk_mul_f32 v[30:31], v[30:31], v[98:99]
	v_mov_b32_dpp v104, v86 row_shr:1 row_mask:0xf bank_mask:0xf
	v_mov_b32_dpp v105, v87 row_shr:1 row_mask:0xf bank_mask:0xf
	v_pk_mul_f32 v[26:27], v[26:27], v[30:31]
	v_pk_fma_f32 v[30:31], v[52:53], v[106:107], v[40:41]
	v_mov_b32_dpp v12, v28 row_shr:2 row_mask:0xf bank_mask:0xf
	v_pk_fma_f32 v[30:31], v[56:57], v[104:105], v[30:31]
	v_mov_b32_dpp v13, v29 row_shr:2 row_mask:0xf bank_mask:0xf
	v_pk_fma_f32 v[30:31], v[86:87], v[60:61], v[30:31]
	v_pk_mul_f32 v[86:87], v[30:31], s[0:1] op_sel_hi:[1,0]
	v_mov_b32_dpp v8, v28 row_shr:1 row_mask:0xf bank_mask:0xf
	v_mov_b32_dpp v9, v29 row_shr:1 row_mask:0xf bank_mask:0xf
	v_mov_b32_dpp v92, v20 row_ror:2 row_mask:0xf bank_mask:0xf
	v_mov_b32_dpp v93, v21 row_ror:2 row_mask:0xf bank_mask:0xf
	v_exp_f32_e32 v86, v86
	v_exp_f32_e32 v87, v87
	v_pk_fma_f32 v[12:13], v[52:53], v[12:13], v[40:41]
	v_mov_b32_dpp v88, v20 row_ror:1 row_mask:0xf bank_mask:0xf
	v_mov_b32_dpp v89, v21 row_ror:1 row_mask:0xf bank_mask:0xf
	v_mov_b32_dpp v92, v76 row_shr:2 row_mask:0xf bank_mask:0xf
	v_mov_b32_dpp v93, v77 row_shr:2 row_mask:0xf bank_mask:0xf
	v_mov_b32_dpp v120, v14 row_shr:2 row_mask:0xf bank_mask:0xf
	v_mov_b32_dpp v121, v15 row_shr:2 row_mask:0xf bank_mask:0xf
	v_pk_fma_f32 v[8:9], v[56:57], v[8:9], v[12:13]
	v_mov_b32_dpp v88, v76 row_shr:1 row_mask:0xf bank_mask:0xf
	v_mov_b32_dpp v89, v77 row_shr:1 row_mask:0xf bank_mask:0xf
	v_mov_b32_dpp v18, v14 row_shr:1 row_mask:0xf bank_mask:0xf
	v_mov_b32_dpp v19, v15 row_shr:1 row_mask:0xf bank_mask:0xf
	v_pk_fma_f32 v[120:121], v[54:55], v[120:121], v[42:43]
	v_pk_fma_f32 v[92:93], v[52:53], v[92:93], v[40:41]
	v_pk_fma_f32 v[8:9], v[28:29], v[60:61], v[8:9]
	v_pk_fma_f32 v[18:19], v[58:59], v[18:19], v[120:121]
	v_pk_fma_f32 v[88:89], v[56:57], v[88:89], v[92:93]
	v_pk_mul_f32 v[12:13], v[8:9], s[0:1] op_sel_hi:[1,0]
	v_pk_fma_f32 v[18:19], v[14:15], v[62:63], v[18:19]
	v_pk_add_f32 v[86:87], v[86:87], 1.0 op_sel_hi:[1,0]
	v_pk_fma_f32 v[76:77], v[76:77], v[60:61], v[88:89]
	v_exp_f32_e32 v12, v12
	v_exp_f32_e32 v13, v13
	v_mov_b32_dpp v110, v72 row_ror:2 row_mask:0xf bank_mask:0xf
	v_mov_b32_dpp v111, v73 row_ror:2 row_mask:0xf bank_mask:0xf
	v_pk_mul_f32 v[120:121], v[18:19], s[0:1] op_sel_hi:[1,0]
	v_rcp_f32_e32 v86, v86
	v_rcp_f32_e32 v87, v87
	v_pk_mul_f32 v[88:89], v[76:77], s[0:1] op_sel_hi:[1,0]
	v_mov_b32_dpp v108, v72 row_ror:1 row_mask:0xf bank_mask:0xf
	v_mov_b32_dpp v109, v73 row_ror:1 row_mask:0xf bank_mask:0xf
	v_mov_b32_dpp v110, v84 row_shr:2 row_mask:0xf bank_mask:0xf
	v_mov_b32_dpp v111, v85 row_shr:2 row_mask:0xf bank_mask:0xf
	v_exp_f32_e32 v120, v120
	v_exp_f32_e32 v121, v121
	v_exp_f32_e32 v88, v88
	v_exp_f32_e32 v89, v89
	v_mov_b32_dpp v108, v84 row_shr:1 row_mask:0xf bank_mask:0xf
	v_mov_b32_dpp v109, v85 row_shr:1 row_mask:0xf bank_mask:0xf
	v_pk_mul_f32 v[2:3], v[2:3], v[96:97] op_sel_hi:[1,0]
	v_pk_mul_f32 v[6:7], v[6:7], v[96:97] op_sel_hi:[1,0]
	v_pk_fma_f32 v[96:97], v[36:37], v[110:111], v[32:33]
	v_pk_add_f32 v[12:13], v[12:13], 1.0 op_sel_hi:[1,0]
	v_pk_fma_f32 v[96:97], v[44:45], v[108:109], v[96:97]
	v_pk_mul_f32 v[30:31], v[30:31], v[86:87]
	v_pk_fma_f32 v[84:85], v[84:85], v[48:49], v[96:97]
	v_rcp_f32_e32 v12, v12
	v_rcp_f32_e32 v13, v13
	v_mov_b32_dpp v4, v24 row_shr:2 row_mask:0xf bank_mask:0xf
	v_mov_b32_dpp v5, v25 row_shr:2 row_mask:0xf bank_mask:0xf
	v_pk_add_f32 v[120:121], v[120:121], 1.0 op_sel_hi:[1,0]
	v_pk_mul_f32 v[30:31], v[84:85], v[30:31]
	v_pk_add_f32 v[84:85], v[88:89], 1.0 op_sel_hi:[1,0]
	v_mov_b32_dpp v0, v24 row_shr:1 row_mask:0xf bank_mask:0xf
	v_mov_b32_dpp v1, v25 row_shr:1 row_mask:0xf bank_mask:0xf
	v_mov_b32_dpp v94, v16 row_ror:2 row_mask:0xf bank_mask:0xf
	v_mov_b32_dpp v95, v17 row_ror:2 row_mask:0xf bank_mask:0xf
	v_rcp_f32_e32 v120, v120
	v_rcp_f32_e32 v121, v121
	v_rcp_f32_e32 v84, v84
	v_rcp_f32_e32 v85, v85
	v_pk_fma_f32 v[4:5], v[36:37], v[4:5], v[32:33]
	v_mov_b32_dpp v90, v16 row_ror:1 row_mask:0xf bank_mask:0xf
; #define LAS __attribute__((address_space(3)))
; DI unsigned pk2(float lo, float hi) { f32x2 v = {lo, hi}; bf16x2_t b = __builtin_convertvector(v, bf16x2_t); return __builtin_bit_cast(unsigned, b); }
;     DI void operator()(const AccT& acc, const Unit& u, int wr, int wc, int fr, int fq) const {
;     ...
;                     const f32x2 bg = *(const LAS f32x2*)(P + lc + 2 * jp), g0 = *(const LAS f32x2*)(P + 32 + lc + 2 * jp), g1 = *(const LAS f32x2*)(P + 64 + lc + 2 * jp), g2 = *(const LAS f32x2*)(P + 96 + lc + 2 * jp);
;                     const f32x2 bv = *(const LAS f32x2*)(P + 128 + lc + 2 * jp), v0 = *(const LAS f32x2*)(P + 160 + lc + 2 * jp), v1 = *(const LAS f32x2*)(P + 192 + lc + 2 * jp), v2 = *(const LAS f32x2*)(P + 224 + lc + 2 * jp);
;                     f32x2 G[4], V[4];
; #pragma unroll
;                     for (int m = 0; m < 4; ++m) { G[m] = (f32x2){acc[ai][0][m][n][2 * jp], acc[ai][0][m][n][2 * jp + 1]} * rs[m]; V[m] = (f32x2){acc[ai][1][m][n][2 * jp], acc[ai][1][m][n][2 * jp + 1]} * rs[m]; }
; #pragma unroll
;                     for (int m = 0; m < 4; ++m) {
;                         const f32x2 zz = {0.f, 0.f}; const f32x2 Gp = m ? G[m - 1] : zz, Vp = m ? V[m - 1] : zz;
;                         const f32x2 gp1 = {dpp_prev1(G[m].x, Gp.x), dpp_prev1(G[m].y, Gp.y)}, gp2 = {dpp_prev2(G[m].x, Gp.x), dpp_prev2(G[m].y, Gp.y)};
;                         const f32x2 vp1 = {dpp_prev1(V[m].x, Vp.x), dpp_prev1(V[m].y, Vp.y)}, vp2 = {dpp_prev2(V[m].x, Vp.x), dpp_prev2(V[m].y, Vp.y)};
;                         const f32x2 gc = bg + g0 * gp2 + g1 * gp1 + g2 * G[m];
;                         const f32x2 vc = bv + v0 * vp2 + v1 * vp1 + v2 * V[m];
;                         const f32x2 xe = gc * (-LOG2E);
;                         f32x2 dn = {__builtin_amdgcn_exp2f(xe.x), __builtin_amdgcn_exp2f(xe.y)}; dn = dn + 1.0f;
;                         const f32x2 rc = {__builtin_amdgcn_rcpf(dn.x), __builtin_amdgcn_rcpf(dn.y)};
;                         const f32x2 rr = gc * rc * vc;
;                         wpk[m][jp] = pk2(rr.x, rr.y); }
;                 }
; #pragma unroll
;                 for (int m = 0; m < 4; ++m) { const int row = m ? tok0 + 16 * m : row0;
;                     *(u32x2*)(ACT + (size_t)row * 2816 + cl + 4 * n) = (u32x2){wpk[m][0], wpk[m][1]}; }
	v_mov_b32_dpp v91, v17 row_ror:1 row_mask:0xf bank_mask:0xf
	v_mov_b32_dpp v94, v72 row_shr:2 row_mask:0xf bank_mask:0xf
	v_mov_b32_dpp v95, v73 row_shr:2 row_mask:0xf bank_mask:0xf
	v_mov_b32_dpp v124, v10 row_shr:2 row_mask:0xf bank_mask:0xf
	v_mov_b32_dpp v125, v11 row_shr:2 row_mask:0xf bank_mask:0xf
	v_pk_fma_f32 v[0:1], v[44:45], v[0:1], v[4:5]
	v_mov_b32_dpp v90, v72 row_shr:1 row_mask:0xf bank_mask:0xf
	v_mov_b32_dpp v91, v73 row_shr:1 row_mask:0xf bank_mask:0xf
	v_mov_b32_dpp v122, v10 row_shr:1 row_mask:0xf bank_mask:0xf
	v_mov_b32_dpp v123, v11 row_shr:1 row_mask:0xf bank_mask:0xf
	v_pk_fma_f32 v[124:125], v[38:39], v[124:125], v[34:35]
	v_pk_fma_f32 v[86:87], v[36:37], v[94:95], v[32:33]
	v_pk_fma_f32 v[0:1], v[24:25], v[48:49], v[0:1]
	v_pk_mul_f32 v[4:5], v[8:9], v[12:13]
	v_pk_fma_f32 v[122:123], v[46:47], v[122:123], v[124:125]
	v_pk_fma_f32 v[86:87], v[44:45], v[90:91], v[86:87]
	v_pk_mul_f32 v[0:1], v[0:1], v[4:5]
	v_mov_b32_dpp v78, v28 row_ror:2 row_mask:0xf bank_mask:0xf
	v_mov_b32_dpp v79, v29 row_ror:2 row_mask:0xf bank_mask:0xf
	v_pk_fma_f32 v[122:123], v[10:11], v[50:51], v[122:123]
	v_pk_mul_f32 v[18:19], v[18:19], v[120:121]
	v_cvt_pk_bf16_f32 v27, v26, v27
	v_pk_fma_f32 v[72:73], v[72:73], v[48:49], v[86:87]
	v_pk_mul_f32 v[76:77], v[76:77], v[84:85]
	v_cvt_pk_bf16_f32 v26, v0, v1
	v_mov_b32_dpp v4, v14 row_ror:2 row_mask:0xf bank_mask:0xf
	v_mov_b32_dpp v5, v15 row_ror:2 row_mask:0xf bank_mask:0xf
	v_mov_b32_dpp v74, v28 row_ror:1 row_mask:0xf bank_mask:0xf
	v_mov_b32_dpp v75, v29 row_ror:1 row_mask:0xf bank_mask:0xf
	v_mov_b32_dpp v78, v20 row_shr:2 row_mask:0xf bank_mask:0xf
	v_mov_b32_dpp v79, v21 row_shr:2 row_mask:0xf bank_mask:0xf
	v_pk_mul_f32 v[18:19], v[122:123], v[18:19]
	v_pk_mul_f32 v[72:73], v[72:73], v[76:77]
	v_mov_b32_dpp v0, v14 row_ror:1 row_mask:0xf bank_mask:0xf
	v_mov_b32_dpp v1, v15 row_ror:1 row_mask:0xf bank_mask:0xf
	v_mov_b32_dpp v4, v6 row_shr:2 row_mask:0xf bank_mask:0xf
	v_mov_b32_dpp v5, v7 row_shr:2 row_mask:0xf bank_mask:0xf
	v_mov_b32_dpp v74, v20 row_shr:1 row_mask:0xf bank_mask:0xf
	v_mov_b32_dpp v75, v21 row_shr:1 row_mask:0xf bank_mask:0xf
	v_cvt_pk_bf16_f32 v19, v18, v19
	v_cvt_pk_bf16_f32 v18, v72, v73
	v_pk_fma_f32 v[72:73], v[52:53], v[78:79], v[40:41]
	v_mov_b32_dpp v0, v6 row_shr:1 row_mask:0xf bank_mask:0xf
	v_mov_b32_dpp v1, v7 row_shr:1 row_mask:0xf bank_mask:0xf
	v_pk_fma_f32 v[4:5], v[54:55], v[4:5], v[42:43]
	v_pk_fma_f32 v[72:73], v[56:57], v[74:75], v[72:73]
	v_pk_fma_f32 v[0:1], v[58:59], v[0:1], v[4:5]
	v_pk_fma_f32 v[20:21], v[20:21], v[60:61], v[72:73]
	v_pk_fma_f32 v[0:1], v[6:7], v[62:63], v[0:1]
	v_pk_mul_f32 v[72:73], v[20:21], s[0:1] op_sel_hi:[1,0]
	v_pk_mul_f32 v[4:5], v[0:1], s[0:1] op_sel_hi:[1,0]
	v_exp_f32_e32 v72, v72
	v_exp_f32_e32 v73, v73
	v_exp_f32_e32 v4, v4
	v_exp_f32_e32 v5, v5
	v_pk_add_f32 v[72:73], v[72:73], 1.0 op_sel_hi:[1,0]
	v_pk_add_f32 v[4:5], v[4:5], 1.0 op_sel_hi:[1,0]
	v_mov_b32_dpp v82, v24 row_ror:2 row_mask:0xf bank_mask:0xf
	v_mov_b32_dpp v83, v25 row_ror:2 row_mask:0xf bank_mask:0xf
	v_rcp_f32_e32 v72, v72
	v_rcp_f32_e32 v73, v73
	v_mov_b32_dpp v12, v10 row_ror:2 row_mask:0xf bank_mask:0xf
	v_mov_b32_dpp v13, v11 row_ror:2 row_mask:0xf bank_mask:0xf
	v_rcp_f32_e32 v4, v4
	v_rcp_f32_e32 v5, v5
	v_mov_b32_dpp v80, v24 row_ror:1 row_mask:0xf bank_mask:0xf
	v_mov_b32_dpp v81, v25 row_ror:1 row_mask:0xf bank_mask:0xf
	v_mov_b32_dpp v82, v16 row_shr:2 row_mask:0xf bank_mask:0xf
	v_mov_b32_dpp v83, v17 row_shr:2 row_mask:0xf bank_mask:0xf
	v_mov_b32_dpp v8, v10 row_ror:1 row_mask:0xf bank_mask:0xf
	v_mov_b32_dpp v9, v11 row_ror:1 row_mask:0xf bank_mask:0xf
	v_mov_b32_dpp v12, v2 row_shr:2 row_mask:0xf bank_mask:0xf
	v_mov_b32_dpp v13, v3 row_shr:2 row_mask:0xf bank_mask:0xf
	v_mov_b32_dpp v80, v16 row_shr:1 row_mask:0xf bank_mask:0xf
	v_mov_b32_dpp v81, v17 row_shr:1 row_mask:0xf bank_mask:0xf
	v_pk_fma_f32 v[74:75], v[36:37], v[82:83], v[32:33]
	v_mov_b32_dpp v8, v2 row_shr:1 row_mask:0xf bank_mask:0xf
	v_mov_b32_dpp v9, v3 row_shr:1 row_mask:0xf bank_mask:0xf
	v_pk_fma_f32 v[6:7], v[38:39], v[12:13], v[34:35]
	v_pk_fma_f32 v[74:75], v[44:45], v[80:81], v[74:75]
	v_pk_fma_f32 v[6:7], v[46:47], v[8:9], v[6:7]
	v_pk_fma_f32 v[16:17], v[16:17], v[48:49], v[74:75]
	v_pk_mul_f32 v[20:21], v[20:21], v[72:73]
	v_pk_fma_f32 v[2:3], v[2:3], v[50:51], v[6:7]
	v_pk_mul_f32 v[0:1], v[0:1], v[4:5]
	v_pk_mul_f32 v[16:17], v[16:17], v[20:21]
	v_pk_mul_f32 v[0:1], v[2:3], v[0:1]
	v_cvt_pk_bf16_f32 v23, v22, v23
	v_cvt_pk_bf16_f32 v30, v30, v31
	v_cvt_pk_bf16_f32 v22, v16, v17
	v_cvt_pk_bf16_f32 v31, v0, v1
	global_store_dwordx2 v[64:65], v[26:27], off offset:8
	global_store_dwordx2 v[66:67], v[22:23], off offset:8
	global_store_dwordx2 v[68:69], v[18:19], off offset:8
	global_store_dwordx2 v[70:71], v[30:31], off offset:8
	s_and_b64 vcc, exec, s[8:9]
	s_mov_b64 s[8:9], -1
	s_cbranch_vccnz .LBB0_1108
	s_andn2_b64 vcc, exec, s[2:3]
	s_cbranch_vccnz .LBB0_1107
	s_barrier
	s_branch .LBB0_1107

; #define LAS __attribute__((address_space(3)))
; DI float rs_from_ss(u64 ssq) { return rsqrtf((float)ssq * (1.f / (1048576.f * 1024.f)) + EPS); }
;     DI void operator()(const AccT& acc, const Unit& u, int wr, int wc, int fr, int fq) const {
;         const int cl = u.pn * 128 + wc * 32 + 8 * fq;
;         LAS float* P = (LAS float*)(plds + (wr * 4 + wc) * 1024);
;         { const int lane = fq * 16 + fr, kind = lane >> 3, c4 = 4 * (lane & 7), k3 = kind & 3;
;           const float* src = (k3 == 0 ? cb : cw + (k3 - 1) * 5632) + (kind >= 4 ? 2816 : 0) + u.pn * 128 + wc * 32 + c4;
;           *(LAS f32x4*)(P + kind * 32 + c4) = *(const f32x4*)src; }
; #pragma unroll
;         for (int ai = 0; ai < 2; ++ai) {
;             const int tok0 = u.pm * 248 + 62 * (2 * ai + wr) - 2 + fr;
;             float rs[4];
; #pragma unroll
;             for (int m = 0; m < 4; ++m) { const int t = tok0 + 16 * m; const int tc = t < 0 ? 0 : (t >= S ? S - 1 : t); const float r = rs_from_ss(rowss[tc]); rs[m] = t < 0 ? 0.f : r; }
;             const int row0 = fr < 2 ? (S + 236 + fr) : tok0;
; #pragma unroll
;             for (int n = 0; n < 2; ++n) {
;                 const int lc = 8 * fq + 4 * n;
;                 unsigned wpk[4][2];
; #pragma unroll
;                 for (int jp = 0; jp < 2; ++jp) {
;                     const f32x2 bg = *(const LAS f32x2*)(P + lc + 2 * jp), g0 = *(const LAS f32x2*)(P + 32 + lc + 2 * jp), g1 = *(const LAS f32x2*)(P + 64 + lc + 2 * jp), g2 = *(const LAS f32x2*)(P + 96 + lc + 2 * jp);
;                     const f32x2 bv = *(const LAS f32x2*)(P + 128 + lc + 2 * jp), v0 = *(const LAS f32x2*)(P + 160 + lc + 2 * jp), v1 = *(const LAS f32x2*)(P + 192 + lc + 2 * jp), v2 = *(const LAS f32x2*)(P + 224 + lc + 2 * jp);
;                     f32x2 G[4], V[4];
; #pragma unroll
;                     for (int m = 0; m < 4; ++m) { G[m] = (f32x2){acc[ai][0][m][n][2 * jp], acc[ai][0][m][n][2 * jp + 1]} * rs[m]; V[m] = (f32x2){acc[ai][1][m][n][2 * jp], acc[ai][1][m][n][2 * jp + 1]} * rs[m]; }
.LBB0_1831:
	s_lshl_b32 s8, s58, 7
	s_ashr_i32 s9, s8, 31
	v_lshl_add_u64 v[128:129], s[8:9], 2, v[168:169]
	s_mul_i32 s9, s57, 0xf8
	v_add_u32_e32 v197, s9, v170
	v_med3_i32 v132, v197, 0, s51
	v_lshlrev_b32_e32 v132, 3, v132
	global_load_dwordx2 v[180:181], v132, s[18:19]
	v_add_u32_e32 v198, 16, v197
	v_med3_i32 v132, v198, 0, s51
	v_add_u32_e32 v199, 32, v197
	v_add_u32_e32 v200, 48, v197
	v_lshlrev_b32_e32 v132, 3, v132
	v_med3_i32 v133, v199, 0, s51
	v_med3_i32 v134, v200, 0, s51
	global_load_dwordx4 v[128:131], v[128:129], off
	v_lshlrev_b32_e32 v133, 3, v133
	v_lshlrev_b32_e32 v134, 3, v134
	global_load_dwordx2 v[182:183], v132, s[18:19]
	global_load_dwordx2 v[202:203], v133, s[18:19]
	global_load_dwordx2 v[204:205], v134, s[18:19]
	v_or_b32_e32 v188, s8, v187
	v_ashrrev_i32_e32 v189, 31, v188
	v_cndmask_b32_e64 v201, v197, v190, s[4:5]
	s_waitcnt vmcnt(0)
	v_add_u32_e32 v250, 0x7c, v197
	v_med3_i32 v250, v250, 0, s51
	v_lshlrev_b32_e32 v250, 3, v250
	global_load_dwordx2 v[242:243], v250, s[18:19]
	v_add_u32_e32 v250, 0x8c, v197
	v_med3_i32 v250, v250, 0, s51
	v_lshlrev_b32_e32 v250, 3, v250
	global_load_dwordx2 v[244:245], v250, s[18:19]
	v_add_u32_e32 v250, 0x9c, v197
	v_med3_i32 v250, v250, 0, s51
	v_lshlrev_b32_e32 v250, 3, v250
	global_load_dwordx2 v[246:247], v250, s[18:19]
	v_add_u32_e32 v250, 0xac, v197
	v_med3_i32 v250, v250, 0, s51
	v_lshlrev_b32_e32 v250, 3, v250
	global_load_dwordx2 v[248:249], v250, s[18:19]
	v_ffbh_u32_e32 v184, v181
	v_min_u32_e32 v184, 32, v184
	v_lshlrev_b64 v[180:181], v184, v[180:181]
	v_min_u32_e32 v180, 1, v180
	v_or_b32_e32 v180, v181, v180
	v_cvt_f32_u32_e32 v180, v180
	v_sub_u32_e32 v184, 32, v184
	ds_write_b128 v191, v[128:131]
	v_ffbh_u32_e32 v186, v183
	v_ffbh_u32_e32 v206, v203
	v_min_u32_e32 v186, 32, v186
	v_ffbh_u32_e32 v207, v205
	v_min_u32_e32 v206, 32, v206
	v_lshlrev_b64 v[182:183], v186, v[182:183]
	v_min_u32_e32 v207, 32, v207
	v_lshlrev_b64 v[202:203], v206, v[202:203]
	v_min_u32_e32 v181, 1, v182
	v_lshlrev_b64 v[204:205], v207, v[204:205]
	v_min_u32_e32 v182, 1, v202
	v_or_b32_e32 v181, v183, v181
	v_min_u32_e32 v202, 1, v204
	v_or_b32_e32 v182, v203, v182
	v_cvt_f32_u32_e32 v181, v181
	v_or_b32_e32 v183, v205, v202
	v_cvt_f32_u32_e32 v182, v182
	v_cvt_f32_u32_e32 v183, v183
	v_sub_u32_e32 v186, 32, v186
	v_ldexp_f32 v180, v180, v184
	v_sub_u32_e32 v206, 32, v206
	v_fmamk_f32 v180, v180, 0x30800000, v196
	v_ldexp_f32 v181, v181, v186
	v_sub_u32_e32 v207, 32, v207
	v_ldexp_f32 v182, v182, v206
	v_mul_f32_e32 v184, 0x4b800000, v180
	v_fmamk_f32 v181, v181, 0x30800000, v196
	v_cmp_gt_f32_e32 vcc, s52, v180
	v_ldexp_f32 v183, v183, v207
	v_fmamk_f32 v182, v182, 0x30800000, v196
	v_cndmask_b32_e32 v180, v180, v184, vcc
	v_mul_f32_e32 v184, 0x4b800000, v181
	v_cmp_gt_f32_e64 s[8:9], s52, v181
	v_fmamk_f32 v183, v183, 0x30800000, v196
	v_mul_f32_e32 v186, 0x4b800000, v182
	v_rsq_f32_e32 v180, v180
	v_cndmask_b32_e64 v181, v181, v184, s[8:9]
	v_cmp_gt_f32_e64 s[10:11], s52, v182
	v_mul_f32_e32 v202, 0x4b800000, v183
	v_cmp_gt_f32_e64 s[12:13], s52, v183
	v_cndmask_b32_e64 v182, v182, v186, s[10:11]
	v_rsq_f32_e32 v181, v181
	v_cndmask_b32_e64 v183, v183, v202, s[12:13]
	v_rsq_f32_e32 v182, v182
	v_rsq_f32_e32 v183, v183
	v_mul_f32_e32 v184, 0x45800000, v180
	v_cndmask_b32_e32 v180, v180, v184, vcc
	v_mul_f32_e32 v184, 0x45800000, v181
	v_cmp_lt_i32_e32 vcc, -1, v197
	v_mul_f32_e32 v202, 0x45800000, v182
	v_mul_f32_e32 v203, 0x45800000, v183
	v_cndmask_b32_e32 v186, 0, v180, vcc
	v_cndmask_b32_e64 v180, v181, v184, s[8:9]
	v_cmp_lt_i32_e32 vcc, s53, v197
	v_cndmask_b32_e64 v181, v182, v202, s[10:11]
	v_cndmask_b32_e64 v183, v183, v203, s[12:13]
	v_cndmask_b32_e32 v184, 0, v180, vcc
	v_cmp_lt_i32_e32 vcc, s54, v197
	v_pk_mul_f32 v[124:125], v[124:125], v[186:187] op_sel_hi:[1,0]
	ds_read_b128 v[136:139], v193
	ds_read_b128 v[148:151], v193 offset:128
	ds_read_b128 v[152:155], v193 offset:256
	ds_read_b128 v[156:159], v193 offset:384
	ds_read_b128 v[128:131], v193 offset:512
	ds_read_b128 v[132:135], v193 offset:640
	ds_read_b128 v[140:143], v193 offset:768
	ds_read_b128 v[144:147], v193 offset:896
	v_cndmask_b32_e32 v182, 0, v181, vcc
	v_cmp_lt_i32_e32 vcc, s55, v197
	v_pk_mul_f32 v[108:109], v[108:109], v[182:183] op_sel_hi:[1,0]
	v_pk_mul_f32 v[202:203], v[104:105], v[182:183] op_sel_hi:[1,0]
	v_cndmask_b32_e32 v180, 0, v183, vcc
	v_mov_b32_e32 v183, 0
	v_pk_mul_f32 v[204:205], v[100:101], v[180:181] op_sel_hi:[1,0]
	v_pk_mul_f32 v[206:207], v[96:97], v[180:181] op_sel_hi:[1,0]
	v_mov_b32_e32 v181, 0
	v_mov_b32_dpp v183, v183 row_ror:2 row_mask:0xf bank_mask:0xf
	v_mov_b32_e32 v100, v183
	v_mov_b32_dpp v181, v181 row_ror:1 row_mask:0xf bank_mask:0xf
	v_mov_b32_e32 v101, v183
	v_mov_b32_e32 v96, v181
	v_mov_b32_e32 v97, v181
	v_mov_b32_dpp v100, v124 row_shr:2 row_mask:0xf bank_mask:0xf
	v_mov_b32_dpp v101, v125 row_shr:2 row_mask:0xf bank_mask:0xf
	v_mov_b32_dpp v96, v124 row_shr:1 row_mask:0xf bank_mask:0xf
	v_mov_b32_dpp v97, v125 row_shr:1 row_mask:0xf bank_mask:0xf
	s_waitcnt lgkmcnt(6)
	v_pk_fma_f32 v[100:101], v[148:149], v[100:101], v[136:137]
	v_pk_mul_f32 v[120:121], v[120:121], v[186:187] op_sel_hi:[1,0]
	s_waitcnt lgkmcnt(5)
	v_pk_fma_f32 v[96:97], v[152:153], v[96:97], v[100:101]
	v_mov_b32_e32 v208, v183
	s_waitcnt lgkmcnt(4)
	v_pk_fma_f32 v[96:97], v[156:157], v[124:125], v[96:97]
	v_mov_b32_e32 v209, v183
	v_pk_mul_f32 v[100:101], v[96:97], s[2:3] op_sel_hi:[1,0]
	v_mov_b32_e32 v104, v181
	v_exp_f32_e32 v100, v100
	v_exp_f32_e32 v101, v101
	v_mov_b32_e32 v105, v181
	v_mov_b32_dpp v208, v120 row_shr:2 row_mask:0xf bank_mask:0xf
	v_mov_b32_dpp v209, v121 row_shr:2 row_mask:0xf bank_mask:0xf
	v_pk_add_f32 v[100:101], v[100:101], 1.0 op_sel_hi:[1,0]
	v_mov_b32_dpp v104, v120 row_shr:1 row_mask:0xf bank_mask:0xf
	v_rcp_f32_e32 v100, v100
	v_rcp_f32_e32 v101, v101
	v_mov_b32_dpp v105, v121 row_shr:1 row_mask:0xf bank_mask:0xf
	s_waitcnt lgkmcnt(2)
; #define LAS __attribute__((address_space(3)))
; DI unsigned pk2(float lo, float hi) { f32x2 v = {lo, hi}; bf16x2_t b = __builtin_convertvector(v, bf16x2_t); return __builtin_bit_cast(unsigned, b); }
;     DI void operator()(const AccT& acc, const Unit& u, int wr, int wc, int fr, int fq) const {
;     ...
;                     const f32x2 bg = *(const LAS f32x2*)(P + lc + 2 * jp), g0 = *(const LAS f32x2*)(P + 32 + lc + 2 * jp), g1 = *(const LAS f32x2*)(P + 64 + lc + 2 * jp), g2 = *(const LAS f32x2*)(P + 96 + lc + 2 * jp);
;                     const f32x2 bv = *(const LAS f32x2*)(P + 128 + lc + 2 * jp), v0 = *(const LAS f32x2*)(P + 160 + lc + 2 * jp), v1 = *(const LAS f32x2*)(P + 192 + lc + 2 * jp), v2 = *(const LAS f32x2*)(P + 224 + lc + 2 * jp);
;                     f32x2 G[4], V[4];
; #pragma unroll
;                     for (int m = 0; m < 4; ++m) { G[m] = (f32x2){acc[ai][0][m][n][2 * jp], acc[ai][0][m][n][2 * jp + 1]} * rs[m]; V[m] = (f32x2){acc[ai][1][m][n][2 * jp], acc[ai][1][m][n][2 * jp + 1]} * rs[m]; }
; #pragma unroll
;                     for (int m = 0; m < 4; ++m) {
;                         const f32x2 zz = {0.f, 0.f}; const f32x2 Gp = m ? G[m - 1] : zz, Vp = m ? V[m - 1] : zz;
;                         const f32x2 gp1 = {dpp_prev1(G[m].x, Gp.x), dpp_prev1(G[m].y, Gp.y)}, gp2 = {dpp_prev2(G[m].x, Gp.x), dpp_prev2(G[m].y, Gp.y)};
;                         const f32x2 vp1 = {dpp_prev1(V[m].x, Vp.x), dpp_prev1(V[m].y, Vp.y)}, vp2 = {dpp_prev2(V[m].x, Vp.x), dpp_prev2(V[m].y, Vp.y)};
;                         const f32x2 gc = bg + g0 * gp2 + g1 * gp1 + g2 * G[m];
;                         const f32x2 vc = bv + v0 * vp2 + v1 * vp1 + v2 * V[m];
;                         const f32x2 xe = gc * (-LOG2E);
;                         f32x2 dn = {__builtin_amdgcn_exp2f(xe.x), __builtin_amdgcn_exp2f(xe.y)}; dn = dn + 1.0f;
;                         const f32x2 rc = {__builtin_amdgcn_rcpf(dn.x), __builtin_amdgcn_rcpf(dn.y)};
;                         const f32x2 rr = gc * rc * vc;
;                         wpk[m][jp] = pk2(rr.x, rr.y); }
	v_pk_fma_f32 v[208:209], v[132:133], v[208:209], v[128:129]
	v_pk_mul_f32 v[116:117], v[116:117], v[184:185] op_sel_hi:[1,0]
	s_waitcnt lgkmcnt(1)
	v_pk_fma_f32 v[104:105], v[140:141], v[104:105], v[208:209]
	v_pk_mul_f32 v[96:97], v[96:97], v[100:101]
	s_waitcnt lgkmcnt(0)
	v_pk_fma_f32 v[104:105], v[144:145], v[120:121], v[104:105]
	v_pk_mul_f32 v[96:97], v[104:105], v[96:97]
	v_mov_b32_dpp v104, v124 row_ror:2 row_mask:0xf bank_mask:0xf
	v_mov_b32_dpp v105, v125 row_ror:2 row_mask:0xf bank_mask:0xf
	v_mov_b32_dpp v100, v124 row_ror:1 row_mask:0xf bank_mask:0xf
	v_mov_b32_dpp v101, v125 row_ror:1 row_mask:0xf bank_mask:0xf
	v_mov_b32_dpp v104, v116 row_shr:2 row_mask:0xf bank_mask:0xf
	v_mov_b32_dpp v105, v117 row_shr:2 row_mask:0xf bank_mask:0xf
	v_mov_b32_dpp v100, v116 row_shr:1 row_mask:0xf bank_mask:0xf
	v_mov_b32_dpp v101, v117 row_shr:1 row_mask:0xf bank_mask:0xf
	v_pk_fma_f32 v[104:105], v[148:149], v[104:105], v[136:137]
	v_pk_fma_f32 v[100:101], v[152:153], v[100:101], v[104:105]
	v_pk_fma_f32 v[100:101], v[156:157], v[116:117], v[100:101]
	v_pk_mul_f32 v[112:113], v[112:113], v[184:185] op_sel_hi:[1,0]
	v_pk_mul_f32 v[104:105], v[100:101], s[2:3] op_sel_hi:[1,0]
	v_exp_f32_e32 v104, v104
	v_exp_f32_e32 v105, v105
	v_mov_b32_dpp v208, v120 row_ror:2 row_mask:0xf bank_mask:0xf
	v_mov_b32_dpp v209, v121 row_ror:2 row_mask:0xf bank_mask:0xf
	v_pk_add_f32 v[104:105], v[104:105], 1.0 op_sel_hi:[1,0]
	v_mov_b32_dpp v124, v120 row_ror:1 row_mask:0xf bank_mask:0xf
	v_rcp_f32_e32 v104, v104
	v_rcp_f32_e32 v105, v105
	v_mov_b32_dpp v125, v121 row_ror:1 row_mask:0xf bank_mask:0xf
	v_mov_b32_dpp v208, v112 row_shr:2 row_mask:0xf bank_mask:0xf
	v_mov_b32_dpp v209, v113 row_shr:2 row_mask:0xf bank_mask:0xf
	v_mov_b32_dpp v124, v112 row_shr:1 row_mask:0xf bank_mask:0xf
	v_mov_b32_dpp v125, v113 row_shr:1 row_mask:0xf bank_mask:0xf
	v_pk_fma_f32 v[120:121], v[132:133], v[208:209], v[128:129]
	v_pk_mul_f32 v[100:101], v[100:101], v[104:105]
	v_pk_fma_f32 v[120:121], v[140:141], v[124:125], v[120:121]
	v_pk_fma_f32 v[120:121], v[144:145], v[112:113], v[120:121]
	v_pk_mul_f32 v[100:101], v[120:121], v[100:101]
	v_mov_b32_dpp v104, v116 row_ror:1 row_mask:0xf bank_mask:0xf
	v_mov_b32_dpp v120, v116 row_ror:2 row_mask:0xf bank_mask:0xf
	v_mov_b32_dpp v121, v117 row_ror:2 row_mask:0xf bank_mask:0xf
	v_mov_b32_dpp v105, v117 row_ror:1 row_mask:0xf bank_mask:0xf
	v_mov_b32_dpp v120, v108 row_shr:2 row_mask:0xf bank_mask:0xf
	v_mov_b32_dpp v121, v109 row_shr:2 row_mask:0xf bank_mask:0xf
	v_mov_b32_dpp v104, v108 row_shr:1 row_mask:0xf bank_mask:0xf
	v_mov_b32_dpp v105, v109 row_shr:1 row_mask:0xf bank_mask:0xf
	v_pk_fma_f32 v[120:121], v[148:149], v[120:121], v[136:137]
	v_pk_fma_f32 v[104:105], v[152:153], v[104:105], v[120:121]
	v_pk_fma_f32 v[104:105], v[156:157], v[108:109], v[104:105]
	v_pk_mul_f32 v[120:121], v[104:105], s[2:3] op_sel_hi:[1,0]
	v_exp_f32_e32 v120, v120
	v_exp_f32_e32 v121, v121
	v_mov_b32_dpp v116, v112 row_ror:1 row_mask:0xf bank_mask:0xf
	v_mov_b32_dpp v117, v113 row_ror:1 row_mask:0xf bank_mask:0xf
	v_mov_b32_dpp v124, v112 row_ror:2 row_mask:0xf bank_mask:0xf
	v_mov_b32_dpp v125, v113 row_ror:2 row_mask:0xf bank_mask:0xf
	v_pk_add_f32 v[112:113], v[120:121], 1.0 op_sel_hi:[1,0]
	v_mov_b32_dpp v124, v202 row_shr:2 row_mask:0xf bank_mask:0xf
	v_rcp_f32_e32 v112, v112
	v_rcp_f32_e32 v113, v113
	v_mov_b32_dpp v125, v203 row_shr:2 row_mask:0xf bank_mask:0xf
	v_mov_b32_dpp v116, v202 row_shr:1 row_mask:0xf bank_mask:0xf
	v_mov_b32_dpp v117, v203 row_shr:1 row_mask:0xf bank_mask:0xf
	v_pk_fma_f32 v[120:121], v[132:133], v[124:125], v[128:129]
	v_pk_mul_f32 v[104:105], v[104:105], v[112:113]
	v_pk_fma_f32 v[116:117], v[140:141], v[116:117], v[120:121]
	v_pk_fma_f32 v[116:117], v[144:145], v[202:203], v[116:117]
	v_pk_mul_f32 v[104:105], v[116:117], v[104:105]
	v_mov_b32_dpp v112, v108 row_ror:1 row_mask:0xf bank_mask:0xf
	v_mov_b32_dpp v116, v108 row_ror:2 row_mask:0xf bank_mask:0xf
	v_mov_b32_dpp v117, v109 row_ror:2 row_mask:0xf bank_mask:0xf
	v_mov_b32_dpp v113, v109 row_ror:1 row_mask:0xf bank_mask:0xf
	v_mov_b32_dpp v116, v204 row_shr:2 row_mask:0xf bank_mask:0xf
	v_mov_b32_dpp v117, v205 row_shr:2 row_mask:0xf bank_mask:0xf
	v_mov_b32_dpp v112, v204 row_shr:1 row_mask:0xf bank_mask:0xf
	v_mov_b32_dpp v113, v205 row_shr:1 row_mask:0xf bank_mask:0xf
	v_pk_fma_f32 v[116:117], v[148:149], v[116:117], v[136:137]
	v_pk_fma_f32 v[112:113], v[152:153], v[112:113], v[116:117]
	v_pk_fma_f32 v[112:113], v[156:157], v[204:205], v[112:113]
	v_pk_mul_f32 v[116:117], v[112:113], s[2:3] op_sel_hi:[1,0]
	v_exp_f32_e32 v116, v116
	v_exp_f32_e32 v117, v117
	v_mov_b32_dpp v120, v202 row_ror:2 row_mask:0xf bank_mask:0xf
	v_mov_b32_dpp v121, v203 row_ror:2 row_mask:0xf bank_mask:0xf
	v_mov_b32_dpp v108, v202 row_ror:1 row_mask:0xf bank_mask:0xf
	v_pk_add_f32 v[116:117], v[116:117], 1.0 op_sel_hi:[1,0]
	v_mov_b32_dpp v109, v203 row_ror:1 row_mask:0xf bank_mask:0xf
	v_rcp_f32_e32 v116, v116
	v_rcp_f32_e32 v117, v117
	v_mov_b32_dpp v120, v206 row_shr:2 row_mask:0xf bank_mask:0xf
	v_mov_b32_dpp v121, v207 row_shr:2 row_mask:0xf bank_mask:0xf
	v_mov_b32_dpp v108, v206 row_shr:1 row_mask:0xf bank_mask:0xf
	v_mov_b32_dpp v109, v207 row_shr:1 row_mask:0xf bank_mask:0xf
	v_pk_fma_f32 v[120:121], v[132:133], v[120:121], v[128:129]
	v_pk_mul_f32 v[112:113], v[112:113], v[116:117]
	v_pk_fma_f32 v[108:109], v[140:141], v[108:109], v[120:121]
	v_pk_mul_f32 v[116:117], v[122:123], v[186:187] op_sel_hi:[1,0]
	v_pk_fma_f32 v[108:109], v[144:145], v[206:207], v[108:109]
	v_mov_b32_e32 v122, v183
	v_pk_mul_f32 v[108:109], v[108:109], v[112:113]
; #define LAS __attribute__((address_space(3)))
; DI unsigned pk2(float lo, float hi) { f32x2 v = {lo, hi}; bf16x2_t b = __builtin_convertvector(v, bf16x2_t); return __builtin_bit_cast(unsigned, b); }
;     DI void operator()(const AccT& acc, const Unit& u, int wr, int wc, int fr, int fq) const {
;     ...
;                     const f32x2 bg = *(const LAS f32x2*)(P + lc + 2 * jp), g0 = *(const LAS f32x2*)(P + 32 + lc + 2 * jp), g1 = *(const LAS f32x2*)(P + 64 + lc + 2 * jp), g2 = *(const LAS f32x2*)(P + 96 + lc + 2 * jp);
;                     const f32x2 bv = *(const LAS f32x2*)(P + 128 + lc + 2 * jp), v0 = *(const LAS f32x2*)(P + 160 + lc + 2 * jp), v1 = *(const LAS f32x2*)(P + 192 + lc + 2 * jp), v2 = *(const LAS f32x2*)(P + 224 + lc + 2 * jp);
;                     f32x2 G[4], V[4];
; #pragma unroll
;                     for (int m = 0; m < 4; ++m) { G[m] = (f32x2){acc[ai][0][m][n][2 * jp], acc[ai][0][m][n][2 * jp + 1]} * rs[m]; V[m] = (f32x2){acc[ai][1][m][n][2 * jp], acc[ai][1][m][n][2 * jp + 1]} * rs[m]; }
; #pragma unroll
;                     for (int m = 0; m < 4; ++m) {
;                         const f32x2 zz = {0.f, 0.f}; const f32x2 Gp = m ? G[m - 1] : zz, Vp = m ? V[m - 1] : zz;
;                         const f32x2 gp1 = {dpp_prev1(G[m].x, Gp.x), dpp_prev1(G[m].y, Gp.y)}, gp2 = {dpp_prev2(G[m].x, Gp.x), dpp_prev2(G[m].y, Gp.y)};
;                         const f32x2 vp1 = {dpp_prev1(V[m].x, Vp.x), dpp_prev1(V[m].y, Vp.y)}, vp2 = {dpp_prev2(V[m].x, Vp.x), dpp_prev2(V[m].y, Vp.y)};
;                         const f32x2 gc = bg + g0 * gp2 + g1 * gp1 + g2 * G[m];
;                         const f32x2 vc = bv + v0 * vp2 + v1 * vp1 + v2 * V[m];
;                         const f32x2 xe = gc * (-LOG2E);
;                         f32x2 dn = {__builtin_amdgcn_exp2f(xe.x), __builtin_amdgcn_exp2f(xe.y)}; dn = dn + 1.0f;
;                         const f32x2 rc = {__builtin_amdgcn_rcpf(dn.x), __builtin_amdgcn_rcpf(dn.y)};
;                         const f32x2 rr = gc * rc * vc;
;                         wpk[m][jp] = pk2(rr.x, rr.y); }
	v_pk_mul_f32 v[112:113], v[126:127], v[186:187] op_sel_hi:[1,0]
	v_mov_b32_e32 v123, v183
	v_mov_b32_e32 v120, v181
	v_mov_b32_e32 v121, v181
	v_mov_b32_dpp v122, v112 row_shr:2 row_mask:0xf bank_mask:0xf
	v_mov_b32_dpp v123, v113 row_shr:2 row_mask:0xf bank_mask:0xf
	v_mov_b32_dpp v120, v112 row_shr:1 row_mask:0xf bank_mask:0xf
	v_mov_b32_dpp v121, v113 row_shr:1 row_mask:0xf bank_mask:0xf
	v_pk_fma_f32 v[122:123], v[150:151], v[122:123], v[138:139]
	v_mov_b32_e32 v126, v183
	v_pk_fma_f32 v[120:121], v[154:155], v[120:121], v[122:123]
	v_mov_b32_e32 v127, v183
	v_pk_fma_f32 v[120:121], v[112:113], v[158:159], v[120:121]
	v_mov_b32_e32 v124, v181
	v_pk_mul_f32 v[122:123], v[120:121], s[2:3] op_sel_hi:[1,0]
	v_mov_b32_e32 v125, v181
	v_exp_f32_e32 v122, v122
	v_exp_f32_e32 v123, v123
	v_mov_b32_dpp v126, v116 row_shr:2 row_mask:0xf bank_mask:0xf
	v_mov_b32_dpp v127, v117 row_shr:2 row_mask:0xf bank_mask:0xf
	v_mov_b32_dpp v124, v116 row_shr:1 row_mask:0xf bank_mask:0xf
	v_pk_add_f32 v[122:123], v[122:123], 1.0 op_sel_hi:[1,0]
	v_mov_b32_dpp v125, v117 row_shr:1 row_mask:0xf bank_mask:0xf
	v_rcp_f32_e32 v122, v122
	v_rcp_f32_e32 v123, v123
	v_pk_fma_f32 v[126:127], v[134:135], v[126:127], v[130:131]
	v_cvt_pk_bf16_f32 v96, v96, v97
	v_pk_fma_f32 v[124:125], v[142:143], v[124:125], v[126:127]
	v_pk_mul_f32 v[120:121], v[120:121], v[122:123]
	v_pk_fma_f32 v[124:125], v[116:117], v[146:147], v[124:125]
	v_pk_mul_f32 v[120:121], v[124:125], v[120:121]
	v_pk_mul_f32 v[118:119], v[118:119], v[184:185] op_sel_hi:[1,0]
	v_cvt_pk_bf16_f32 v97, v120, v121
	v_mov_b32_dpp v122, v112 row_ror:2 row_mask:0xf bank_mask:0xf
	v_mov_b32_dpp v123, v113 row_ror:2 row_mask:0xf bank_mask:0xf
	v_mov_b32_dpp v120, v112 row_ror:1 row_mask:0xf bank_mask:0xf
	v_mov_b32_dpp v121, v113 row_ror:1 row_mask:0xf bank_mask:0xf
	v_mov_b32_dpp v122, v118 row_shr:2 row_mask:0xf bank_mask:0xf
	v_mov_b32_dpp v123, v119 row_shr:2 row_mask:0xf bank_mask:0xf
	v_mov_b32_dpp v120, v118 row_shr:1 row_mask:0xf bank_mask:0xf
	v_mov_b32_dpp v121, v119 row_shr:1 row_mask:0xf bank_mask:0xf
	v_pk_fma_f32 v[122:123], v[150:151], v[122:123], v[138:139]
	v_pk_fma_f32 v[120:121], v[154:155], v[120:121], v[122:123]
	v_pk_fma_f32 v[120:121], v[118:119], v[158:159], v[120:121]
	v_pk_mul_f32 v[122:123], v[120:121], s[2:3] op_sel_hi:[1,0]
	v_exp_f32_e32 v122, v122
	v_exp_f32_e32 v123, v123
	v_mov_b32_dpp v112, v116 row_ror:1 row_mask:0xf bank_mask:0xf
	v_mov_b32_dpp v113, v117 row_ror:1 row_mask:0xf bank_mask:0xf
	v_mov_b32_dpp v124, v116 row_ror:2 row_mask:0xf bank_mask:0xf
	v_mov_b32_dpp v125, v117 row_ror:2 row_mask:0xf bank_mask:0xf
	v_pk_add_f32 v[116:117], v[122:123], 1.0 op_sel_hi:[1,0]
	v_pk_mul_f32 v[114:115], v[114:115], v[184:185] op_sel_hi:[1,0]
	v_rcp_f32_e32 v116, v116
	v_rcp_f32_e32 v117, v117
	v_mov_b32_dpp v124, v114 row_shr:2 row_mask:0xf bank_mask:0xf
	v_mov_b32_dpp v125, v115 row_shr:2 row_mask:0xf bank_mask:0xf
	v_mov_b32_dpp v112, v114 row_shr:1 row_mask:0xf bank_mask:0xf
	v_mov_b32_dpp v113, v115 row_shr:1 row_mask:0xf bank_mask:0xf
	v_pk_fma_f32 v[122:123], v[134:135], v[124:125], v[130:131]
	v_pk_mul_f32 v[116:117], v[120:121], v[116:117]
	v_pk_fma_f32 v[112:113], v[142:143], v[112:113], v[122:123]
	v_cvt_pk_bf16_f32 v100, v100, v101
	v_pk_fma_f32 v[112:113], v[114:115], v[146:147], v[112:113]
	v_pk_mul_f32 v[110:111], v[110:111], v[182:183] op_sel_hi:[1,0]
	v_pk_mul_f32 v[112:113], v[112:113], v[116:117]
	v_cvt_pk_bf16_f32 v101, v112, v113
	v_mov_b32_dpp v116, v118 row_ror:2 row_mask:0xf bank_mask:0xf
	v_mov_b32_dpp v117, v119 row_ror:2 row_mask:0xf bank_mask:0xf
	v_mov_b32_dpp v112, v118 row_ror:1 row_mask:0xf bank_mask:0xf
	v_mov_b32_dpp v113, v119 row_ror:1 row_mask:0xf bank_mask:0xf
	v_mov_b32_dpp v116, v110 row_shr:2 row_mask:0xf bank_mask:0xf
	v_mov_b32_dpp v117, v111 row_shr:2 row_mask:0xf bank_mask:0xf
	v_mov_b32_dpp v112, v110 row_shr:1 row_mask:0xf bank_mask:0xf
	v_mov_b32_dpp v113, v111 row_shr:1 row_mask:0xf bank_mask:0xf
	v_pk_fma_f32 v[116:117], v[150:151], v[116:117], v[138:139]
	v_pk_fma_f32 v[112:113], v[154:155], v[112:113], v[116:117]
	v_pk_fma_f32 v[112:113], v[110:111], v[158:159], v[112:113]
	v_pk_mul_f32 v[116:117], v[112:113], s[2:3] op_sel_hi:[1,0]
	v_exp_f32_e32 v116, v116
	v_exp_f32_e32 v117, v117
	v_mov_b32_dpp v118, v114 row_ror:1 row_mask:0xf bank_mask:0xf
	v_mov_b32_dpp v119, v115 row_ror:1 row_mask:0xf bank_mask:0xf
	v_mov_b32_dpp v120, v114 row_ror:2 row_mask:0xf bank_mask:0xf
	v_mov_b32_dpp v121, v115 row_ror:2 row_mask:0xf bank_mask:0xf
	v_pk_add_f32 v[114:115], v[116:117], 1.0 op_sel_hi:[1,0]
	v_pk_mul_f32 v[106:107], v[106:107], v[182:183] op_sel_hi:[1,0]
	v_rcp_f32_e32 v114, v114
	v_rcp_f32_e32 v115, v115
	v_mov_b32_dpp v120, v106 row_shr:2 row_mask:0xf bank_mask:0xf
	v_mov_b32_dpp v121, v107 row_shr:2 row_mask:0xf bank_mask:0xf
	v_mov_b32_dpp v118, v106 row_shr:1 row_mask:0xf bank_mask:0xf
	v_mov_b32_dpp v119, v107 row_shr:1 row_mask:0xf bank_mask:0xf
	v_pk_fma_f32 v[116:117], v[134:135], v[120:121], v[130:131]
	v_pk_mul_f32 v[112:113], v[112:113], v[114:115]
	v_pk_fma_f32 v[116:117], v[142:143], v[118:119], v[116:117]
	v_pk_fma_f32 v[116:117], v[106:107], v[146:147], v[116:117]
	v_pk_mul_f32 v[112:113], v[116:117], v[112:113]
	v_cvt_pk_bf16_f32 v104, v104, v105
	v_pk_mul_f32 v[102:103], v[102:103], v[180:181] op_sel_hi:[1,0]
	v_cvt_pk_bf16_f32 v105, v112, v113
	v_mov_b32_dpp v114, v110 row_ror:2 row_mask:0xf bank_mask:0xf
	v_mov_b32_dpp v115, v111 row_ror:2 row_mask:0xf bank_mask:0xf
	v_mov_b32_dpp v112, v110 row_ror:1 row_mask:0xf bank_mask:0xf
	v_mov_b32_dpp v113, v111 row_ror:1 row_mask:0xf bank_mask:0xf
; #define LAS __attribute__((address_space(3)))
; DI unsigned pk2(float lo, float hi) { f32x2 v = {lo, hi}; bf16x2_t b = __builtin_convertvector(v, bf16x2_t); return __builtin_bit_cast(unsigned, b); }
;     DI void operator()(const AccT& acc, const Unit& u, int wr, int wc, int fr, int fq) const {
;     ...
;                     const f32x2 bg = *(const LAS f32x2*)(P + lc + 2 * jp), g0 = *(const LAS f32x2*)(P + 32 + lc + 2 * jp), g1 = *(const LAS f32x2*)(P + 64 + lc + 2 * jp), g2 = *(const LAS f32x2*)(P + 96 + lc + 2 * jp);
;                     const f32x2 bv = *(const LAS f32x2*)(P + 128 + lc + 2 * jp), v0 = *(const LAS f32x2*)(P + 160 + lc + 2 * jp), v1 = *(const LAS f32x2*)(P + 192 + lc + 2 * jp), v2 = *(const LAS f32x2*)(P + 224 + lc + 2 * jp);
;                     f32x2 G[4], V[4];
; #pragma unroll
;                     for (int m = 0; m < 4; ++m) { G[m] = (f32x2){acc[ai][0][m][n][2 * jp], acc[ai][0][m][n][2 * jp + 1]} * rs[m]; V[m] = (f32x2){acc[ai][1][m][n][2 * jp], acc[ai][1][m][n][2 * jp + 1]} * rs[m]; }
; #pragma unroll
;                     for (int m = 0; m < 4; ++m) {
;                         const f32x2 zz = {0.f, 0.f}; const f32x2 Gp = m ? G[m - 1] : zz, Vp = m ? V[m - 1] : zz;
;                         const f32x2 gp1 = {dpp_prev1(G[m].x, Gp.x), dpp_prev1(G[m].y, Gp.y)}, gp2 = {dpp_prev2(G[m].x, Gp.x), dpp_prev2(G[m].y, Gp.y)};
;                         const f32x2 vp1 = {dpp_prev1(V[m].x, Vp.x), dpp_prev1(V[m].y, Vp.y)}, vp2 = {dpp_prev2(V[m].x, Vp.x), dpp_prev2(V[m].y, Vp.y)};
;                         const f32x2 gc = bg + g0 * gp2 + g1 * gp1 + g2 * G[m];
;                         const f32x2 vc = bv + v0 * vp2 + v1 * vp1 + v2 * V[m];
;                         const f32x2 xe = gc * (-LOG2E);
;                         f32x2 dn = {__builtin_amdgcn_exp2f(xe.x), __builtin_amdgcn_exp2f(xe.y)}; dn = dn + 1.0f;
;                         const f32x2 rc = {__builtin_amdgcn_rcpf(dn.x), __builtin_amdgcn_rcpf(dn.y)};
;                         const f32x2 rr = gc * rc * vc;
;                         wpk[m][jp] = pk2(rr.x, rr.y); }
;                 }
; #pragma unroll
;                 for (int m = 0; m < 4; ++m) { const int row = m ? tok0 + 16 * m : row0;
;                     *(u32x2*)(ACT + (size_t)row * 2816 + cl + 4 * n) = (u32x2){wpk[m][0], wpk[m][1]}; }
	v_mov_b32_dpp v114, v102 row_shr:2 row_mask:0xf bank_mask:0xf
	v_mov_b32_dpp v115, v103 row_shr:2 row_mask:0xf bank_mask:0xf
	v_mov_b32_dpp v112, v102 row_shr:1 row_mask:0xf bank_mask:0xf
	v_mov_b32_dpp v113, v103 row_shr:1 row_mask:0xf bank_mask:0xf
	v_pk_fma_f32 v[114:115], v[150:151], v[114:115], v[138:139]
	v_pk_fma_f32 v[112:113], v[154:155], v[112:113], v[114:115]
	v_pk_fma_f32 v[102:103], v[102:103], v[158:159], v[112:113]
	v_pk_mul_f32 v[112:113], v[102:103], s[2:3] op_sel_hi:[1,0]
	v_exp_f32_e32 v112, v112
	v_exp_f32_e32 v113, v113
	v_mov_b32_dpp v110, v106 row_ror:1 row_mask:0xf bank_mask:0xf
	v_mov_b32_dpp v111, v107 row_ror:1 row_mask:0xf bank_mask:0xf
	v_mov_b32_dpp v116, v106 row_ror:2 row_mask:0xf bank_mask:0xf
	v_mov_b32_dpp v117, v107 row_ror:2 row_mask:0xf bank_mask:0xf
	v_pk_add_f32 v[106:107], v[112:113], 1.0 op_sel_hi:[1,0]
	v_pk_mul_f32 v[98:99], v[98:99], v[180:181] op_sel_hi:[1,0]
	v_rcp_f32_e32 v106, v106
	v_rcp_f32_e32 v107, v107
	v_mov_b32_dpp v116, v98 row_shr:2 row_mask:0xf bank_mask:0xf
	v_mov_b32_dpp v117, v99 row_shr:2 row_mask:0xf bank_mask:0xf
	v_mov_b32_dpp v110, v98 row_shr:1 row_mask:0xf bank_mask:0xf
	v_mov_b32_dpp v111, v99 row_shr:1 row_mask:0xf bank_mask:0xf
	v_pk_fma_f32 v[112:113], v[134:135], v[116:117], v[130:131]
	v_pk_mul_f32 v[102:103], v[102:103], v[106:107]
	v_pk_fma_f32 v[110:111], v[142:143], v[110:111], v[112:113]
	v_mov_b64_e32 v[128:129], s[16:17]
	v_pk_fma_f32 v[98:99], v[98:99], v[146:147], v[110:111]
	v_cvt_pk_bf16_f32 v108, v108, v109
	v_pk_mul_f32 v[98:99], v[98:99], v[102:103]
	v_lshlrev_b64 v[130:131], 1, v[188:189]
	v_cvt_pk_bf16_f32 v109, v98, v99
	v_mad_i64_i32 v[98:99], s[8:9], v201, s48, v[128:129]
	v_lshl_add_u64 v[132:133], v[98:99], 0, v[130:131]
	global_store_dwordx2 v[132:133], v[96:97], off
	v_mad_i64_i32 v[96:97], s[8:9], v198, s48, v[128:129]
	v_lshl_add_u64 v[134:135], v[96:97], 0, v[130:131]
	v_mad_i64_i32 v[96:97], s[8:9], v199, s48, v[128:129]
	v_lshl_add_u64 v[136:137], v[96:97], 0, v[130:131]
	v_mad_i64_i32 v[96:97], s[8:9], v200, s48, v[128:129]
	v_lshl_add_u64 v[138:139], v[96:97], 0, v[130:131]
	global_store_dwordx2 v[134:135], v[100:101], off
	global_store_dwordx2 v[136:137], v[104:105], off
	global_store_dwordx2 v[138:139], v[108:109], off
	v_pk_mul_f32 v[92:93], v[92:93], v[186:187] op_sel_hi:[1,0]
	v_pk_mul_f32 v[142:143], v[68:69], v[180:181] op_sel_hi:[1,0]
	v_mov_b32_e32 v68, v183
	v_mov_b32_e32 v69, v183
	v_pk_mul_f32 v[144:145], v[64:65], v[180:181] op_sel_hi:[1,0]
	v_mov_b32_e32 v64, v181
	v_mov_b32_e32 v65, v181
	v_mov_b32_dpp v68, v92 row_shr:2 row_mask:0xf bank_mask:0xf
	v_mov_b32_dpp v69, v93 row_shr:2 row_mask:0xf bank_mask:0xf
	ds_read_b128 v[104:107], v193 offset:16
	ds_read_b128 v[116:119], v193 offset:144
	ds_read_b128 v[120:123], v193 offset:272
	ds_read_b128 v[124:127], v193 offset:400
	ds_read_b128 v[96:99], v193 offset:528
	ds_read_b128 v[100:103], v193 offset:656
	ds_read_b128 v[108:111], v193 offset:784
	ds_read_b128 v[112:115], v193 offset:912
	v_mov_b32_dpp v64, v92 row_shr:1 row_mask:0xf bank_mask:0xf
	v_mov_b32_dpp v65, v93 row_shr:1 row_mask:0xf bank_mask:0xf
	s_waitcnt lgkmcnt(6)
	v_pk_fma_f32 v[68:69], v[116:117], v[68:69], v[104:105]
	v_pk_mul_f32 v[88:89], v[88:89], v[186:187] op_sel_hi:[1,0]
	s_waitcnt lgkmcnt(5)
	v_pk_fma_f32 v[64:65], v[120:121], v[64:65], v[68:69]
	v_mov_b32_e32 v146, v183
	s_waitcnt lgkmcnt(4)
	v_pk_fma_f32 v[64:65], v[92:93], v[124:125], v[64:65]
	v_mov_b32_e32 v147, v183
	v_pk_mul_f32 v[68:69], v[64:65], s[2:3] op_sel_hi:[1,0]
	v_pk_mul_f32 v[140:141], v[72:73], v[182:183] op_sel_hi:[1,0]
	v_exp_f32_e32 v68, v68
	v_exp_f32_e32 v69, v69
	v_mov_b32_e32 v72, v181
	v_mov_b32_e32 v73, v181
	v_mov_b32_dpp v146, v88 row_shr:2 row_mask:0xf bank_mask:0xf
	v_pk_add_f32 v[68:69], v[68:69], 1.0 op_sel_hi:[1,0]
	v_mov_b32_dpp v147, v89 row_shr:2 row_mask:0xf bank_mask:0xf
	v_rcp_f32_e32 v68, v68
	v_rcp_f32_e32 v69, v69
	v_mov_b32_dpp v72, v88 row_shr:1 row_mask:0xf bank_mask:0xf
	v_mov_b32_dpp v73, v89 row_shr:1 row_mask:0xf bank_mask:0xf
	s_waitcnt lgkmcnt(2)
	v_pk_fma_f32 v[146:147], v[100:101], v[146:147], v[96:97]
	v_pk_mul_f32 v[64:65], v[64:65], v[68:69]
	s_waitcnt lgkmcnt(1)
	v_pk_fma_f32 v[72:73], v[108:109], v[72:73], v[146:147]
	v_pk_mul_f32 v[84:85], v[84:85], v[184:185] op_sel_hi:[1,0]
	s_waitcnt lgkmcnt(0)
; #define LAS __attribute__((address_space(3)))
; DI unsigned pk2(float lo, float hi) { f32x2 v = {lo, hi}; bf16x2_t b = __builtin_convertvector(v, bf16x2_t); return __builtin_bit_cast(unsigned, b); }
;     DI void operator()(const AccT& acc, const Unit& u, int wr, int wc, int fr, int fq) const {
;     ...
;                     const f32x2 bg = *(const LAS f32x2*)(P + lc + 2 * jp), g0 = *(const LAS f32x2*)(P + 32 + lc + 2 * jp), g1 = *(const LAS f32x2*)(P + 64 + lc + 2 * jp), g2 = *(const LAS f32x2*)(P + 96 + lc + 2 * jp);
;                     const f32x2 bv = *(const LAS f32x2*)(P + 128 + lc + 2 * jp), v0 = *(const LAS f32x2*)(P + 160 + lc + 2 * jp), v1 = *(const LAS f32x2*)(P + 192 + lc + 2 * jp), v2 = *(const LAS f32x2*)(P + 224 + lc + 2 * jp);
;                     f32x2 G[4], V[4];
; #pragma unroll
;                     for (int m = 0; m < 4; ++m) { G[m] = (f32x2){acc[ai][0][m][n][2 * jp], acc[ai][0][m][n][2 * jp + 1]} * rs[m]; V[m] = (f32x2){acc[ai][1][m][n][2 * jp], acc[ai][1][m][n][2 * jp + 1]} * rs[m]; }
; #pragma unroll
;                     for (int m = 0; m < 4; ++m) {
;                         const f32x2 zz = {0.f, 0.f}; const f32x2 Gp = m ? G[m - 1] : zz, Vp = m ? V[m - 1] : zz;
;                         const f32x2 gp1 = {dpp_prev1(G[m].x, Gp.x), dpp_prev1(G[m].y, Gp.y)}, gp2 = {dpp_prev2(G[m].x, Gp.x), dpp_prev2(G[m].y, Gp.y)};
;                         const f32x2 vp1 = {dpp_prev1(V[m].x, Vp.x), dpp_prev1(V[m].y, Vp.y)}, vp2 = {dpp_prev2(V[m].x, Vp.x), dpp_prev2(V[m].y, Vp.y)};
;                         const f32x2 gc = bg + g0 * gp2 + g1 * gp1 + g2 * G[m];
;                         const f32x2 vc = bv + v0 * vp2 + v1 * vp1 + v2 * V[m];
;                         const f32x2 xe = gc * (-LOG2E);
;                         f32x2 dn = {__builtin_amdgcn_exp2f(xe.x), __builtin_amdgcn_exp2f(xe.y)}; dn = dn + 1.0f;
;                         const f32x2 rc = {__builtin_amdgcn_rcpf(dn.x), __builtin_amdgcn_rcpf(dn.y)};
;                         const f32x2 rr = gc * rc * vc;
;                         wpk[m][jp] = pk2(rr.x, rr.y); }
	v_pk_fma_f32 v[72:73], v[88:89], v[112:113], v[72:73]
	v_pk_mul_f32 v[64:65], v[72:73], v[64:65]
	v_mov_b32_dpp v72, v92 row_ror:2 row_mask:0xf bank_mask:0xf
	v_mov_b32_dpp v73, v93 row_ror:2 row_mask:0xf bank_mask:0xf
	v_mov_b32_dpp v68, v92 row_ror:1 row_mask:0xf bank_mask:0xf
	v_mov_b32_dpp v69, v93 row_ror:1 row_mask:0xf bank_mask:0xf
	v_mov_b32_dpp v72, v84 row_shr:2 row_mask:0xf bank_mask:0xf
	v_mov_b32_dpp v73, v85 row_shr:2 row_mask:0xf bank_mask:0xf
	v_mov_b32_dpp v68, v84 row_shr:1 row_mask:0xf bank_mask:0xf
	v_mov_b32_dpp v69, v85 row_shr:1 row_mask:0xf bank_mask:0xf
	v_pk_fma_f32 v[72:73], v[116:117], v[72:73], v[104:105]
	v_pk_fma_f32 v[68:69], v[120:121], v[68:69], v[72:73]
	v_pk_fma_f32 v[68:69], v[84:85], v[124:125], v[68:69]
	v_pk_mul_f32 v[80:81], v[80:81], v[184:185] op_sel_hi:[1,0]
	v_pk_mul_f32 v[72:73], v[68:69], s[2:3] op_sel_hi:[1,0]
	v_exp_f32_e32 v72, v72
	v_exp_f32_e32 v73, v73
	v_mov_b32_dpp v146, v88 row_ror:2 row_mask:0xf bank_mask:0xf
	v_mov_b32_dpp v147, v89 row_ror:2 row_mask:0xf bank_mask:0xf
	v_pk_add_f32 v[72:73], v[72:73], 1.0 op_sel_hi:[1,0]
	v_mov_b32_dpp v92, v88 row_ror:1 row_mask:0xf bank_mask:0xf
	v_rcp_f32_e32 v72, v72
	v_rcp_f32_e32 v73, v73
	v_mov_b32_dpp v93, v89 row_ror:1 row_mask:0xf bank_mask:0xf
	v_mov_b32_dpp v146, v80 row_shr:2 row_mask:0xf bank_mask:0xf
	v_mov_b32_dpp v147, v81 row_shr:2 row_mask:0xf bank_mask:0xf
	v_mov_b32_dpp v92, v80 row_shr:1 row_mask:0xf bank_mask:0xf
	v_mov_b32_dpp v93, v81 row_shr:1 row_mask:0xf bank_mask:0xf
	v_pk_fma_f32 v[88:89], v[100:101], v[146:147], v[96:97]
	v_pk_mul_f32 v[68:69], v[68:69], v[72:73]
	v_pk_fma_f32 v[88:89], v[108:109], v[92:93], v[88:89]
	v_pk_mul_f32 v[76:77], v[76:77], v[182:183] op_sel_hi:[1,0]
	v_pk_fma_f32 v[88:89], v[80:81], v[112:113], v[88:89]
	v_pk_mul_f32 v[68:69], v[88:89], v[68:69]
	v_mov_b32_dpp v88, v84 row_ror:2 row_mask:0xf bank_mask:0xf
	v_mov_b32_dpp v89, v85 row_ror:2 row_mask:0xf bank_mask:0xf
	v_mov_b32_dpp v72, v84 row_ror:1 row_mask:0xf bank_mask:0xf
	v_mov_b32_dpp v73, v85 row_ror:1 row_mask:0xf bank_mask:0xf
	v_mov_b32_dpp v88, v76 row_shr:2 row_mask:0xf bank_mask:0xf
	v_mov_b32_dpp v89, v77 row_shr:2 row_mask:0xf bank_mask:0xf
	v_mov_b32_dpp v72, v76 row_shr:1 row_mask:0xf bank_mask:0xf
	v_mov_b32_dpp v73, v77 row_shr:1 row_mask:0xf bank_mask:0xf
	v_pk_fma_f32 v[88:89], v[116:117], v[88:89], v[104:105]
	v_pk_fma_f32 v[72:73], v[120:121], v[72:73], v[88:89]
	v_pk_fma_f32 v[72:73], v[76:77], v[124:125], v[72:73]
	v_pk_mul_f32 v[88:89], v[72:73], s[2:3] op_sel_hi:[1,0]
	v_exp_f32_e32 v88, v88
	v_exp_f32_e32 v89, v89
	v_mov_b32_dpp v84, v80 row_ror:1 row_mask:0xf bank_mask:0xf
	v_mov_b32_dpp v85, v81 row_ror:1 row_mask:0xf bank_mask:0xf
	v_mov_b32_dpp v92, v80 row_ror:2 row_mask:0xf bank_mask:0xf
	v_mov_b32_dpp v93, v81 row_ror:2 row_mask:0xf bank_mask:0xf
	v_pk_add_f32 v[80:81], v[88:89], 1.0 op_sel_hi:[1,0]
	v_mov_b32_dpp v92, v140 row_shr:2 row_mask:0xf bank_mask:0xf
	v_rcp_f32_e32 v80, v80
	v_rcp_f32_e32 v81, v81
	v_mov_b32_dpp v93, v141 row_shr:2 row_mask:0xf bank_mask:0xf
	v_mov_b32_dpp v84, v140 row_shr:1 row_mask:0xf bank_mask:0xf
	v_mov_b32_dpp v85, v141 row_shr:1 row_mask:0xf bank_mask:0xf
	v_pk_fma_f32 v[88:89], v[100:101], v[92:93], v[96:97]
	v_pk_mul_f32 v[72:73], v[72:73], v[80:81]
	v_pk_fma_f32 v[84:85], v[108:109], v[84:85], v[88:89]
	v_pk_fma_f32 v[84:85], v[140:141], v[112:113], v[84:85]
	v_pk_mul_f32 v[72:73], v[84:85], v[72:73]
	v_mov_b32_dpp v80, v76 row_ror:1 row_mask:0xf bank_mask:0xf
	v_mov_b32_dpp v84, v76 row_ror:2 row_mask:0xf bank_mask:0xf
	v_mov_b32_dpp v85, v77 row_ror:2 row_mask:0xf bank_mask:0xf
	v_mov_b32_dpp v81, v77 row_ror:1 row_mask:0xf bank_mask:0xf
	v_mov_b32_dpp v84, v142 row_shr:2 row_mask:0xf bank_mask:0xf
	v_mov_b32_dpp v85, v143 row_shr:2 row_mask:0xf bank_mask:0xf
	v_mov_b32_dpp v80, v142 row_shr:1 row_mask:0xf bank_mask:0xf
	v_mov_b32_dpp v81, v143 row_shr:1 row_mask:0xf bank_mask:0xf
	v_pk_fma_f32 v[84:85], v[116:117], v[84:85], v[104:105]
	v_pk_fma_f32 v[80:81], v[120:121], v[80:81], v[84:85]
	v_pk_fma_f32 v[80:81], v[142:143], v[124:125], v[80:81]
	v_pk_mul_f32 v[84:85], v[80:81], s[2:3] op_sel_hi:[1,0]
	v_exp_f32_e32 v84, v84
	v_exp_f32_e32 v85, v85
	v_mov_b32_dpp v88, v140 row_ror:2 row_mask:0xf bank_mask:0xf
	v_mov_b32_dpp v89, v141 row_ror:2 row_mask:0xf bank_mask:0xf
	v_mov_b32_dpp v76, v140 row_ror:1 row_mask:0xf bank_mask:0xf
	v_pk_add_f32 v[84:85], v[84:85], 1.0 op_sel_hi:[1,0]
	v_mov_b32_dpp v77, v141 row_ror:1 row_mask:0xf bank_mask:0xf
	v_rcp_f32_e32 v84, v84
	v_rcp_f32_e32 v85, v85
	v_mov_b32_dpp v88, v144 row_shr:2 row_mask:0xf bank_mask:0xf
	v_mov_b32_dpp v89, v145 row_shr:2 row_mask:0xf bank_mask:0xf
	v_mov_b32_dpp v76, v144 row_shr:1 row_mask:0xf bank_mask:0xf
	v_mov_b32_dpp v77, v145 row_shr:1 row_mask:0xf bank_mask:0xf
	v_pk_fma_f32 v[88:89], v[100:101], v[88:89], v[96:97]
	v_pk_mul_f32 v[80:81], v[80:81], v[84:85]
	v_pk_fma_f32 v[76:77], v[108:109], v[76:77], v[88:89]
	v_pk_mul_f32 v[84:85], v[90:91], v[186:187] op_sel_hi:[1,0]
	v_pk_fma_f32 v[76:77], v[144:145], v[112:113], v[76:77]
	v_mov_b32_e32 v90, v183
	v_pk_mul_f32 v[76:77], v[76:77], v[80:81]
	v_pk_mul_f32 v[80:81], v[94:95], v[186:187] op_sel_hi:[1,0]
	v_mov_b32_e32 v91, v183
	v_mov_b32_e32 v88, v181
	v_mov_b32_e32 v89, v181
	v_mov_b32_dpp v90, v80 row_shr:2 row_mask:0xf bank_mask:0xf
	v_mov_b32_dpp v91, v81 row_shr:2 row_mask:0xf bank_mask:0xf
	v_mov_b32_dpp v88, v80 row_shr:1 row_mask:0xf bank_mask:0xf
	v_mov_b32_dpp v89, v81 row_shr:1 row_mask:0xf bank_mask:0xf
	v_pk_fma_f32 v[90:91], v[118:119], v[90:91], v[106:107]
	v_mov_b32_e32 v94, v183
	v_pk_fma_f32 v[88:89], v[122:123], v[88:89], v[90:91]
; #define LAS __attribute__((address_space(3)))
; DI unsigned pk2(float lo, float hi) { f32x2 v = {lo, hi}; bf16x2_t b = __builtin_convertvector(v, bf16x2_t); return __builtin_bit_cast(unsigned, b); }
;     DI void operator()(const AccT& acc, const Unit& u, int wr, int wc, int fr, int fq) const {
;     ...
;                     const f32x2 bg = *(const LAS f32x2*)(P + lc + 2 * jp), g0 = *(const LAS f32x2*)(P + 32 + lc + 2 * jp), g1 = *(const LAS f32x2*)(P + 64 + lc + 2 * jp), g2 = *(const LAS f32x2*)(P + 96 + lc + 2 * jp);
;                     const f32x2 bv = *(const LAS f32x2*)(P + 128 + lc + 2 * jp), v0 = *(const LAS f32x2*)(P + 160 + lc + 2 * jp), v1 = *(const LAS f32x2*)(P + 192 + lc + 2 * jp), v2 = *(const LAS f32x2*)(P + 224 + lc + 2 * jp);
;                     f32x2 G[4], V[4];
; #pragma unroll
;                     for (int m = 0; m < 4; ++m) { G[m] = (f32x2){acc[ai][0][m][n][2 * jp], acc[ai][0][m][n][2 * jp + 1]} * rs[m]; V[m] = (f32x2){acc[ai][1][m][n][2 * jp], acc[ai][1][m][n][2 * jp + 1]} * rs[m]; }
; #pragma unroll
;                     for (int m = 0; m < 4; ++m) {
;                         const f32x2 zz = {0.f, 0.f}; const f32x2 Gp = m ? G[m - 1] : zz, Vp = m ? V[m - 1] : zz;
;                         const f32x2 gp1 = {dpp_prev1(G[m].x, Gp.x), dpp_prev1(G[m].y, Gp.y)}, gp2 = {dpp_prev2(G[m].x, Gp.x), dpp_prev2(G[m].y, Gp.y)};
;                         const f32x2 vp1 = {dpp_prev1(V[m].x, Vp.x), dpp_prev1(V[m].y, Vp.y)}, vp2 = {dpp_prev2(V[m].x, Vp.x), dpp_prev2(V[m].y, Vp.y)};
;                         const f32x2 gc = bg + g0 * gp2 + g1 * gp1 + g2 * G[m];
;                         const f32x2 vc = bv + v0 * vp2 + v1 * vp1 + v2 * V[m];
;                         const f32x2 xe = gc * (-LOG2E);
;                         f32x2 dn = {__builtin_amdgcn_exp2f(xe.x), __builtin_amdgcn_exp2f(xe.y)}; dn = dn + 1.0f;
;                         const f32x2 rc = {__builtin_amdgcn_rcpf(dn.x), __builtin_amdgcn_rcpf(dn.y)};
;                         const f32x2 rr = gc * rc * vc;
;                         wpk[m][jp] = pk2(rr.x, rr.y); }
	v_mov_b32_e32 v95, v183
	v_pk_fma_f32 v[88:89], v[80:81], v[126:127], v[88:89]
	v_mov_b32_e32 v92, v181
	v_pk_mul_f32 v[90:91], v[88:89], s[2:3] op_sel_hi:[1,0]
	v_mov_b32_e32 v93, v181
	v_exp_f32_e32 v90, v90
	v_exp_f32_e32 v91, v91
	v_mov_b32_dpp v94, v84 row_shr:2 row_mask:0xf bank_mask:0xf
	v_mov_b32_dpp v95, v85 row_shr:2 row_mask:0xf bank_mask:0xf
	v_mov_b32_dpp v92, v84 row_shr:1 row_mask:0xf bank_mask:0xf
	v_pk_add_f32 v[90:91], v[90:91], 1.0 op_sel_hi:[1,0]
	v_mov_b32_dpp v93, v85 row_shr:1 row_mask:0xf bank_mask:0xf
	v_rcp_f32_e32 v90, v90
	v_rcp_f32_e32 v91, v91
	v_pk_fma_f32 v[94:95], v[102:103], v[94:95], v[98:99]
	v_cvt_pk_bf16_f32 v64, v64, v65
	v_pk_fma_f32 v[92:93], v[110:111], v[92:93], v[94:95]
	v_pk_mul_f32 v[88:89], v[88:89], v[90:91]
	v_pk_fma_f32 v[92:93], v[84:85], v[114:115], v[92:93]
	v_pk_mul_f32 v[88:89], v[92:93], v[88:89]
	v_pk_mul_f32 v[86:87], v[86:87], v[184:185] op_sel_hi:[1,0]
	v_cvt_pk_bf16_f32 v65, v88, v89
	v_mov_b32_dpp v90, v80 row_ror:2 row_mask:0xf bank_mask:0xf
	v_mov_b32_dpp v91, v81 row_ror:2 row_mask:0xf bank_mask:0xf
	v_mov_b32_dpp v88, v80 row_ror:1 row_mask:0xf bank_mask:0xf
	v_mov_b32_dpp v89, v81 row_ror:1 row_mask:0xf bank_mask:0xf
	v_mov_b32_dpp v90, v86 row_shr:2 row_mask:0xf bank_mask:0xf
	v_mov_b32_dpp v91, v87 row_shr:2 row_mask:0xf bank_mask:0xf
	v_mov_b32_dpp v88, v86 row_shr:1 row_mask:0xf bank_mask:0xf
	v_mov_b32_dpp v89, v87 row_shr:1 row_mask:0xf bank_mask:0xf
	v_pk_fma_f32 v[90:91], v[118:119], v[90:91], v[106:107]
	v_pk_fma_f32 v[88:89], v[122:123], v[88:89], v[90:91]
	v_pk_fma_f32 v[88:89], v[86:87], v[126:127], v[88:89]
	v_pk_mul_f32 v[90:91], v[88:89], s[2:3] op_sel_hi:[1,0]
	v_exp_f32_e32 v90, v90
	v_exp_f32_e32 v91, v91
	v_mov_b32_dpp v80, v84 row_ror:1 row_mask:0xf bank_mask:0xf
	v_mov_b32_dpp v81, v85 row_ror:1 row_mask:0xf bank_mask:0xf
	v_mov_b32_dpp v92, v84 row_ror:2 row_mask:0xf bank_mask:0xf
	v_mov_b32_dpp v93, v85 row_ror:2 row_mask:0xf bank_mask:0xf
	v_pk_add_f32 v[84:85], v[90:91], 1.0 op_sel_hi:[1,0]
	v_pk_mul_f32 v[82:83], v[82:83], v[184:185] op_sel_hi:[1,0]
	v_rcp_f32_e32 v84, v84
	v_rcp_f32_e32 v85, v85
	v_mov_b32_dpp v92, v82 row_shr:2 row_mask:0xf bank_mask:0xf
	v_mov_b32_dpp v93, v83 row_shr:2 row_mask:0xf bank_mask:0xf
	v_mov_b32_dpp v80, v82 row_shr:1 row_mask:0xf bank_mask:0xf
	v_mov_b32_dpp v81, v83 row_shr:1 row_mask:0xf bank_mask:0xf
	v_pk_fma_f32 v[90:91], v[102:103], v[92:93], v[98:99]
	v_pk_mul_f32 v[84:85], v[88:89], v[84:85]
	v_pk_fma_f32 v[80:81], v[110:111], v[80:81], v[90:91]
	v_cvt_pk_bf16_f32 v68, v68, v69
	v_pk_fma_f32 v[80:81], v[82:83], v[114:115], v[80:81]
	v_pk_mul_f32 v[78:79], v[78:79], v[182:183] op_sel_hi:[1,0]
	v_pk_mul_f32 v[80:81], v[80:81], v[84:85]
	v_cvt_pk_bf16_f32 v69, v80, v81
	v_mov_b32_dpp v84, v86 row_ror:2 row_mask:0xf bank_mask:0xf
	v_mov_b32_dpp v85, v87 row_ror:2 row_mask:0xf bank_mask:0xf
	v_mov_b32_dpp v80, v86 row_ror:1 row_mask:0xf bank_mask:0xf
	v_mov_b32_dpp v81, v87 row_ror:1 row_mask:0xf bank_mask:0xf
	v_mov_b32_dpp v84, v78 row_shr:2 row_mask:0xf bank_mask:0xf
	v_mov_b32_dpp v85, v79 row_shr:2 row_mask:0xf bank_mask:0xf
	v_mov_b32_dpp v80, v78 row_shr:1 row_mask:0xf bank_mask:0xf
	v_mov_b32_dpp v81, v79 row_shr:1 row_mask:0xf bank_mask:0xf
	v_pk_fma_f32 v[84:85], v[118:119], v[84:85], v[106:107]
	v_pk_fma_f32 v[80:81], v[122:123], v[80:81], v[84:85]
	v_pk_fma_f32 v[80:81], v[78:79], v[126:127], v[80:81]
	v_pk_mul_f32 v[84:85], v[80:81], s[2:3] op_sel_hi:[1,0]
	v_exp_f32_e32 v84, v84
	v_exp_f32_e32 v85, v85
	v_mov_b32_dpp v86, v82 row_ror:1 row_mask:0xf bank_mask:0xf
	v_mov_b32_dpp v87, v83 row_ror:1 row_mask:0xf bank_mask:0xf
	v_mov_b32_dpp v88, v82 row_ror:2 row_mask:0xf bank_mask:0xf
	v_mov_b32_dpp v89, v83 row_ror:2 row_mask:0xf bank_mask:0xf
	v_pk_add_f32 v[82:83], v[84:85], 1.0 op_sel_hi:[1,0]
	v_pk_mul_f32 v[74:75], v[74:75], v[182:183] op_sel_hi:[1,0]
	v_rcp_f32_e32 v82, v82
	v_rcp_f32_e32 v83, v83
	v_mov_b32_dpp v88, v74 row_shr:2 row_mask:0xf bank_mask:0xf
	v_mov_b32_dpp v89, v75 row_shr:2 row_mask:0xf bank_mask:0xf
	v_mov_b32_dpp v86, v74 row_shr:1 row_mask:0xf bank_mask:0xf
	v_mov_b32_dpp v87, v75 row_shr:1 row_mask:0xf bank_mask:0xf
	v_pk_fma_f32 v[84:85], v[102:103], v[88:89], v[98:99]
	v_pk_mul_f32 v[80:81], v[80:81], v[82:83]
	v_pk_fma_f32 v[84:85], v[110:111], v[86:87], v[84:85]
	v_pk_fma_f32 v[84:85], v[74:75], v[114:115], v[84:85]
	v_pk_mul_f32 v[80:81], v[84:85], v[80:81]
	v_cvt_pk_bf16_f32 v72, v72, v73
	v_pk_mul_f32 v[70:71], v[70:71], v[180:181] op_sel_hi:[1,0]
	v_cvt_pk_bf16_f32 v73, v80, v81
	v_mov_b32_dpp v82, v78 row_ror:2 row_mask:0xf bank_mask:0xf
	v_mov_b32_dpp v83, v79 row_ror:2 row_mask:0xf bank_mask:0xf
	v_mov_b32_dpp v80, v78 row_ror:1 row_mask:0xf bank_mask:0xf
	v_mov_b32_dpp v81, v79 row_ror:1 row_mask:0xf bank_mask:0xf
	v_mov_b32_dpp v82, v70 row_shr:2 row_mask:0xf bank_mask:0xf
	v_mov_b32_dpp v83, v71 row_shr:2 row_mask:0xf bank_mask:0xf
	v_mov_b32_dpp v80, v70 row_shr:1 row_mask:0xf bank_mask:0xf
	v_mov_b32_dpp v81, v71 row_shr:1 row_mask:0xf bank_mask:0xf
	v_pk_fma_f32 v[82:83], v[118:119], v[82:83], v[106:107]
	v_pk_fma_f32 v[80:81], v[122:123], v[80:81], v[82:83]
	v_pk_fma_f32 v[70:71], v[70:71], v[126:127], v[80:81]
	v_pk_mul_f32 v[80:81], v[70:71], s[2:3] op_sel_hi:[1,0]
	v_exp_f32_e32 v80, v80
	v_exp_f32_e32 v81, v81
	v_mov_b32_dpp v78, v74 row_ror:1 row_mask:0xf bank_mask:0xf
	v_mov_b32_dpp v79, v75 row_ror:1 row_mask:0xf bank_mask:0xf
	v_mov_b32_dpp v84, v74 row_ror:2 row_mask:0xf bank_mask:0xf
	v_mov_b32_dpp v85, v75 row_ror:2 row_mask:0xf bank_mask:0xf
	v_pk_add_f32 v[74:75], v[80:81], 1.0 op_sel_hi:[1,0]
	v_pk_mul_f32 v[66:67], v[66:67], v[180:181] op_sel_hi:[1,0]
;     DI void operator()(const AccT& acc, const Unit& u, int wr, int wc, int fr, int fq) const {
;     ...
;             for (int m = 0; m < 4; ++m) { const int t = tok0 + 16 * m; const int tc = t < 0 ? 0 : (t >= S ? S - 1 : t); const float r = rs_from_ss(rowss[tc]); rs[m] = t < 0 ? 0.f : r; }
;             const int row0 = fr < 2 ? (S + 236 + fr) : tok0;
; #pragma unroll
;             for (int n = 0; n < 2; ++n) {
;                 const int lc = 8 * fq + 4 * n;
;                 unsigned wpk[4][2];
; #pragma unroll
;                 for (int jp = 0; jp < 2; ++jp) {
;                     const f32x2 bg = *(const LAS f32x2*)(P + lc + 2 * jp), g0 = *(const LAS f32x2*)(P + 32 + lc + 2 * jp), g1 = *(const LAS f32x2*)(P + 64 + lc + 2 * jp), g2 = *(const LAS f32x2*)(P + 96 + lc + 2 * jp);
;                     const f32x2 bv = *(const LAS f32x2*)(P + 128 + lc + 2 * jp), v0 = *(const LAS f32x2*)(P + 160 + lc + 2 * jp), v1 = *(const LAS f32x2*)(P + 192 + lc + 2 * jp), v2 = *(const LAS f32x2*)(P + 224 + lc + 2 * jp);
;                     f32x2 G[4], V[4];
; #pragma unroll
;                     for (int m = 0; m < 4; ++m) { G[m] = (f32x2){acc[ai][0][m][n][2 * jp], acc[ai][0][m][n][2 * jp + 1]} * rs[m]; V[m] = (f32x2){acc[ai][1][m][n][2 * jp], acc[ai][1][m][n][2 * jp + 1]} * rs[m]; }
; #pragma unroll
;                     for (int m = 0; m < 4; ++m) {
;                         const f32x2 zz = {0.f, 0.f}; const f32x2 Gp = m ? G[m - 1] : zz, Vp = m ? V[m - 1] : zz;
;                         const f32x2 gp1 = {dpp_prev1(G[m].x, Gp.x), dpp_prev1(G[m].y, Gp.y)}, gp2 = {dpp_prev2(G[m].x, Gp.x), dpp_prev2(G[m].y, Gp.y)};
;                         const f32x2 vp1 = {dpp_prev1(V[m].x, Vp.x), dpp_prev1(V[m].y, Vp.y)}, vp2 = {dpp_prev2(V[m].x, Vp.x), dpp_prev2(V[m].y, Vp.y)};
;                         const f32x2 gc = bg + g0 * gp2 + g1 * gp1 + g2 * G[m];
;                         const f32x2 vc = bv + v0 * vp2 + v1 * vp1 + v2 * V[m];
;                         const f32x2 xe = gc * (-LOG2E);
;                         f32x2 dn = {__builtin_amdgcn_exp2f(xe.x), __builtin_amdgcn_exp2f(xe.y)}; dn = dn + 1.0f;
;                         const f32x2 rc = {__builtin_amdgcn_rcpf(dn.x), __builtin_amdgcn_rcpf(dn.y)};
;                         const f32x2 rr = gc * rc * vc;
;                         wpk[m][jp] = pk2(rr.x, rr.y); }
;                 }
; #pragma unroll
	v_rcp_f32_e32 v74, v74
	v_rcp_f32_e32 v75, v75
	v_mov_b32_dpp v84, v66 row_shr:2 row_mask:0xf bank_mask:0xf
	v_mov_b32_dpp v85, v67 row_shr:2 row_mask:0xf bank_mask:0xf
	v_mov_b32_dpp v78, v66 row_shr:1 row_mask:0xf bank_mask:0xf
	v_mov_b32_dpp v79, v67 row_shr:1 row_mask:0xf bank_mask:0xf
	v_pk_fma_f32 v[80:81], v[102:103], v[84:85], v[98:99]
	v_pk_mul_f32 v[70:71], v[70:71], v[74:75]
	v_pk_fma_f32 v[78:79], v[110:111], v[78:79], v[80:81]
	v_cvt_pk_bf16_f32 v76, v76, v77
	v_pk_fma_f32 v[66:67], v[66:67], v[114:115], v[78:79]
	s_nop 0
	v_pk_mul_f32 v[66:67], v[66:67], v[70:71]
	s_nop 0
	v_cvt_pk_bf16_f32 v77, v66, v67
	global_store_dwordx2 v[132:133], v[64:65], off offset:8
	global_store_dwordx2 v[134:135], v[68:69], off offset:8
	global_store_dwordx2 v[136:137], v[72:73], off offset:8
	global_store_dwordx2 v[138:139], v[76:77], off offset:8
	v_add_u32_e32 v96, 0x7c, v197
	v_med3_i32 v64, v96, 0, s51
	v_add_u32_e32 v97, 0x8c, v197
	v_add_u32_e32 v99, 0x9c, v197
	v_add_u32_e32 v101, 0xac, v197
	v_lshlrev_b32_e32 v64, 3, v64
	v_med3_i32 v65, v97, 0, s51
	v_med3_i32 v66, v99, 0, s51
	v_med3_i32 v67, v101, 0, s51
	v_lshlrev_b32_e32 v65, 3, v65
	v_lshlrev_b32_e32 v66, 3, v66
	v_lshlrev_b32_e32 v67, 3, v67
	v_cndmask_b32_e64 v103, v96, v190, s[4:5]
	v_mov_b32_e32 v112, v181
	v_mov_b32_e32 v113, v181
	ds_read_b128 v[72:75], v193
	ds_read_b128 v[84:87], v193 offset:128
	ds_read_b128 v[88:91], v193 offset:256
	ds_read_b128 v[92:95], v193 offset:384
	ds_read_b128 v[64:67], v193 offset:512
	ds_read_b128 v[68:71], v193 offset:640
	ds_read_b128 v[76:79], v193 offset:768
	ds_read_b128 v[80:83], v193 offset:896
	s_waitcnt vmcnt(8)
	v_mov_b32_e32 v104, v242
	v_mov_b32_e32 v105, v243
	v_mov_b32_e32 v106, v244
	v_mov_b32_e32 v107, v245
	v_mov_b32_e32 v108, v246
	v_mov_b32_e32 v109, v247
	v_mov_b32_e32 v110, v248
	v_mov_b32_e32 v111, v249
	v_ffbh_u32_e32 v98, v105
	v_ffbh_u32_e32 v100, v107
	v_ffbh_u32_e32 v102, v109
	v_min_u32_e32 v98, 32, v98
	v_min_u32_e32 v100, 32, v100
	v_min_u32_e32 v102, 32, v102
	v_lshlrev_b64 v[104:105], v98, v[104:105]
	v_ffbh_u32_e32 v114, v111
	v_lshlrev_b64 v[106:107], v100, v[106:107]
	v_lshlrev_b64 v[108:109], v102, v[108:109]
	v_min_u32_e32 v104, 1, v104
	v_min_u32_e32 v114, 32, v114
	v_min_u32_e32 v106, 1, v106
	v_min_u32_e32 v108, 1, v108
	v_or_b32_e32 v104, v105, v104
	v_lshlrev_b64 v[110:111], v114, v[110:111]
	v_or_b32_e32 v105, v107, v106
	v_or_b32_e32 v106, v109, v108
	v_cvt_f32_u32_e32 v104, v104
	v_min_u32_e32 v110, 1, v110
	v_cvt_f32_u32_e32 v105, v105
	v_cvt_f32_u32_e32 v106, v106
	v_or_b32_e32 v107, v111, v110
	v_sub_u32_e32 v98, 32, v98
	v_cvt_f32_u32_e32 v107, v107
	v_sub_u32_e32 v100, 32, v100
	v_sub_u32_e32 v102, 32, v102
	v_ldexp_f32 v98, v104, v98
	v_ldexp_f32 v100, v105, v100
	v_ldexp_f32 v102, v106, v102
	v_fmamk_f32 v98, v98, 0x30800000, v196
	v_sub_u32_e32 v114, 32, v114
	v_fmamk_f32 v100, v100, 0x30800000, v196
	v_fmamk_f32 v102, v102, 0x30800000, v196
	v_mul_f32_e32 v105, 0x4b800000, v98
	v_cmp_gt_f32_e32 vcc, s52, v98
	v_ldexp_f32 v104, v107, v114
	v_mul_f32_e32 v106, 0x4b800000, v100
	v_mul_f32_e32 v107, 0x4b800000, v102
	v_cndmask_b32_e32 v98, v98, v105, vcc
	v_cmp_gt_f32_e64 s[8:9], s52, v100
	v_cmp_gt_f32_e64 s[10:11], s52, v102
	v_fmamk_f32 v104, v104, 0x30800000, v196
	v_cndmask_b32_e64 v100, v100, v106, s[8:9]
	v_cndmask_b32_e64 v102, v102, v107, s[10:11]
	v_rsq_f32_e32 v98, v98
	v_mul_f32_e32 v108, 0x4b800000, v104
	v_cmp_gt_f32_e64 s[12:13], s52, v104
	v_rsq_f32_e32 v100, v100
	v_rsq_f32_e32 v102, v102
	v_cndmask_b32_e64 v104, v104, v108, s[12:13]
	v_rsq_f32_e32 v104, v104
	v_mul_f32_e32 v105, 0x45800000, v98
	v_mul_f32_e32 v106, 0x45800000, v100
	v_mul_f32_e32 v107, 0x45800000, v102
	v_cndmask_b32_e32 v98, v98, v105, vcc
	v_cmp_lt_i32_e32 vcc, -1, v96
	v_cndmask_b32_e64 v100, v100, v106, s[8:9]
	v_cndmask_b32_e64 v105, v102, v107, s[10:11]
	v_cndmask_b32_e32 v102, 0, v98, vcc
	v_cmp_lt_i32_e32 vcc, s53, v96
	v_mul_f32_e32 v108, 0x45800000, v104
	v_cndmask_b32_e64 v104, v104, v108, s[12:13]
	v_cndmask_b32_e32 v100, 0, v100, vcc
	v_cmp_lt_i32_e32 vcc, s54, v96
	v_pk_mul_f32 v[60:61], v[60:61], v[102:103] op_sel_hi:[1,0]
	v_pk_mul_f32 v[56:57], v[56:57], v[102:103] op_sel_hi:[1,0]
	v_cndmask_b32_e32 v98, 0, v105, vcc
	v_cmp_lt_i32_e32 vcc, s55, v96
	v_mov_b32_dpp v112, v60 row_shr:1 row_mask:0xf bank_mask:0xf
	v_mov_b32_dpp v113, v61 row_shr:1 row_mask:0xf bank_mask:0xf
	v_cndmask_b32_e32 v96, 0, v104, vcc
	v_pk_mul_f32 v[108:109], v[32:33], v[96:97] op_sel_hi:[1,0]
	v_mov_b32_e32 v32, v183
	v_mov_b32_e32 v33, v183
	v_pk_mul_f32 v[104:105], v[40:41], v[98:99] op_sel_hi:[1,0]
	v_mov_b32_dpp v32, v60 row_shr:2 row_mask:0xf bank_mask:0xf
	v_mov_b32_dpp v33, v61 row_shr:2 row_mask:0xf bank_mask:0xf
	s_waitcnt lgkmcnt(6)
	v_pk_fma_f32 v[32:33], v[84:85], v[32:33], v[72:73]
	v_mov_b32_e32 v40, v183
	s_waitcnt lgkmcnt(5)
	v_pk_fma_f32 v[32:33], v[88:89], v[112:113], v[32:33]
	v_mov_b32_e32 v41, v183
	s_waitcnt lgkmcnt(4)
	v_pk_fma_f32 v[32:33], v[92:93], v[60:61], v[32:33]
	v_pk_mul_f32 v[106:107], v[36:37], v[96:97] op_sel_hi:[1,0]
	v_pk_mul_f32 v[110:111], v[32:33], s[2:3] op_sel_hi:[1,0]
	v_mov_b32_e32 v36, v181
	v_exp_f32_e32 v110, v110
	v_exp_f32_e32 v111, v111
	v_mov_b32_e32 v37, v181
	v_mov_b32_dpp v40, v56 row_shr:2 row_mask:0xf bank_mask:0xf
	v_mov_b32_dpp v41, v57 row_shr:2 row_mask:0xf bank_mask:0xf
	v_pk_add_f32 v[110:111], v[110:111], 1.0 op_sel_hi:[1,0]
	v_mov_b32_dpp v36, v56 row_shr:1 row_mask:0xf bank_mask:0xf
	v_rcp_f32_e32 v110, v110
	v_rcp_f32_e32 v111, v111
	v_mov_b32_dpp v37, v57 row_shr:1 row_mask:0xf bank_mask:0xf
	s_waitcnt lgkmcnt(2)
; #define LAS __attribute__((address_space(3)))
; DI unsigned pk2(float lo, float hi) { f32x2 v = {lo, hi}; bf16x2_t b = __builtin_convertvector(v, bf16x2_t); return __builtin_bit_cast(unsigned, b); }
;     DI void operator()(const AccT& acc, const Unit& u, int wr, int wc, int fr, int fq) const {
;     ...
;                     const f32x2 bg = *(const LAS f32x2*)(P + lc + 2 * jp), g0 = *(const LAS f32x2*)(P + 32 + lc + 2 * jp), g1 = *(const LAS f32x2*)(P + 64 + lc + 2 * jp), g2 = *(const LAS f32x2*)(P + 96 + lc + 2 * jp);
;                     const f32x2 bv = *(const LAS f32x2*)(P + 128 + lc + 2 * jp), v0 = *(const LAS f32x2*)(P + 160 + lc + 2 * jp), v1 = *(const LAS f32x2*)(P + 192 + lc + 2 * jp), v2 = *(const LAS f32x2*)(P + 224 + lc + 2 * jp);
;                     f32x2 G[4], V[4];
; #pragma unroll
;                     for (int m = 0; m < 4; ++m) { G[m] = (f32x2){acc[ai][0][m][n][2 * jp], acc[ai][0][m][n][2 * jp + 1]} * rs[m]; V[m] = (f32x2){acc[ai][1][m][n][2 * jp], acc[ai][1][m][n][2 * jp + 1]} * rs[m]; }
; #pragma unroll
;                     for (int m = 0; m < 4; ++m) {
;                         const f32x2 zz = {0.f, 0.f}; const f32x2 Gp = m ? G[m - 1] : zz, Vp = m ? V[m - 1] : zz;
;                         const f32x2 gp1 = {dpp_prev1(G[m].x, Gp.x), dpp_prev1(G[m].y, Gp.y)}, gp2 = {dpp_prev2(G[m].x, Gp.x), dpp_prev2(G[m].y, Gp.y)};
;                         const f32x2 vp1 = {dpp_prev1(V[m].x, Vp.x), dpp_prev1(V[m].y, Vp.y)}, vp2 = {dpp_prev2(V[m].x, Vp.x), dpp_prev2(V[m].y, Vp.y)};
;                         const f32x2 gc = bg + g0 * gp2 + g1 * gp1 + g2 * G[m];
;                         const f32x2 vc = bv + v0 * vp2 + v1 * vp1 + v2 * V[m];
;                         const f32x2 xe = gc * (-LOG2E);
;                         f32x2 dn = {__builtin_amdgcn_exp2f(xe.x), __builtin_amdgcn_exp2f(xe.y)}; dn = dn + 1.0f;
;                         const f32x2 rc = {__builtin_amdgcn_rcpf(dn.x), __builtin_amdgcn_rcpf(dn.y)};
;                         const f32x2 rr = gc * rc * vc;
;                         wpk[m][jp] = pk2(rr.x, rr.y); }
	v_pk_fma_f32 v[40:41], v[68:69], v[40:41], v[64:65]
	v_pk_mul_f32 v[52:53], v[52:53], v[100:101] op_sel_hi:[1,0]
	s_waitcnt lgkmcnt(1)
	v_pk_fma_f32 v[36:37], v[76:77], v[36:37], v[40:41]
	v_pk_mul_f32 v[32:33], v[32:33], v[110:111]
	s_waitcnt lgkmcnt(0)
	v_pk_fma_f32 v[36:37], v[80:81], v[56:57], v[36:37]
	v_pk_mul_f32 v[32:33], v[36:37], v[32:33]
	v_mov_b32_dpp v40, v60 row_ror:2 row_mask:0xf bank_mask:0xf
	v_mov_b32_dpp v41, v61 row_ror:2 row_mask:0xf bank_mask:0xf
	v_mov_b32_dpp v36, v60 row_ror:1 row_mask:0xf bank_mask:0xf
	v_mov_b32_dpp v37, v61 row_ror:1 row_mask:0xf bank_mask:0xf
	v_mov_b32_dpp v40, v52 row_shr:2 row_mask:0xf bank_mask:0xf
	v_mov_b32_dpp v41, v53 row_shr:2 row_mask:0xf bank_mask:0xf
	v_mov_b32_dpp v36, v52 row_shr:1 row_mask:0xf bank_mask:0xf
	v_mov_b32_dpp v37, v53 row_shr:1 row_mask:0xf bank_mask:0xf
	v_pk_fma_f32 v[40:41], v[84:85], v[40:41], v[72:73]
	v_pk_fma_f32 v[36:37], v[88:89], v[36:37], v[40:41]
	v_pk_fma_f32 v[36:37], v[92:93], v[52:53], v[36:37]
	v_pk_mul_f32 v[48:49], v[48:49], v[100:101] op_sel_hi:[1,0]
	v_pk_mul_f32 v[40:41], v[36:37], s[2:3] op_sel_hi:[1,0]
	v_exp_f32_e32 v40, v40
	v_exp_f32_e32 v41, v41
	v_mov_b32_dpp v110, v56 row_ror:2 row_mask:0xf bank_mask:0xf
	v_mov_b32_dpp v111, v57 row_ror:2 row_mask:0xf bank_mask:0xf
	v_pk_add_f32 v[40:41], v[40:41], 1.0 op_sel_hi:[1,0]
	v_mov_b32_dpp v60, v56 row_ror:1 row_mask:0xf bank_mask:0xf
	v_rcp_f32_e32 v40, v40
	v_rcp_f32_e32 v41, v41
	v_mov_b32_dpp v61, v57 row_ror:1 row_mask:0xf bank_mask:0xf
	v_mov_b32_dpp v110, v48 row_shr:2 row_mask:0xf bank_mask:0xf
	v_mov_b32_dpp v111, v49 row_shr:2 row_mask:0xf bank_mask:0xf
	v_mov_b32_dpp v60, v48 row_shr:1 row_mask:0xf bank_mask:0xf
	v_mov_b32_dpp v61, v49 row_shr:1 row_mask:0xf bank_mask:0xf
	v_pk_fma_f32 v[56:57], v[68:69], v[110:111], v[64:65]
	v_pk_mul_f32 v[36:37], v[36:37], v[40:41]
	v_pk_fma_f32 v[56:57], v[76:77], v[60:61], v[56:57]
	v_pk_mul_f32 v[44:45], v[44:45], v[98:99] op_sel_hi:[1,0]
	v_pk_fma_f32 v[56:57], v[80:81], v[48:49], v[56:57]
	v_pk_mul_f32 v[36:37], v[56:57], v[36:37]
	v_mov_b32_dpp v56, v52 row_ror:2 row_mask:0xf bank_mask:0xf
	v_mov_b32_dpp v57, v53 row_ror:2 row_mask:0xf bank_mask:0xf
	v_mov_b32_dpp v40, v52 row_ror:1 row_mask:0xf bank_mask:0xf
	v_mov_b32_dpp v41, v53 row_ror:1 row_mask:0xf bank_mask:0xf
	v_mov_b32_dpp v56, v44 row_shr:2 row_mask:0xf bank_mask:0xf
	v_mov_b32_dpp v57, v45 row_shr:2 row_mask:0xf bank_mask:0xf
	v_mov_b32_dpp v40, v44 row_shr:1 row_mask:0xf bank_mask:0xf
	v_mov_b32_dpp v41, v45 row_shr:1 row_mask:0xf bank_mask:0xf
	v_pk_fma_f32 v[56:57], v[84:85], v[56:57], v[72:73]
	v_pk_fma_f32 v[40:41], v[88:89], v[40:41], v[56:57]
	v_pk_fma_f32 v[40:41], v[92:93], v[44:45], v[40:41]
	v_pk_mul_f32 v[56:57], v[40:41], s[2:3] op_sel_hi:[1,0]
	v_exp_f32_e32 v56, v56
	v_exp_f32_e32 v57, v57
	v_mov_b32_dpp v52, v48 row_ror:1 row_mask:0xf bank_mask:0xf
	v_mov_b32_dpp v53, v49 row_ror:1 row_mask:0xf bank_mask:0xf
	v_mov_b32_dpp v60, v48 row_ror:2 row_mask:0xf bank_mask:0xf
	v_mov_b32_dpp v61, v49 row_ror:2 row_mask:0xf bank_mask:0xf
	v_pk_add_f32 v[48:49], v[56:57], 1.0 op_sel_hi:[1,0]
	v_mov_b32_dpp v60, v104 row_shr:2 row_mask:0xf bank_mask:0xf
	v_rcp_f32_e32 v48, v48
	v_rcp_f32_e32 v49, v49
	v_mov_b32_dpp v61, v105 row_shr:2 row_mask:0xf bank_mask:0xf
	v_mov_b32_dpp v52, v104 row_shr:1 row_mask:0xf bank_mask:0xf
	v_mov_b32_dpp v53, v105 row_shr:1 row_mask:0xf bank_mask:0xf
	v_pk_fma_f32 v[56:57], v[68:69], v[60:61], v[64:65]
	v_pk_mul_f32 v[40:41], v[40:41], v[48:49]
	v_pk_fma_f32 v[52:53], v[76:77], v[52:53], v[56:57]
	v_pk_fma_f32 v[52:53], v[80:81], v[104:105], v[52:53]
	v_pk_mul_f32 v[40:41], v[52:53], v[40:41]
	v_mov_b32_dpp v48, v44 row_ror:1 row_mask:0xf bank_mask:0xf
	v_mov_b32_dpp v52, v44 row_ror:2 row_mask:0xf bank_mask:0xf
	v_mov_b32_dpp v53, v45 row_ror:2 row_mask:0xf bank_mask:0xf
	v_mov_b32_dpp v49, v45 row_ror:1 row_mask:0xf bank_mask:0xf
	v_mov_b32_dpp v52, v106 row_shr:2 row_mask:0xf bank_mask:0xf
	v_mov_b32_dpp v53, v107 row_shr:2 row_mask:0xf bank_mask:0xf
	v_mov_b32_dpp v48, v106 row_shr:1 row_mask:0xf bank_mask:0xf
	v_mov_b32_dpp v49, v107 row_shr:1 row_mask:0xf bank_mask:0xf
	v_pk_fma_f32 v[52:53], v[84:85], v[52:53], v[72:73]
	v_pk_fma_f32 v[48:49], v[88:89], v[48:49], v[52:53]
	v_pk_fma_f32 v[48:49], v[92:93], v[106:107], v[48:49]
	v_pk_mul_f32 v[52:53], v[48:49], s[2:3] op_sel_hi:[1,0]
	v_exp_f32_e32 v52, v52
	v_exp_f32_e32 v53, v53
	v_mov_b32_dpp v56, v104 row_ror:2 row_mask:0xf bank_mask:0xf
	v_mov_b32_dpp v57, v105 row_ror:2 row_mask:0xf bank_mask:0xf
	v_mov_b32_dpp v44, v104 row_ror:1 row_mask:0xf bank_mask:0xf
	v_pk_add_f32 v[52:53], v[52:53], 1.0 op_sel_hi:[1,0]
	v_mov_b32_dpp v45, v105 row_ror:1 row_mask:0xf bank_mask:0xf
	v_rcp_f32_e32 v52, v52
	v_rcp_f32_e32 v53, v53
	v_mov_b32_dpp v56, v108 row_shr:2 row_mask:0xf bank_mask:0xf
	v_mov_b32_dpp v57, v109 row_shr:2 row_mask:0xf bank_mask:0xf
	v_mov_b32_dpp v44, v108 row_shr:1 row_mask:0xf bank_mask:0xf
	v_mov_b32_dpp v45, v109 row_shr:1 row_mask:0xf bank_mask:0xf
	v_pk_fma_f32 v[56:57], v[68:69], v[56:57], v[64:65]
	v_pk_mul_f32 v[48:49], v[48:49], v[52:53]
	v_pk_fma_f32 v[44:45], v[76:77], v[44:45], v[56:57]
	v_pk_mul_f32 v[52:53], v[58:59], v[102:103] op_sel_hi:[1,0]
	v_pk_fma_f32 v[44:45], v[80:81], v[108:109], v[44:45]
	v_mov_b32_e32 v58, v183
	v_pk_mul_f32 v[44:45], v[44:45], v[48:49]
	v_pk_mul_f32 v[48:49], v[62:63], v[102:103] op_sel_hi:[1,0]
	v_mov_b32_e32 v59, v183
	v_mov_b32_e32 v56, v181
	v_mov_b32_e32 v57, v181
	v_mov_b32_dpp v58, v48 row_shr:2 row_mask:0xf bank_mask:0xf
	v_mov_b32_dpp v59, v49 row_shr:2 row_mask:0xf bank_mask:0xf
	v_mov_b32_dpp v56, v48 row_shr:1 row_mask:0xf bank_mask:0xf
; #define LAS __attribute__((address_space(3)))
; DI unsigned pk2(float lo, float hi) { f32x2 v = {lo, hi}; bf16x2_t b = __builtin_convertvector(v, bf16x2_t); return __builtin_bit_cast(unsigned, b); }
;     DI void operator()(const AccT& acc, const Unit& u, int wr, int wc, int fr, int fq) const {
;     ...
;                     const f32x2 bg = *(const LAS f32x2*)(P + lc + 2 * jp), g0 = *(const LAS f32x2*)(P + 32 + lc + 2 * jp), g1 = *(const LAS f32x2*)(P + 64 + lc + 2 * jp), g2 = *(const LAS f32x2*)(P + 96 + lc + 2 * jp);
;                     const f32x2 bv = *(const LAS f32x2*)(P + 128 + lc + 2 * jp), v0 = *(const LAS f32x2*)(P + 160 + lc + 2 * jp), v1 = *(const LAS f32x2*)(P + 192 + lc + 2 * jp), v2 = *(const LAS f32x2*)(P + 224 + lc + 2 * jp);
;                     f32x2 G[4], V[4];
; #pragma unroll
;                     for (int m = 0; m < 4; ++m) { G[m] = (f32x2){acc[ai][0][m][n][2 * jp], acc[ai][0][m][n][2 * jp + 1]} * rs[m]; V[m] = (f32x2){acc[ai][1][m][n][2 * jp], acc[ai][1][m][n][2 * jp + 1]} * rs[m]; }
; #pragma unroll
;                     for (int m = 0; m < 4; ++m) {
;                         const f32x2 zz = {0.f, 0.f}; const f32x2 Gp = m ? G[m - 1] : zz, Vp = m ? V[m - 1] : zz;
;                         const f32x2 gp1 = {dpp_prev1(G[m].x, Gp.x), dpp_prev1(G[m].y, Gp.y)}, gp2 = {dpp_prev2(G[m].x, Gp.x), dpp_prev2(G[m].y, Gp.y)};
;                         const f32x2 vp1 = {dpp_prev1(V[m].x, Vp.x), dpp_prev1(V[m].y, Vp.y)}, vp2 = {dpp_prev2(V[m].x, Vp.x), dpp_prev2(V[m].y, Vp.y)};
;                         const f32x2 gc = bg + g0 * gp2 + g1 * gp1 + g2 * G[m];
;                         const f32x2 vc = bv + v0 * vp2 + v1 * vp1 + v2 * V[m];
;                         const f32x2 xe = gc * (-LOG2E);
;                         f32x2 dn = {__builtin_amdgcn_exp2f(xe.x), __builtin_amdgcn_exp2f(xe.y)}; dn = dn + 1.0f;
;                         const f32x2 rc = {__builtin_amdgcn_rcpf(dn.x), __builtin_amdgcn_rcpf(dn.y)};
;                         const f32x2 rr = gc * rc * vc;
;                         wpk[m][jp] = pk2(rr.x, rr.y); }
	v_mov_b32_dpp v57, v49 row_shr:1 row_mask:0xf bank_mask:0xf
	v_pk_fma_f32 v[58:59], v[86:87], v[58:59], v[74:75]
	v_mov_b32_e32 v62, v183
	v_pk_fma_f32 v[56:57], v[90:91], v[56:57], v[58:59]
	v_mov_b32_e32 v63, v183
	v_pk_fma_f32 v[56:57], v[48:49], v[94:95], v[56:57]
	v_mov_b32_e32 v60, v181
	v_pk_mul_f32 v[58:59], v[56:57], s[2:3] op_sel_hi:[1,0]
	v_mov_b32_e32 v61, v181
	v_exp_f32_e32 v58, v58
	v_exp_f32_e32 v59, v59
	v_mov_b32_dpp v62, v52 row_shr:2 row_mask:0xf bank_mask:0xf
	v_mov_b32_dpp v63, v53 row_shr:2 row_mask:0xf bank_mask:0xf
	v_mov_b32_dpp v60, v52 row_shr:1 row_mask:0xf bank_mask:0xf
	v_pk_add_f32 v[58:59], v[58:59], 1.0 op_sel_hi:[1,0]
	v_mov_b32_dpp v61, v53 row_shr:1 row_mask:0xf bank_mask:0xf
	v_rcp_f32_e32 v58, v58
	v_rcp_f32_e32 v59, v59
	v_pk_fma_f32 v[62:63], v[70:71], v[62:63], v[66:67]
	v_cvt_pk_bf16_f32 v32, v32, v33
	v_pk_fma_f32 v[60:61], v[78:79], v[60:61], v[62:63]
	v_pk_mul_f32 v[56:57], v[56:57], v[58:59]
	v_pk_fma_f32 v[60:61], v[52:53], v[82:83], v[60:61]
	v_pk_mul_f32 v[56:57], v[60:61], v[56:57]
	v_pk_mul_f32 v[54:55], v[54:55], v[100:101] op_sel_hi:[1,0]
	v_cvt_pk_bf16_f32 v33, v56, v57
	v_mov_b32_dpp v58, v48 row_ror:2 row_mask:0xf bank_mask:0xf
	v_mov_b32_dpp v59, v49 row_ror:2 row_mask:0xf bank_mask:0xf
	v_mov_b32_dpp v56, v48 row_ror:1 row_mask:0xf bank_mask:0xf
	v_mov_b32_dpp v57, v49 row_ror:1 row_mask:0xf bank_mask:0xf
	v_mov_b32_dpp v58, v54 row_shr:2 row_mask:0xf bank_mask:0xf
	v_mov_b32_dpp v59, v55 row_shr:2 row_mask:0xf bank_mask:0xf
	v_mov_b32_dpp v56, v54 row_shr:1 row_mask:0xf bank_mask:0xf
	v_mov_b32_dpp v57, v55 row_shr:1 row_mask:0xf bank_mask:0xf
	v_pk_fma_f32 v[58:59], v[86:87], v[58:59], v[74:75]
	v_pk_fma_f32 v[56:57], v[90:91], v[56:57], v[58:59]
	v_pk_fma_f32 v[56:57], v[54:55], v[94:95], v[56:57]
	v_pk_mul_f32 v[58:59], v[56:57], s[2:3] op_sel_hi:[1,0]
	v_exp_f32_e32 v58, v58
	v_exp_f32_e32 v59, v59
	v_mov_b32_dpp v48, v52 row_ror:1 row_mask:0xf bank_mask:0xf
	v_mov_b32_dpp v49, v53 row_ror:1 row_mask:0xf bank_mask:0xf
	v_mov_b32_dpp v60, v52 row_ror:2 row_mask:0xf bank_mask:0xf
	v_mov_b32_dpp v61, v53 row_ror:2 row_mask:0xf bank_mask:0xf
	v_pk_add_f32 v[52:53], v[58:59], 1.0 op_sel_hi:[1,0]
	v_pk_mul_f32 v[50:51], v[50:51], v[100:101] op_sel_hi:[1,0]
	v_rcp_f32_e32 v52, v52
	v_rcp_f32_e32 v53, v53
	v_mov_b32_dpp v60, v50 row_shr:2 row_mask:0xf bank_mask:0xf
	v_mov_b32_dpp v61, v51 row_shr:2 row_mask:0xf bank_mask:0xf
	v_mov_b32_dpp v48, v50 row_shr:1 row_mask:0xf bank_mask:0xf
	v_mov_b32_dpp v49, v51 row_shr:1 row_mask:0xf bank_mask:0xf
	v_pk_fma_f32 v[58:59], v[70:71], v[60:61], v[66:67]
	v_pk_mul_f32 v[52:53], v[56:57], v[52:53]
	v_pk_fma_f32 v[48:49], v[78:79], v[48:49], v[58:59]
	v_cvt_pk_bf16_f32 v36, v36, v37
	v_pk_fma_f32 v[48:49], v[50:51], v[82:83], v[48:49]
	v_pk_mul_f32 v[46:47], v[46:47], v[98:99] op_sel_hi:[1,0]
	v_pk_mul_f32 v[48:49], v[48:49], v[52:53]
	v_cvt_pk_bf16_f32 v37, v48, v49
	v_mov_b32_dpp v52, v54 row_ror:2 row_mask:0xf bank_mask:0xf
	v_mov_b32_dpp v53, v55 row_ror:2 row_mask:0xf bank_mask:0xf
	v_mov_b32_dpp v48, v54 row_ror:1 row_mask:0xf bank_mask:0xf
	v_mov_b32_dpp v49, v55 row_ror:1 row_mask:0xf bank_mask:0xf
	v_mov_b32_dpp v52, v46 row_shr:2 row_mask:0xf bank_mask:0xf
	v_mov_b32_dpp v53, v47 row_shr:2 row_mask:0xf bank_mask:0xf
	v_mov_b32_dpp v48, v46 row_shr:1 row_mask:0xf bank_mask:0xf
	v_mov_b32_dpp v49, v47 row_shr:1 row_mask:0xf bank_mask:0xf
	v_pk_fma_f32 v[52:53], v[86:87], v[52:53], v[74:75]
	v_pk_fma_f32 v[48:49], v[90:91], v[48:49], v[52:53]
	v_pk_fma_f32 v[48:49], v[46:47], v[94:95], v[48:49]
	v_pk_mul_f32 v[52:53], v[48:49], s[2:3] op_sel_hi:[1,0]
	v_exp_f32_e32 v52, v52
	v_exp_f32_e32 v53, v53
	v_mov_b32_dpp v54, v50 row_ror:1 row_mask:0xf bank_mask:0xf
	v_mov_b32_dpp v55, v51 row_ror:1 row_mask:0xf bank_mask:0xf
	v_mov_b32_dpp v56, v50 row_ror:2 row_mask:0xf bank_mask:0xf
	v_mov_b32_dpp v57, v51 row_ror:2 row_mask:0xf bank_mask:0xf
	v_pk_add_f32 v[50:51], v[52:53], 1.0 op_sel_hi:[1,0]
	v_pk_mul_f32 v[42:43], v[42:43], v[98:99] op_sel_hi:[1,0]
	v_rcp_f32_e32 v50, v50
	v_rcp_f32_e32 v51, v51
	v_mov_b32_dpp v56, v42 row_shr:2 row_mask:0xf bank_mask:0xf
	v_mov_b32_dpp v57, v43 row_shr:2 row_mask:0xf bank_mask:0xf
	v_mov_b32_dpp v54, v42 row_shr:1 row_mask:0xf bank_mask:0xf
	v_mov_b32_dpp v55, v43 row_shr:1 row_mask:0xf bank_mask:0xf
	v_pk_fma_f32 v[52:53], v[70:71], v[56:57], v[66:67]
	v_pk_mul_f32 v[48:49], v[48:49], v[50:51]
	v_pk_fma_f32 v[52:53], v[78:79], v[54:55], v[52:53]
	v_pk_fma_f32 v[52:53], v[42:43], v[82:83], v[52:53]
	v_pk_mul_f32 v[48:49], v[52:53], v[48:49]
	v_cvt_pk_bf16_f32 v40, v40, v41
	v_pk_mul_f32 v[38:39], v[38:39], v[96:97] op_sel_hi:[1,0]
	v_cvt_pk_bf16_f32 v41, v48, v49
	v_mov_b32_dpp v50, v46 row_ror:2 row_mask:0xf bank_mask:0xf
	v_mov_b32_dpp v51, v47 row_ror:2 row_mask:0xf bank_mask:0xf
	v_mov_b32_dpp v48, v46 row_ror:1 row_mask:0xf bank_mask:0xf
	v_mov_b32_dpp v49, v47 row_ror:1 row_mask:0xf bank_mask:0xf
	v_mov_b32_dpp v50, v38 row_shr:2 row_mask:0xf bank_mask:0xf
	v_mov_b32_dpp v51, v39 row_shr:2 row_mask:0xf bank_mask:0xf
	v_mov_b32_dpp v48, v38 row_shr:1 row_mask:0xf bank_mask:0xf
	v_mov_b32_dpp v49, v39 row_shr:1 row_mask:0xf bank_mask:0xf
	v_pk_fma_f32 v[50:51], v[86:87], v[50:51], v[74:75]
	v_pk_fma_f32 v[48:49], v[90:91], v[48:49], v[50:51]
	v_pk_fma_f32 v[38:39], v[38:39], v[94:95], v[48:49]
	v_pk_mul_f32 v[48:49], v[38:39], s[2:3] op_sel_hi:[1,0]
	v_exp_f32_e32 v48, v48
	v_exp_f32_e32 v49, v49
	v_mov_b32_dpp v46, v42 row_ror:1 row_mask:0xf bank_mask:0xf
	v_mov_b32_dpp v47, v43 row_ror:1 row_mask:0xf bank_mask:0xf
	v_mov_b32_dpp v52, v42 row_ror:2 row_mask:0xf bank_mask:0xf
; #define LAS __attribute__((address_space(3)))
; DI unsigned pk2(float lo, float hi) { f32x2 v = {lo, hi}; bf16x2_t b = __builtin_convertvector(v, bf16x2_t); return __builtin_bit_cast(unsigned, b); }
;     DI void operator()(const AccT& acc, const Unit& u, int wr, int wc, int fr, int fq) const {
;     ...
;                     const f32x2 bg = *(const LAS f32x2*)(P + lc + 2 * jp), g0 = *(const LAS f32x2*)(P + 32 + lc + 2 * jp), g1 = *(const LAS f32x2*)(P + 64 + lc + 2 * jp), g2 = *(const LAS f32x2*)(P + 96 + lc + 2 * jp);
;                     const f32x2 bv = *(const LAS f32x2*)(P + 128 + lc + 2 * jp), v0 = *(const LAS f32x2*)(P + 160 + lc + 2 * jp), v1 = *(const LAS f32x2*)(P + 192 + lc + 2 * jp), v2 = *(const LAS f32x2*)(P + 224 + lc + 2 * jp);
;                     f32x2 G[4], V[4];
; #pragma unroll
;                     for (int m = 0; m < 4; ++m) { G[m] = (f32x2){acc[ai][0][m][n][2 * jp], acc[ai][0][m][n][2 * jp + 1]} * rs[m]; V[m] = (f32x2){acc[ai][1][m][n][2 * jp], acc[ai][1][m][n][2 * jp + 1]} * rs[m]; }
; #pragma unroll
;                     for (int m = 0; m < 4; ++m) {
;                         const f32x2 zz = {0.f, 0.f}; const f32x2 Gp = m ? G[m - 1] : zz, Vp = m ? V[m - 1] : zz;
;                         const f32x2 gp1 = {dpp_prev1(G[m].x, Gp.x), dpp_prev1(G[m].y, Gp.y)}, gp2 = {dpp_prev2(G[m].x, Gp.x), dpp_prev2(G[m].y, Gp.y)};
;                         const f32x2 vp1 = {dpp_prev1(V[m].x, Vp.x), dpp_prev1(V[m].y, Vp.y)}, vp2 = {dpp_prev2(V[m].x, Vp.x), dpp_prev2(V[m].y, Vp.y)};
;                         const f32x2 gc = bg + g0 * gp2 + g1 * gp1 + g2 * G[m];
;                         const f32x2 vc = bv + v0 * vp2 + v1 * vp1 + v2 * V[m];
;                         const f32x2 xe = gc * (-LOG2E);
;                         f32x2 dn = {__builtin_amdgcn_exp2f(xe.x), __builtin_amdgcn_exp2f(xe.y)}; dn = dn + 1.0f;
;                         const f32x2 rc = {__builtin_amdgcn_rcpf(dn.x), __builtin_amdgcn_rcpf(dn.y)};
;                         const f32x2 rr = gc * rc * vc;
;                         wpk[m][jp] = pk2(rr.x, rr.y); }
;                 }
; #pragma unroll
;                 for (int m = 0; m < 4; ++m) { const int row = m ? tok0 + 16 * m : row0;
;                     *(u32x2*)(ACT + (size_t)row * 2816 + cl + 4 * n) = (u32x2){wpk[m][0], wpk[m][1]}; }
	v_mov_b32_dpp v53, v43 row_ror:2 row_mask:0xf bank_mask:0xf
	v_pk_add_f32 v[42:43], v[48:49], 1.0 op_sel_hi:[1,0]
	v_pk_mul_f32 v[34:35], v[34:35], v[96:97] op_sel_hi:[1,0]
	v_rcp_f32_e32 v42, v42
	v_rcp_f32_e32 v43, v43
	v_mov_b32_dpp v52, v34 row_shr:2 row_mask:0xf bank_mask:0xf
	v_mov_b32_dpp v53, v35 row_shr:2 row_mask:0xf bank_mask:0xf
	v_mov_b32_dpp v46, v34 row_shr:1 row_mask:0xf bank_mask:0xf
	v_mov_b32_dpp v47, v35 row_shr:1 row_mask:0xf bank_mask:0xf
	v_pk_fma_f32 v[48:49], v[70:71], v[52:53], v[66:67]
	v_pk_mul_f32 v[38:39], v[38:39], v[42:43]
	v_pk_fma_f32 v[46:47], v[78:79], v[46:47], v[48:49]
	v_cvt_pk_bf16_f32 v44, v44, v45
	v_pk_fma_f32 v[34:35], v[34:35], v[82:83], v[46:47]
	s_nop 0
	v_pk_mul_f32 v[34:35], v[34:35], v[38:39]
	s_nop 0
	v_cvt_pk_bf16_f32 v45, v34, v35
	v_mad_i64_i32 v[34:35], s[8:9], v103, s48, v[128:129]
	v_lshl_add_u64 v[64:65], v[34:35], 0, v[130:131]
	global_store_dwordx2 v[64:65], v[32:33], off
	v_mad_i64_i32 v[32:33], s[8:9], v97, s48, v[128:129]
	v_lshl_add_u64 v[66:67], v[32:33], 0, v[130:131]
	v_mad_i64_i32 v[32:33], s[8:9], v99, s48, v[128:129]
	v_lshl_add_u64 v[68:69], v[32:33], 0, v[130:131]
	v_mad_i64_i32 v[32:33], s[8:9], v101, s48, v[128:129]
	v_lshl_add_u64 v[70:71], v[32:33], 0, v[130:131]
	global_store_dwordx2 v[66:67], v[36:37], off
	global_store_dwordx2 v[68:69], v[40:41], off
	global_store_dwordx2 v[70:71], v[44:45], off
	v_pk_mul_f32 v[30:31], v[30:31], v[102:103] op_sel_hi:[1,0]
	v_pk_mul_f32 v[22:23], v[22:23], v[100:101] op_sel_hi:[1,0]
	s_nop 0
	v_mov_b32_dpp v114, v30 row_ror:2 row_mask:0xf bank_mask:0xf
	v_mov_b32_dpp v115, v31 row_ror:2 row_mask:0xf bank_mask:0xf
	v_mov_b32_dpp v112, v30 row_ror:1 row_mask:0xf bank_mask:0xf
	v_mov_b32_dpp v113, v31 row_ror:1 row_mask:0xf bank_mask:0xf
	v_mov_b32_dpp v114, v22 row_shr:2 row_mask:0xf bank_mask:0xf
	v_mov_b32_dpp v115, v23 row_shr:2 row_mask:0xf bank_mask:0xf
	ds_read_b128 v[40:43], v193 offset:16
	ds_read_b128 v[52:55], v193 offset:144
	ds_read_b128 v[56:59], v193 offset:272
	ds_read_b128 v[60:63], v193 offset:400
	ds_read_b128 v[32:35], v193 offset:528
	ds_read_b128 v[36:39], v193 offset:656
	ds_read_b128 v[44:47], v193 offset:784
	ds_read_b128 v[48:51], v193 offset:912
	v_mov_b32_dpp v112, v22 row_shr:1 row_mask:0xf bank_mask:0xf
	v_mov_b32_dpp v113, v23 row_shr:1 row_mask:0xf bank_mask:0xf
	s_waitcnt lgkmcnt(6)
	v_pk_fma_f32 v[114:115], v[54:55], v[114:115], v[42:43]
	v_pk_mul_f32 v[28:29], v[28:29], v[102:103] op_sel_hi:[1,0]
	v_pk_mul_f32 v[24:25], v[24:25], v[102:103] op_sel_hi:[1,0]
	v_pk_mul_f32 v[20:21], v[20:21], v[100:101] op_sel_hi:[1,0]
	v_pk_mul_f32 v[16:17], v[16:17], v[100:101] op_sel_hi:[1,0]
	v_pk_mul_f32 v[26:27], v[26:27], v[102:103] op_sel_hi:[1,0]
	v_pk_mul_f32 v[100:101], v[18:19], v[100:101] op_sel_hi:[1,0]
	v_mov_b32_e32 v102, v183
	v_mov_b32_e32 v103, v183
	s_waitcnt lgkmcnt(5)
	v_pk_fma_f32 v[112:113], v[58:59], v[112:113], v[114:115]
	v_pk_mul_f32 v[76:77], v[12:13], v[98:99] op_sel_hi:[1,0]
	v_pk_mul_f32 v[72:73], v[8:9], v[98:99] op_sel_hi:[1,0]
	v_pk_mul_f32 v[14:15], v[14:15], v[98:99] op_sel_hi:[1,0]
	v_pk_mul_f32 v[10:11], v[10:11], v[98:99] op_sel_hi:[1,0]
	v_mov_b32_e32 v98, v181
	v_mov_b32_e32 v99, v181
	v_mov_b32_dpp v102, v30 row_shr:2 row_mask:0xf bank_mask:0xf
	v_mov_b32_dpp v103, v31 row_shr:2 row_mask:0xf bank_mask:0xf
	v_mov_b32_dpp v18, v22 row_ror:1 row_mask:0xf bank_mask:0xf
	v_mov_b32_dpp v19, v23 row_ror:1 row_mask:0xf bank_mask:0xf
	v_mov_b32_dpp v120, v22 row_ror:2 row_mask:0xf bank_mask:0xf
	v_mov_b32_dpp v121, v23 row_ror:2 row_mask:0xf bank_mask:0xf
	s_waitcnt lgkmcnt(4)
	v_pk_fma_f32 v[22:23], v[22:23], v[62:63], v[112:113]
	v_mov_b32_dpp v98, v30 row_shr:1 row_mask:0xf bank_mask:0xf
	v_mov_b32_dpp v99, v31 row_shr:1 row_mask:0xf bank_mask:0xf
	v_pk_mul_f32 v[112:113], v[22:23], s[2:3] op_sel_hi:[1,0]
	v_pk_fma_f32 v[102:103], v[54:55], v[102:103], v[42:43]
	v_exp_f32_e32 v112, v112
	v_exp_f32_e32 v113, v113
	v_pk_fma_f32 v[98:99], v[58:59], v[98:99], v[102:103]
	v_pk_fma_f32 v[30:31], v[30:31], v[62:63], v[98:99]
	v_pk_mul_f32 v[98:99], v[30:31], s[2:3] op_sel_hi:[1,0]
	v_pk_add_f32 v[112:113], v[112:113], 1.0 op_sel_hi:[1,0]
	v_exp_f32_e32 v98, v98
	v_exp_f32_e32 v99, v99
	v_mov_b32_dpp v118, v26 row_ror:2 row_mask:0xf bank_mask:0xf
	v_mov_b32_dpp v119, v27 row_ror:2 row_mask:0xf bank_mask:0xf
	v_rcp_f32_e32 v112, v112
	v_rcp_f32_e32 v113, v113
	v_mov_b32_dpp v116, v26 row_ror:1 row_mask:0xf bank_mask:0xf
	v_mov_b32_dpp v117, v27 row_ror:1 row_mask:0xf bank_mask:0xf
	v_mov_b32_dpp v118, v100 row_shr:2 row_mask:0xf bank_mask:0xf
	v_mov_b32_dpp v119, v101 row_shr:2 row_mask:0xf bank_mask:0xf
	v_mov_b32_dpp v116, v100 row_shr:1 row_mask:0xf bank_mask:0xf
	v_mov_b32_dpp v117, v101 row_shr:1 row_mask:0xf bank_mask:0xf
	s_waitcnt lgkmcnt(2)
	v_pk_fma_f32 v[114:115], v[38:39], v[118:119], v[34:35]
	v_pk_add_f32 v[98:99], v[98:99], 1.0 op_sel_hi:[1,0]
	v_mov_b32_e32 v182, v183
	s_waitcnt lgkmcnt(1)
	v_pk_fma_f32 v[114:115], v[46:47], v[116:117], v[114:115]
	v_rcp_f32_e32 v98, v98
	v_rcp_f32_e32 v99, v99
	v_pk_mul_f32 v[86:87], v[4:5], v[96:97] op_sel_hi:[1,0]
	v_mov_b32_e32 v12, v183
	v_mov_b32_e32 v13, v183
	v_mov_b32_e32 v4, v183
	v_mov_b32_e32 v5, v183
	v_mov_b32_e32 v180, v181
	v_mov_b32_dpp v182, v26 row_shr:2 row_mask:0xf bank_mask:0xf
	v_mov_b32_dpp v183, v27 row_shr:2 row_mask:0xf bank_mask:0xf
	v_mov_b32_dpp v122, v100 row_ror:1 row_mask:0xf bank_mask:0xf
	v_mov_b32_dpp v123, v101 row_ror:1 row_mask:0xf bank_mask:0xf
	v_mov_b32_dpp v124, v100 row_ror:2 row_mask:0xf bank_mask:0xf
	v_mov_b32_dpp v125, v101 row_ror:2 row_mask:0xf bank_mask:0xf
	s_waitcnt lgkmcnt(0)
; #define LAS __attribute__((address_space(3)))
; DI unsigned pk2(float lo, float hi) { f32x2 v = {lo, hi}; bf16x2_t b = __builtin_convertvector(v, bf16x2_t); return __builtin_bit_cast(unsigned, b); }
;     DI void operator()(const AccT& acc, const Unit& u, int wr, int wc, int fr, int fq) const {
;     ...
;                     const f32x2 bg = *(const LAS f32x2*)(P + lc + 2 * jp), g0 = *(const LAS f32x2*)(P + 32 + lc + 2 * jp), g1 = *(const LAS f32x2*)(P + 64 + lc + 2 * jp), g2 = *(const LAS f32x2*)(P + 96 + lc + 2 * jp);
;                     const f32x2 bv = *(const LAS f32x2*)(P + 128 + lc + 2 * jp), v0 = *(const LAS f32x2*)(P + 160 + lc + 2 * jp), v1 = *(const LAS f32x2*)(P + 192 + lc + 2 * jp), v2 = *(const LAS f32x2*)(P + 224 + lc + 2 * jp);
;                     f32x2 G[4], V[4];
; #pragma unroll
;                     for (int m = 0; m < 4; ++m) { G[m] = (f32x2){acc[ai][0][m][n][2 * jp], acc[ai][0][m][n][2 * jp + 1]} * rs[m]; V[m] = (f32x2){acc[ai][1][m][n][2 * jp], acc[ai][1][m][n][2 * jp + 1]} * rs[m]; }
; #pragma unroll
;                     for (int m = 0; m < 4; ++m) {
;                         const f32x2 zz = {0.f, 0.f}; const f32x2 Gp = m ? G[m - 1] : zz, Vp = m ? V[m - 1] : zz;
;                         const f32x2 gp1 = {dpp_prev1(G[m].x, Gp.x), dpp_prev1(G[m].y, Gp.y)}, gp2 = {dpp_prev2(G[m].x, Gp.x), dpp_prev2(G[m].y, Gp.y)};
;                         const f32x2 vp1 = {dpp_prev1(V[m].x, Vp.x), dpp_prev1(V[m].y, Vp.y)}, vp2 = {dpp_prev2(V[m].x, Vp.x), dpp_prev2(V[m].y, Vp.y)};
;                         const f32x2 gc = bg + g0 * gp2 + g1 * gp1 + g2 * G[m];
;                         const f32x2 vc = bv + v0 * vp2 + v1 * vp1 + v2 * V[m];
;                         const f32x2 xe = gc * (-LOG2E);
;                         f32x2 dn = {__builtin_amdgcn_exp2f(xe.x), __builtin_amdgcn_exp2f(xe.y)}; dn = dn + 1.0f;
;                         const f32x2 rc = {__builtin_amdgcn_rcpf(dn.x), __builtin_amdgcn_rcpf(dn.y)};
;                         const f32x2 rr = gc * rc * vc;
;                         wpk[m][jp] = pk2(rr.x, rr.y); }
	v_pk_fma_f32 v[100:101], v[100:101], v[50:51], v[114:115]
	v_pk_mul_f32 v[22:23], v[22:23], v[112:113]
	v_pk_mul_f32 v[84:85], v[0:1], v[96:97] op_sel_hi:[1,0]
	v_mov_b32_e32 v8, v181
	v_mov_b32_e32 v9, v181
	v_mov_b32_e32 v0, v181
	v_mov_b32_e32 v1, v181
	v_mov_b32_dpp v180, v26 row_shr:1 row_mask:0xf bank_mask:0xf
	v_mov_b32_dpp v181, v27 row_shr:1 row_mask:0xf bank_mask:0xf
	v_pk_mul_f32 v[22:23], v[100:101], v[22:23]
	v_pk_fma_f32 v[100:101], v[38:39], v[182:183], v[34:35]
	v_mov_b32_dpp v106, v76 row_ror:2 row_mask:0xf bank_mask:0xf
	v_mov_b32_dpp v107, v77 row_ror:2 row_mask:0xf bank_mask:0xf
	v_pk_fma_f32 v[100:101], v[46:47], v[180:181], v[100:101]
	v_mov_b32_dpp v104, v76 row_ror:1 row_mask:0xf bank_mask:0xf
	v_mov_b32_dpp v105, v77 row_ror:1 row_mask:0xf bank_mask:0xf
	v_mov_b32_dpp v106, v86 row_shr:2 row_mask:0xf bank_mask:0xf
	v_mov_b32_dpp v107, v87 row_shr:2 row_mask:0xf bank_mask:0xf
	v_pk_fma_f32 v[26:27], v[26:27], v[50:51], v[100:101]
	v_pk_mul_f32 v[30:31], v[30:31], v[98:99]
	v_mov_b32_dpp v104, v86 row_shr:1 row_mask:0xf bank_mask:0xf
	v_mov_b32_dpp v105, v87 row_shr:1 row_mask:0xf bank_mask:0xf
	v_pk_mul_f32 v[26:27], v[26:27], v[30:31]
	v_pk_fma_f32 v[30:31], v[52:53], v[106:107], v[40:41]
	v_mov_b32_dpp v12, v28 row_shr:2 row_mask:0xf bank_mask:0xf
	v_pk_fma_f32 v[30:31], v[56:57], v[104:105], v[30:31]
	v_mov_b32_dpp v13, v29 row_shr:2 row_mask:0xf bank_mask:0xf
	v_pk_fma_f32 v[30:31], v[86:87], v[60:61], v[30:31]
	v_pk_mul_f32 v[86:87], v[30:31], s[2:3] op_sel_hi:[1,0]
	v_mov_b32_dpp v8, v28 row_shr:1 row_mask:0xf bank_mask:0xf
	v_mov_b32_dpp v9, v29 row_shr:1 row_mask:0xf bank_mask:0xf
	v_mov_b32_dpp v92, v20 row_ror:2 row_mask:0xf bank_mask:0xf
	v_mov_b32_dpp v93, v21 row_ror:2 row_mask:0xf bank_mask:0xf
	v_exp_f32_e32 v86, v86
	v_exp_f32_e32 v87, v87
	v_pk_fma_f32 v[12:13], v[52:53], v[12:13], v[40:41]
	v_mov_b32_dpp v88, v20 row_ror:1 row_mask:0xf bank_mask:0xf
	v_mov_b32_dpp v89, v21 row_ror:1 row_mask:0xf bank_mask:0xf
	v_mov_b32_dpp v92, v76 row_shr:2 row_mask:0xf bank_mask:0xf
	v_mov_b32_dpp v93, v77 row_shr:2 row_mask:0xf bank_mask:0xf
	v_mov_b32_dpp v120, v14 row_shr:2 row_mask:0xf bank_mask:0xf
	v_mov_b32_dpp v121, v15 row_shr:2 row_mask:0xf bank_mask:0xf
	v_pk_fma_f32 v[8:9], v[56:57], v[8:9], v[12:13]
	v_mov_b32_dpp v88, v76 row_shr:1 row_mask:0xf bank_mask:0xf
	v_mov_b32_dpp v89, v77 row_shr:1 row_mask:0xf bank_mask:0xf
	v_mov_b32_dpp v18, v14 row_shr:1 row_mask:0xf bank_mask:0xf
	v_mov_b32_dpp v19, v15 row_shr:1 row_mask:0xf bank_mask:0xf
	v_pk_fma_f32 v[120:121], v[54:55], v[120:121], v[42:43]
	v_pk_fma_f32 v[92:93], v[52:53], v[92:93], v[40:41]
	v_pk_fma_f32 v[8:9], v[28:29], v[60:61], v[8:9]
	v_pk_fma_f32 v[18:19], v[58:59], v[18:19], v[120:121]
	v_pk_fma_f32 v[88:89], v[56:57], v[88:89], v[92:93]
	v_pk_mul_f32 v[12:13], v[8:9], s[2:3] op_sel_hi:[1,0]
	v_pk_fma_f32 v[18:19], v[14:15], v[62:63], v[18:19]
	v_pk_add_f32 v[86:87], v[86:87], 1.0 op_sel_hi:[1,0]
	v_pk_fma_f32 v[76:77], v[76:77], v[60:61], v[88:89]
	v_exp_f32_e32 v12, v12
	v_exp_f32_e32 v13, v13
	v_mov_b32_dpp v110, v72 row_ror:2 row_mask:0xf bank_mask:0xf
	v_mov_b32_dpp v111, v73 row_ror:2 row_mask:0xf bank_mask:0xf
	v_pk_mul_f32 v[120:121], v[18:19], s[2:3] op_sel_hi:[1,0]
	v_rcp_f32_e32 v86, v86
	v_rcp_f32_e32 v87, v87
	v_pk_mul_f32 v[88:89], v[76:77], s[2:3] op_sel_hi:[1,0]
	v_mov_b32_dpp v108, v72 row_ror:1 row_mask:0xf bank_mask:0xf
	v_mov_b32_dpp v109, v73 row_ror:1 row_mask:0xf bank_mask:0xf
	v_mov_b32_dpp v110, v84 row_shr:2 row_mask:0xf bank_mask:0xf
	v_mov_b32_dpp v111, v85 row_shr:2 row_mask:0xf bank_mask:0xf
	v_exp_f32_e32 v120, v120
	v_exp_f32_e32 v121, v121
	v_exp_f32_e32 v88, v88
	v_exp_f32_e32 v89, v89
	v_mov_b32_dpp v108, v84 row_shr:1 row_mask:0xf bank_mask:0xf
	v_mov_b32_dpp v109, v85 row_shr:1 row_mask:0xf bank_mask:0xf
	v_pk_mul_f32 v[2:3], v[2:3], v[96:97] op_sel_hi:[1,0]
	v_pk_mul_f32 v[6:7], v[6:7], v[96:97] op_sel_hi:[1,0]
	v_pk_fma_f32 v[96:97], v[36:37], v[110:111], v[32:33]
	v_pk_add_f32 v[12:13], v[12:13], 1.0 op_sel_hi:[1,0]
	v_pk_fma_f32 v[96:97], v[44:45], v[108:109], v[96:97]
	v_pk_mul_f32 v[30:31], v[30:31], v[86:87]
	v_pk_fma_f32 v[84:85], v[84:85], v[48:49], v[96:97]
	v_rcp_f32_e32 v12, v12
	v_rcp_f32_e32 v13, v13
	v_mov_b32_dpp v4, v24 row_shr:2 row_mask:0xf bank_mask:0xf
	v_mov_b32_dpp v5, v25 row_shr:2 row_mask:0xf bank_mask:0xf
	v_pk_add_f32 v[120:121], v[120:121], 1.0 op_sel_hi:[1,0]
	v_pk_mul_f32 v[30:31], v[84:85], v[30:31]
	v_pk_add_f32 v[84:85], v[88:89], 1.0 op_sel_hi:[1,0]
	v_mov_b32_dpp v0, v24 row_shr:1 row_mask:0xf bank_mask:0xf
	v_mov_b32_dpp v1, v25 row_shr:1 row_mask:0xf bank_mask:0xf
	v_mov_b32_dpp v94, v16 row_ror:2 row_mask:0xf bank_mask:0xf
	v_mov_b32_dpp v95, v17 row_ror:2 row_mask:0xf bank_mask:0xf
	v_rcp_f32_e32 v120, v120
	v_rcp_f32_e32 v121, v121
	v_rcp_f32_e32 v84, v84
	v_rcp_f32_e32 v85, v85
	v_pk_fma_f32 v[4:5], v[36:37], v[4:5], v[32:33]
	v_mov_b32_dpp v90, v16 row_ror:1 row_mask:0xf bank_mask:0xf
; #define LAS __attribute__((address_space(3)))
; DI unsigned pk2(float lo, float hi) { f32x2 v = {lo, hi}; bf16x2_t b = __builtin_convertvector(v, bf16x2_t); return __builtin_bit_cast(unsigned, b); }
;     DI void operator()(const AccT& acc, const Unit& u, int wr, int wc, int fr, int fq) const {
;     ...
;                     const f32x2 bg = *(const LAS f32x2*)(P + lc + 2 * jp), g0 = *(const LAS f32x2*)(P + 32 + lc + 2 * jp), g1 = *(const LAS f32x2*)(P + 64 + lc + 2 * jp), g2 = *(const LAS f32x2*)(P + 96 + lc + 2 * jp);
;                     const f32x2 bv = *(const LAS f32x2*)(P + 128 + lc + 2 * jp), v0 = *(const LAS f32x2*)(P + 160 + lc + 2 * jp), v1 = *(const LAS f32x2*)(P + 192 + lc + 2 * jp), v2 = *(const LAS f32x2*)(P + 224 + lc + 2 * jp);
;                     f32x2 G[4], V[4];
; #pragma unroll
;                     for (int m = 0; m < 4; ++m) { G[m] = (f32x2){acc[ai][0][m][n][2 * jp], acc[ai][0][m][n][2 * jp + 1]} * rs[m]; V[m] = (f32x2){acc[ai][1][m][n][2 * jp], acc[ai][1][m][n][2 * jp + 1]} * rs[m]; }
; #pragma unroll
;                     for (int m = 0; m < 4; ++m) {
;                         const f32x2 zz = {0.f, 0.f}; const f32x2 Gp = m ? G[m - 1] : zz, Vp = m ? V[m - 1] : zz;
;                         const f32x2 gp1 = {dpp_prev1(G[m].x, Gp.x), dpp_prev1(G[m].y, Gp.y)}, gp2 = {dpp_prev2(G[m].x, Gp.x), dpp_prev2(G[m].y, Gp.y)};
;                         const f32x2 vp1 = {dpp_prev1(V[m].x, Vp.x), dpp_prev1(V[m].y, Vp.y)}, vp2 = {dpp_prev2(V[m].x, Vp.x), dpp_prev2(V[m].y, Vp.y)};
;                         const f32x2 gc = bg + g0 * gp2 + g1 * gp1 + g2 * G[m];
;                         const f32x2 vc = bv + v0 * vp2 + v1 * vp1 + v2 * V[m];
;                         const f32x2 xe = gc * (-LOG2E);
;                         f32x2 dn = {__builtin_amdgcn_exp2f(xe.x), __builtin_amdgcn_exp2f(xe.y)}; dn = dn + 1.0f;
;                         const f32x2 rc = {__builtin_amdgcn_rcpf(dn.x), __builtin_amdgcn_rcpf(dn.y)};
;                         const f32x2 rr = gc * rc * vc;
;                         wpk[m][jp] = pk2(rr.x, rr.y); }
;                 }
; #pragma unroll
;                 for (int m = 0; m < 4; ++m) { const int row = m ? tok0 + 16 * m : row0;
;                     *(u32x2*)(ACT + (size_t)row * 2816 + cl + 4 * n) = (u32x2){wpk[m][0], wpk[m][1]}; }
	v_mov_b32_dpp v91, v17 row_ror:1 row_mask:0xf bank_mask:0xf
	v_mov_b32_dpp v94, v72 row_shr:2 row_mask:0xf bank_mask:0xf
	v_mov_b32_dpp v95, v73 row_shr:2 row_mask:0xf bank_mask:0xf
	v_mov_b32_dpp v124, v10 row_shr:2 row_mask:0xf bank_mask:0xf
	v_mov_b32_dpp v125, v11 row_shr:2 row_mask:0xf bank_mask:0xf
	v_pk_fma_f32 v[0:1], v[44:45], v[0:1], v[4:5]
	v_mov_b32_dpp v90, v72 row_shr:1 row_mask:0xf bank_mask:0xf
	v_mov_b32_dpp v91, v73 row_shr:1 row_mask:0xf bank_mask:0xf
	v_mov_b32_dpp v122, v10 row_shr:1 row_mask:0xf bank_mask:0xf
	v_mov_b32_dpp v123, v11 row_shr:1 row_mask:0xf bank_mask:0xf
	v_pk_fma_f32 v[124:125], v[38:39], v[124:125], v[34:35]
	v_pk_fma_f32 v[86:87], v[36:37], v[94:95], v[32:33]
	v_pk_fma_f32 v[0:1], v[24:25], v[48:49], v[0:1]
	v_pk_mul_f32 v[4:5], v[8:9], v[12:13]
	v_pk_fma_f32 v[122:123], v[46:47], v[122:123], v[124:125]
	v_pk_fma_f32 v[86:87], v[44:45], v[90:91], v[86:87]
	v_pk_mul_f32 v[0:1], v[0:1], v[4:5]
	v_mov_b32_dpp v78, v28 row_ror:2 row_mask:0xf bank_mask:0xf
	v_mov_b32_dpp v79, v29 row_ror:2 row_mask:0xf bank_mask:0xf
	v_pk_fma_f32 v[122:123], v[10:11], v[50:51], v[122:123]
	v_pk_mul_f32 v[18:19], v[18:19], v[120:121]
	v_cvt_pk_bf16_f32 v27, v26, v27
	v_pk_fma_f32 v[72:73], v[72:73], v[48:49], v[86:87]
	v_pk_mul_f32 v[76:77], v[76:77], v[84:85]
	v_cvt_pk_bf16_f32 v26, v0, v1
	v_mov_b32_dpp v4, v14 row_ror:2 row_mask:0xf bank_mask:0xf
	v_mov_b32_dpp v5, v15 row_ror:2 row_mask:0xf bank_mask:0xf
	v_mov_b32_dpp v74, v28 row_ror:1 row_mask:0xf bank_mask:0xf
	v_mov_b32_dpp v75, v29 row_ror:1 row_mask:0xf bank_mask:0xf
	v_mov_b32_dpp v78, v20 row_shr:2 row_mask:0xf bank_mask:0xf
	v_mov_b32_dpp v79, v21 row_shr:2 row_mask:0xf bank_mask:0xf
	v_pk_mul_f32 v[18:19], v[122:123], v[18:19]
	v_pk_mul_f32 v[72:73], v[72:73], v[76:77]
	v_mov_b32_dpp v0, v14 row_ror:1 row_mask:0xf bank_mask:0xf
	v_mov_b32_dpp v1, v15 row_ror:1 row_mask:0xf bank_mask:0xf
	v_mov_b32_dpp v4, v6 row_shr:2 row_mask:0xf bank_mask:0xf
	v_mov_b32_dpp v5, v7 row_shr:2 row_mask:0xf bank_mask:0xf
	v_mov_b32_dpp v74, v20 row_shr:1 row_mask:0xf bank_mask:0xf
	v_mov_b32_dpp v75, v21 row_shr:1 row_mask:0xf bank_mask:0xf
	v_cvt_pk_bf16_f32 v19, v18, v19
	v_cvt_pk_bf16_f32 v18, v72, v73
	v_pk_fma_f32 v[72:73], v[52:53], v[78:79], v[40:41]
	v_mov_b32_dpp v0, v6 row_shr:1 row_mask:0xf bank_mask:0xf
	v_mov_b32_dpp v1, v7 row_shr:1 row_mask:0xf bank_mask:0xf
	v_pk_fma_f32 v[4:5], v[54:55], v[4:5], v[42:43]
	v_pk_fma_f32 v[72:73], v[56:57], v[74:75], v[72:73]
	v_pk_fma_f32 v[0:1], v[58:59], v[0:1], v[4:5]
	v_pk_fma_f32 v[20:21], v[20:21], v[60:61], v[72:73]
	v_pk_fma_f32 v[0:1], v[6:7], v[62:63], v[0:1]
	v_pk_mul_f32 v[72:73], v[20:21], s[2:3] op_sel_hi:[1,0]
	v_pk_mul_f32 v[4:5], v[0:1], s[2:3] op_sel_hi:[1,0]
	v_exp_f32_e32 v72, v72
	v_exp_f32_e32 v73, v73
	v_exp_f32_e32 v4, v4
	v_exp_f32_e32 v5, v5
	v_pk_add_f32 v[72:73], v[72:73], 1.0 op_sel_hi:[1,0]
	v_pk_add_f32 v[4:5], v[4:5], 1.0 op_sel_hi:[1,0]
	v_mov_b32_dpp v82, v24 row_ror:2 row_mask:0xf bank_mask:0xf
	v_mov_b32_dpp v83, v25 row_ror:2 row_mask:0xf bank_mask:0xf
	v_rcp_f32_e32 v72, v72
	v_rcp_f32_e32 v73, v73
	v_mov_b32_dpp v12, v10 row_ror:2 row_mask:0xf bank_mask:0xf
	v_mov_b32_dpp v13, v11 row_ror:2 row_mask:0xf bank_mask:0xf
	v_rcp_f32_e32 v4, v4
	v_rcp_f32_e32 v5, v5
	v_mov_b32_dpp v80, v24 row_ror:1 row_mask:0xf bank_mask:0xf
	v_mov_b32_dpp v81, v25 row_ror:1 row_mask:0xf bank_mask:0xf
	v_mov_b32_dpp v82, v16 row_shr:2 row_mask:0xf bank_mask:0xf
	v_mov_b32_dpp v83, v17 row_shr:2 row_mask:0xf bank_mask:0xf
	v_mov_b32_dpp v8, v10 row_ror:1 row_mask:0xf bank_mask:0xf
	v_mov_b32_dpp v9, v11 row_ror:1 row_mask:0xf bank_mask:0xf
	v_mov_b32_dpp v12, v2 row_shr:2 row_mask:0xf bank_mask:0xf
	v_mov_b32_dpp v13, v3 row_shr:2 row_mask:0xf bank_mask:0xf
	v_mov_b32_dpp v80, v16 row_shr:1 row_mask:0xf bank_mask:0xf
	v_mov_b32_dpp v81, v17 row_shr:1 row_mask:0xf bank_mask:0xf
	v_pk_fma_f32 v[74:75], v[36:37], v[82:83], v[32:33]
	v_mov_b32_dpp v8, v2 row_shr:1 row_mask:0xf bank_mask:0xf
	v_mov_b32_dpp v9, v3 row_shr:1 row_mask:0xf bank_mask:0xf
	v_pk_fma_f32 v[6:7], v[38:39], v[12:13], v[34:35]
	v_pk_fma_f32 v[74:75], v[44:45], v[80:81], v[74:75]
	v_pk_fma_f32 v[6:7], v[46:47], v[8:9], v[6:7]
	v_pk_fma_f32 v[16:17], v[16:17], v[48:49], v[74:75]
	v_pk_mul_f32 v[20:21], v[20:21], v[72:73]
	v_pk_fma_f32 v[2:3], v[2:3], v[50:51], v[6:7]
	v_pk_mul_f32 v[0:1], v[0:1], v[4:5]
	v_pk_mul_f32 v[16:17], v[16:17], v[20:21]
	v_pk_mul_f32 v[0:1], v[2:3], v[0:1]
	v_cvt_pk_bf16_f32 v23, v22, v23
	v_cvt_pk_bf16_f32 v30, v30, v31
	v_cvt_pk_bf16_f32 v22, v16, v17
	v_cvt_pk_bf16_f32 v31, v0, v1
	global_store_dwordx2 v[64:65], v[26:27], off offset:8
	global_store_dwordx2 v[66:67], v[22:23], off offset:8
	global_store_dwordx2 v[68:69], v[18:19], off offset:8
	global_store_dwordx2 v[70:71], v[30:31], off offset:8
	s_and_b64 vcc, exec, s[6:7]
	s_mov_b64 s[6:7], -1
	s_cbranch_vccnz .LBB0_1817
	s_andn2_b64 vcc, exec, s[14:15]
	s_cbranch_vccnz .LBB0_1816
	s_barrier
	s_branch .LBB0_1816
